# v12 + MFMA order: both k-steps of each accumulator issued back to back (SrcC forwarding)
# speedup vs baseline: 1.0051x; 1.0051x over previous
; #define PG8_STAGE(bufoff, gbase, voff) do { _Pragma("unroll") for (int _i = 0; _i < 2; ++_i) \
;         __builtin_amdgcn_global_load_lds((const unsigned*)((const char*)(gbase) + (voff)[_i]), (PG8_LAS unsigned*)(lds + (bufoff) + ldsw + _i * 8192), 16, 0, 0); } while (0)
; #define PG8_LDA(dst, b, h) do { _Pragma("unroll") for (int m = 0; m < 4; ++m) _Pragma("unroll") for (int k = 0; k < 2; ++k) dst[m][k] = *(const PG8_LAS bf16x8*)(lds + PG8_SA(b, h) + aoff + m * 2048 + k * 1024); } while (0)
; #define PG8_LDB(dst, b, h) do { _Pragma("unroll") for (int n = 0; n < 2; ++n) _Pragma("unroll") for (int k = 0; k < 2; ++k) dst[n][k] = *(const PG8_LAS bf16x8*)(lds + PG8_SB(b, h) + boff + n * 2048 + k * 1024); } while (0)
; #define PG8_MMA(ai, bj, At, Bt) do { __builtin_amdgcn_s_setprio(1); _Pragma("unroll") for (int m = 0; m < 4; ++m) _Pragma("unroll") for (int n = 0; n < 2; ++n) _Pragma("unroll") for (int k = 0; k < 2; ++k) \
;         acc[ai][bj][m][n] = __builtin_amdgcn_mfma_f32_16x16x32_bf16(Bt[n][k], At[m][k], acc[ai][bj][m][n], 0, 0, 0); __builtin_amdgcn_s_setprio(0); } while (0)
; #define PG8_WAIT_V(n) asm volatile("s_waitcnt vmcnt(" #n ")" ::: "memory")
; #define PG8_WAIT_L(n) asm volatile("s_waitcnt lgkmcnt(" #n ")" ::: "memory")
; template <class Epi, class Sched, bool ALIGN_EPI = false, bool SP2 = false>
; __device__ __forceinline__ void gemm_phase(PG8_LAS unsigned char* lds, const Gemm g, const Sched& S, const Epi& E) {
;     ...
;             const bool last = (t == nt - 2);
;             const char* a1 = cA + (size_t)(t + 1) * kstep;
;             const char* a2 = last ? nA : cA + (size_t)(t + 2) * kstep; const char* b2 = last ? nB : cB + (size_t)(t + 2) * kstep;
;             const char* a3 = a2 + kstep; const char* b3 = b2 + kstep;
;             if (last && has_next) S.a_ready(nxt);
;             if constexpr (SP2) {
;             PG8_LDB(B0, 0, 0); PG8_LDB(B1, 0, 1); PG8_SCHED; PG8_LDA(At, 0, 0); PG8_STAGE(PG8_SA(1, 1), a1 + hstep, voffA);
;             PG8_WAIT_V(8); PG8_WAIT_L(0); PG8_BAR; PG8_MMA(0, 0, At, B0); PG8_MMA(0, 1, At, B1); PG8_BAR; PG8_SCHED;
;             PG8_LDA(At, 0, 1); PG8_STAGE(PG8_SB(0, 0), b2, voffB); PG8_STAGE(PG8_SB(0, 1), b2 + hstep, voffB); PG8_STAGE(PG8_SA(0, 0), a2, voffA);
;             PG8_WAIT_V(8); PG8_WAIT_L(0); PG8_BAR; PG8_MMA(1, 0, At, B0); PG8_MMA(1, 1, At, B1); PG8_BAR; PG8_SCHED;
.LBB0_202:
	s_add_i32 s78, s38, 2
	s_add_u32 s79, s22, 0x80
	s_addc_u32 s39, s23, 0
	s_cmp_eq_u32 s33, s38
	s_cselect_b32 s39, s7, s39
	s_cselect_b32 s38, s6, s79
	v_add_u32_e32 v0, s19, v150
	s_cselect_b32 s81, s17, s77
	s_cselect_b32 s80, s16, s76
	s_add_i32 s79, 0, 0x14000
	ds_read_b128 v[152:155], v0
	ds_read_b128 v[156:159], v0 offset:1024
	ds_read_b128 v[160:163], v0 offset:2048
	ds_read_b128 v[164:167], v0 offset:3072
	v_add_u32_e32 v0, s79, v150
	ds_read_b128 v[168:171], v0
	ds_read_b128 v[172:175], v0 offset:1024
	ds_read_b128 v[176:179], v0 offset:2048
	ds_read_b128 v[184:187], v0 offset:3072
	v_lshl_add_u64 v[2:3], s[22:23], 0, v[144:145]
	s_add_i32 m0, s42, 0xc000
	ds_read_b128 v[188:191], v151
	ds_read_b128 v[192:195], v151 offset:1024
	ds_read_b128 v[196:199], v151 offset:2048
	ds_read_b128 v[200:203], v151 offset:3072
	ds_read_b128 v[204:207], v151 offset:4096
	ds_read_b128 v[230:233], v151 offset:5120
	ds_read_b128 v[234:237], v151 offset:6144
	ds_read_b128 v[238:241], v151 offset:7168
	global_load_lds_dwordx4 v[2:3], off
	v_lshl_add_u64 v[2:3], s[22:23], 0, v[146:147]
	s_add_i32 m0, s42, 0xe000
	s_nop 0
	global_load_lds_dwordx4 v[2:3], off
	s_waitcnt vmcnt(8)
	s_waitcnt lgkmcnt(0)
	s_barrier
	s_setprio 1
	s_waitcnt lgkmcnt(0)
	v_mfma_f32_16x16x32_bf16 v[132:135], v[152:155], v[188:191], v[132:135]
	v_mfma_f32_16x16x32_bf16 v[132:135], v[156:159], v[192:195], v[132:135]
	v_mfma_f32_16x16x32_bf16 v[128:131], v[160:163], v[188:191], v[128:131]
	v_mfma_f32_16x16x32_bf16 v[128:131], v[164:167], v[192:195], v[128:131]
	v_mfma_f32_16x16x32_bf16 v[116:119], v[152:155], v[196:199], v[116:119]
	v_mfma_f32_16x16x32_bf16 v[116:119], v[156:159], v[200:203], v[116:119]
	v_mfma_f32_16x16x32_bf16 v[112:115], v[160:163], v[196:199], v[112:115]
	v_mfma_f32_16x16x32_bf16 v[112:115], v[164:167], v[200:203], v[112:115]
	v_mfma_f32_16x16x32_bf16 v[100:103], v[152:155], v[204:207], v[100:103]
	v_mfma_f32_16x16x32_bf16 v[100:103], v[156:159], v[230:233], v[100:103]
	v_mfma_f32_16x16x32_bf16 v[96:99], v[160:163], v[204:207], v[96:99]
	v_mfma_f32_16x16x32_bf16 v[96:99], v[164:167], v[230:233], v[96:99]
	v_mfma_f32_16x16x32_bf16 v[84:87], v[152:155], v[234:237], v[84:87]
	v_mfma_f32_16x16x32_bf16 v[84:87], v[156:159], v[238:241], v[84:87]
	v_mfma_f32_16x16x32_bf16 v[80:83], v[160:163], v[234:237], v[80:83]
	v_mfma_f32_16x16x32_bf16 v[80:83], v[164:167], v[238:241], v[80:83]
	s_setprio 0
	s_setprio 1
	v_mfma_f32_16x16x32_bf16 v[124:127], v[168:171], v[188:191], v[124:127]
	v_mfma_f32_16x16x32_bf16 v[124:127], v[172:175], v[192:195], v[124:127]
	v_mfma_f32_16x16x32_bf16 v[120:123], v[176:179], v[188:191], v[120:123]
	v_mfma_f32_16x16x32_bf16 v[120:123], v[184:187], v[192:195], v[120:123]
	v_mfma_f32_16x16x32_bf16 v[108:111], v[168:171], v[196:199], v[108:111]
	v_mfma_f32_16x16x32_bf16 v[108:111], v[172:175], v[200:203], v[108:111]
	v_mfma_f32_16x16x32_bf16 v[104:107], v[176:179], v[196:199], v[104:107]
	v_mfma_f32_16x16x32_bf16 v[104:107], v[184:187], v[200:203], v[104:107]
	v_mfma_f32_16x16x32_bf16 v[92:95], v[168:171], v[204:207], v[92:95]
	v_mfma_f32_16x16x32_bf16 v[92:95], v[172:175], v[230:233], v[92:95]
	v_mfma_f32_16x16x32_bf16 v[88:91], v[176:179], v[204:207], v[88:91]
	v_mfma_f32_16x16x32_bf16 v[88:91], v[184:187], v[230:233], v[88:91]
	v_mfma_f32_16x16x32_bf16 v[76:79], v[168:171], v[234:237], v[76:79]
	v_mfma_f32_16x16x32_bf16 v[76:79], v[172:175], v[238:241], v[76:79]
	v_mfma_f32_16x16x32_bf16 v[72:75], v[176:179], v[234:237], v[72:75]
	v_mfma_f32_16x16x32_bf16 v[72:75], v[184:187], v[238:241], v[72:75]
	s_setprio 0
	s_barrier
	s_add_i32 s82, s19, s20
	v_lshl_add_u64 v[2:3], s[80:81], 0, v[140:141]
	s_mov_b32 m0, s82
	ds_read_b128 v[188:191], v151 offset:16384
	ds_read_b128 v[192:195], v151 offset:17408
	ds_read_b128 v[196:199], v151 offset:18432
	ds_read_b128 v[200:203], v151 offset:19456
	ds_read_b128 v[204:207], v151 offset:20480
	ds_read_b128 v[230:233], v151 offset:21504
	ds_read_b128 v[234:237], v151 offset:22528
	ds_read_b128 v[238:241], v151 offset:23552
	global_load_lds_dwordx4 v[2:3], off
	s_add_i32 m0, s82, 0x2000
	v_lshl_add_u64 v[180:181], s[80:81], 0, v[136:137]
	s_add_u32 s80, s80, s48
	s_addc_u32 s81, s81, s49
	s_add_i32 s79, s79, s20
	global_load_lds_dwordx4 v[180:181], off
	v_lshl_add_u64 v[208:209], s[80:81], 0, v[140:141]
	s_mov_b32 m0, s79
	v_lshl_add_u64 v[216:217], s[80:81], 0, v[136:137]
	global_load_lds_dwordx4 v[208:209], off
	s_add_i32 m0, s79, 0x2000
	v_lshl_add_u64 v[224:225], s[38:39], 0, v[142:143]
	global_load_lds_dwordx4 v[216:217], off
	s_mov_b32 m0, s42
	v_lshl_add_u64 v[226:227], s[38:39], 0, v[138:139]
	global_load_lds_dwordx4 v[224:225], off
	s_mov_b32 m0, s45
	s_nop 0
	global_load_lds_dwordx4 v[226:227], off
	s_waitcnt vmcnt(8)
	s_waitcnt lgkmcnt(0)
	s_barrier
; #define PG8_STAGE(bufoff, gbase, voff) do { _Pragma("unroll") for (int _i = 0; _i < 2; ++_i) \
;         __builtin_amdgcn_global_load_lds((const unsigned*)((const char*)(gbase) + (voff)[_i]), (PG8_LAS unsigned*)(lds + (bufoff) + ldsw + _i * 8192), 16, 0, 0); } while (0)
; #define PG8_LDA(dst, b, h) do { _Pragma("unroll") for (int m = 0; m < 4; ++m) _Pragma("unroll") for (int k = 0; k < 2; ++k) dst[m][k] = *(const PG8_LAS bf16x8*)(lds + PG8_SA(b, h) + aoff + m * 2048 + k * 1024); } while (0)
; #define PG8_LDB(dst, b, h) do { _Pragma("unroll") for (int n = 0; n < 2; ++n) _Pragma("unroll") for (int k = 0; k < 2; ++k) dst[n][k] = *(const PG8_LAS bf16x8*)(lds + PG8_SB(b, h) + boff + n * 2048 + k * 1024); } while (0)
; #define PG8_MMA(ai, bj, At, Bt) do { __builtin_amdgcn_s_setprio(1); _Pragma("unroll") for (int m = 0; m < 4; ++m) _Pragma("unroll") for (int n = 0; n < 2; ++n) _Pragma("unroll") for (int k = 0; k < 2; ++k) \
;         acc[ai][bj][m][n] = __builtin_amdgcn_mfma_f32_16x16x32_bf16(Bt[n][k], At[m][k], acc[ai][bj][m][n], 0, 0, 0); __builtin_amdgcn_s_setprio(0); } while (0)
; #define PG8_WAIT_V(n) asm volatile("s_waitcnt vmcnt(" #n ")" ::: "memory")
; #define PG8_WAIT_L(n) asm volatile("s_waitcnt lgkmcnt(" #n ")" ::: "memory")
; #define PG8_BAR __builtin_amdgcn_s_barrier()
; #define PG8_SCHED __builtin_amdgcn_sched_barrier(0)
; template <class Epi, class Sched, bool ALIGN_EPI = false, bool SP2 = false>
; __device__ __forceinline__ void gemm_phase(PG8_LAS unsigned char* lds, const Gemm g, const Sched& S, const Epi& E) {
;     ...
;             PG8_WAIT_V(8); PG8_WAIT_L(0); PG8_BAR; PG8_MMA(1, 0, At, B0); PG8_MMA(1, 1, At, B1); PG8_BAR; PG8_SCHED;
;             PG8_LDB(B0, 1, 0); PG8_LDB(B1, 1, 1); PG8_SCHED; PG8_LDA(At, 1, 0); PG8_STAGE(PG8_SA(0, 1), a2 + hstep, voffA);
;             PG8_WAIT_V(8); PG8_WAIT_L(0); PG8_BAR; PG8_MMA(0, 0, At, B0); PG8_MMA(0, 1, At, B1); PG8_BAR; PG8_SCHED;
	s_setprio 1
	s_waitcnt lgkmcnt(0)
	v_mfma_f32_16x16x32_bf16 v[68:71], v[152:155], v[188:191], v[68:71]
	v_mfma_f32_16x16x32_bf16 v[68:71], v[156:159], v[192:195], v[68:71]
	v_mfma_f32_16x16x32_bf16 v[64:67], v[160:163], v[188:191], v[64:67]
	v_mfma_f32_16x16x32_bf16 v[64:67], v[164:167], v[192:195], v[64:67]
	v_mfma_f32_16x16x32_bf16 v[52:55], v[152:155], v[196:199], v[52:55]
	v_mfma_f32_16x16x32_bf16 v[52:55], v[156:159], v[200:203], v[52:55]
	v_mfma_f32_16x16x32_bf16 v[48:51], v[160:163], v[196:199], v[48:51]
	v_mfma_f32_16x16x32_bf16 v[48:51], v[164:167], v[200:203], v[48:51]
	v_mfma_f32_16x16x32_bf16 v[36:39], v[152:155], v[204:207], v[36:39]
	v_mfma_f32_16x16x32_bf16 v[36:39], v[156:159], v[230:233], v[36:39]
	v_mfma_f32_16x16x32_bf16 v[32:35], v[160:163], v[204:207], v[32:35]
	v_mfma_f32_16x16x32_bf16 v[32:35], v[164:167], v[230:233], v[32:35]
	v_mfma_f32_16x16x32_bf16 v[20:23], v[152:155], v[234:237], v[20:23]
	v_mfma_f32_16x16x32_bf16 v[20:23], v[156:159], v[238:241], v[20:23]
	v_mfma_f32_16x16x32_bf16 v[16:19], v[160:163], v[234:237], v[16:19]
	v_mfma_f32_16x16x32_bf16 v[16:19], v[164:167], v[238:241], v[16:19]
	s_setprio 0
	s_setprio 1
	v_mfma_f32_16x16x32_bf16 v[60:63], v[168:171], v[188:191], v[60:63]
	v_mfma_f32_16x16x32_bf16 v[60:63], v[172:175], v[192:195], v[60:63]
	v_mfma_f32_16x16x32_bf16 v[56:59], v[176:179], v[188:191], v[56:59]
	v_mfma_f32_16x16x32_bf16 v[56:59], v[184:187], v[192:195], v[56:59]
	v_mfma_f32_16x16x32_bf16 v[44:47], v[168:171], v[196:199], v[44:47]
	v_mfma_f32_16x16x32_bf16 v[44:47], v[172:175], v[200:203], v[44:47]
	v_mfma_f32_16x16x32_bf16 v[40:43], v[176:179], v[196:199], v[40:43]
	v_mfma_f32_16x16x32_bf16 v[40:43], v[184:187], v[200:203], v[40:43]
	v_mfma_f32_16x16x32_bf16 v[28:31], v[168:171], v[204:207], v[28:31]
	v_mfma_f32_16x16x32_bf16 v[28:31], v[172:175], v[230:233], v[28:31]
	v_mfma_f32_16x16x32_bf16 v[24:27], v[176:179], v[204:207], v[24:27]
	v_mfma_f32_16x16x32_bf16 v[24:27], v[184:187], v[230:233], v[24:27]
	v_mfma_f32_16x16x32_bf16 v[12:15], v[168:171], v[234:237], v[12:15]
	v_mfma_f32_16x16x32_bf16 v[12:15], v[172:175], v[238:241], v[12:15]
	v_mfma_f32_16x16x32_bf16 v[8:11], v[176:179], v[234:237], v[8:11]
	v_mfma_f32_16x16x32_bf16 v[8:11], v[184:187], v[238:241], v[8:11]
	s_setprio 0
	s_barrier
	v_add_u32_e32 v0, s91, v150
	s_add_i32 s79, 0, 0x1c000
	ds_read_b128 v[152:155], v0
	ds_read_b128 v[156:159], v0 offset:1024
	ds_read_b128 v[160:163], v0 offset:2048
	ds_read_b128 v[164:167], v0 offset:3072
	v_add_u32_e32 v0, s79, v150
	ds_read_b128 v[168:171], v0
	ds_read_b128 v[172:175], v0 offset:1024
	ds_read_b128 v[176:179], v0 offset:2048
	ds_read_b128 v[184:187], v0 offset:3072
	s_add_u32 s38, s38, s48
	s_addc_u32 s39, s39, s49
	s_mov_b32 m0, s46
	v_lshl_add_u64 v[228:229], s[38:39], 0, v[142:143]
	ds_read_b128 v[188:191], v151 offset:32768
	ds_read_b128 v[192:195], v151 offset:33792
	ds_read_b128 v[196:199], v151 offset:34816
	ds_read_b128 v[200:203], v151 offset:35840
	ds_read_b128 v[204:207], v151 offset:36864
	ds_read_b128 v[230:233], v151 offset:37888
	ds_read_b128 v[234:237], v151 offset:38912
	ds_read_b128 v[238:241], v151 offset:39936
	global_load_lds_dwordx4 v[228:229], off
	v_lshl_add_u64 v[228:229], s[38:39], 0, v[138:139]
	s_mov_b32 m0, s47
	s_nop 0
	global_load_lds_dwordx4 v[228:229], off
	s_waitcnt vmcnt(8)
	s_waitcnt lgkmcnt(0)
	s_barrier
	s_setprio 1
	s_waitcnt lgkmcnt(0)
	v_mfma_f32_16x16x32_bf16 v[132:135], v[152:155], v[188:191], v[132:135]
	v_mfma_f32_16x16x32_bf16 v[132:135], v[156:159], v[192:195], v[132:135]
	v_mfma_f32_16x16x32_bf16 v[128:131], v[160:163], v[188:191], v[128:131]
	v_mfma_f32_16x16x32_bf16 v[128:131], v[164:167], v[192:195], v[128:131]
	v_mfma_f32_16x16x32_bf16 v[116:119], v[152:155], v[196:199], v[116:119]
	v_mfma_f32_16x16x32_bf16 v[116:119], v[156:159], v[200:203], v[116:119]
	v_mfma_f32_16x16x32_bf16 v[112:115], v[160:163], v[196:199], v[112:115]
	v_mfma_f32_16x16x32_bf16 v[112:115], v[164:167], v[200:203], v[112:115]
	v_mfma_f32_16x16x32_bf16 v[100:103], v[152:155], v[204:207], v[100:103]
	v_mfma_f32_16x16x32_bf16 v[100:103], v[156:159], v[230:233], v[100:103]
	v_mfma_f32_16x16x32_bf16 v[96:99], v[160:163], v[204:207], v[96:99]
	v_mfma_f32_16x16x32_bf16 v[96:99], v[164:167], v[230:233], v[96:99]
	v_mfma_f32_16x16x32_bf16 v[84:87], v[152:155], v[234:237], v[84:87]
	v_mfma_f32_16x16x32_bf16 v[84:87], v[156:159], v[238:241], v[84:87]
	v_mfma_f32_16x16x32_bf16 v[80:83], v[160:163], v[234:237], v[80:83]
	v_mfma_f32_16x16x32_bf16 v[80:83], v[164:167], v[238:241], v[80:83]
	s_setprio 0
	s_setprio 1
	v_mfma_f32_16x16x32_bf16 v[124:127], v[168:171], v[188:191], v[124:127]
	v_mfma_f32_16x16x32_bf16 v[124:127], v[172:175], v[192:195], v[124:127]
	v_mfma_f32_16x16x32_bf16 v[120:123], v[176:179], v[188:191], v[120:123]
	v_mfma_f32_16x16x32_bf16 v[120:123], v[184:187], v[192:195], v[120:123]
	v_mfma_f32_16x16x32_bf16 v[108:111], v[168:171], v[196:199], v[108:111]
	v_mfma_f32_16x16x32_bf16 v[108:111], v[172:175], v[200:203], v[108:111]
	v_mfma_f32_16x16x32_bf16 v[104:107], v[176:179], v[196:199], v[104:107]
	v_mfma_f32_16x16x32_bf16 v[104:107], v[184:187], v[200:203], v[104:107]
	v_mfma_f32_16x16x32_bf16 v[92:95], v[168:171], v[204:207], v[92:95]
	v_mfma_f32_16x16x32_bf16 v[92:95], v[172:175], v[230:233], v[92:95]
	v_mfma_f32_16x16x32_bf16 v[88:91], v[176:179], v[204:207], v[88:91]
	v_mfma_f32_16x16x32_bf16 v[88:91], v[184:187], v[230:233], v[88:91]
	v_mfma_f32_16x16x32_bf16 v[76:79], v[168:171], v[234:237], v[76:79]
	v_mfma_f32_16x16x32_bf16 v[76:79], v[172:175], v[238:241], v[76:79]
	v_mfma_f32_16x16x32_bf16 v[72:75], v[176:179], v[234:237], v[72:75]
	v_mfma_f32_16x16x32_bf16 v[72:75], v[184:187], v[238:241], v[72:75]
	s_setprio 0
	s_barrier
; #define PG8_STAGE(bufoff, gbase, voff) do { _Pragma("unroll") for (int _i = 0; _i < 2; ++_i) \
;         __builtin_amdgcn_global_load_lds((const unsigned*)((const char*)(gbase) + (voff)[_i]), (PG8_LAS unsigned*)(lds + (bufoff) + ldsw + _i * 8192), 16, 0, 0); } while (0)
; #define PG8_LDA(dst, b, h) do { _Pragma("unroll") for (int m = 0; m < 4; ++m) _Pragma("unroll") for (int k = 0; k < 2; ++k) dst[m][k] = *(const PG8_LAS bf16x8*)(lds + PG8_SA(b, h) + aoff + m * 2048 + k * 1024); } while (0)
; #define PG8_MMA(ai, bj, At, Bt) do { __builtin_amdgcn_s_setprio(1); _Pragma("unroll") for (int m = 0; m < 4; ++m) _Pragma("unroll") for (int n = 0; n < 2; ++n) _Pragma("unroll") for (int k = 0; k < 2; ++k) \
;         acc[ai][bj][m][n] = __builtin_amdgcn_mfma_f32_16x16x32_bf16(Bt[n][k], At[m][k], acc[ai][bj][m][n], 0, 0, 0); __builtin_amdgcn_s_setprio(0); } while (0)
; #define PG8_WAIT_V(n) asm volatile("s_waitcnt vmcnt(" #n ")" ::: "memory")
; #define PG8_WAIT_L(n) asm volatile("s_waitcnt lgkmcnt(" #n ")" ::: "memory")
; #define PG8_BAR __builtin_amdgcn_s_barrier()
; #define PG8_SCHED __builtin_amdgcn_sched_barrier(0)
; template <class Epi, class Sched, bool ALIGN_EPI = false, bool SP2 = false>
; __device__ __forceinline__ void gemm_phase(PG8_LAS unsigned char* lds, const Gemm g, const Sched& S, const Epi& E) {
;     ...
;         for (int t = 0; t < nt; t += 2) {
;     ...
;             PG8_LDA(At, 1, 1); PG8_STAGE(PG8_SB(1, 0), b3, voffB); PG8_STAGE(PG8_SB(1, 1), b3 + hstep, voffB); PG8_STAGE(PG8_SA(1, 0), a3, voffA);
;             PG8_WAIT_V(8); PG8_WAIT_L(0); PG8_BAR; PG8_MMA(1, 0, At, B0); PG8_MMA(1, 1, At, B1); PG8_BAR; PG8_SCHED;
	s_add_i32 s38, s91, s20
	v_lshl_add_u64 v[2:3], v[2:3], 0, s[24:25]
	s_mov_b32 m0, s38
	ds_read_b128 v[188:191], v151 offset:49152
	ds_read_b128 v[192:195], v151 offset:50176
	ds_read_b128 v[196:199], v151 offset:51200
	ds_read_b128 v[200:203], v151 offset:52224
	ds_read_b128 v[204:207], v151 offset:53248
	ds_read_b128 v[230:233], v151 offset:54272
	ds_read_b128 v[234:237], v151 offset:55296
	ds_read_b128 v[238:241], v151 offset:56320
	global_load_lds_dwordx4 v[2:3], off
	v_lshl_add_u64 v[2:3], v[180:181], 0, s[24:25]
	s_add_i32 m0, s38, 0x2000
	s_add_i32 s38, s79, s20
	global_load_lds_dwordx4 v[2:3], off
	v_lshl_add_u64 v[2:3], v[208:209], 0, s[24:25]
	s_mov_b32 m0, s38
	s_nop 0
	global_load_lds_dwordx4 v[2:3], off
	v_lshl_add_u64 v[2:3], v[216:217], 0, s[24:25]
	s_add_i32 m0, s38, 0x2000
	s_nop 0
	global_load_lds_dwordx4 v[2:3], off
	v_lshl_add_u64 v[2:3], v[224:225], 0, s[24:25]
	s_mov_b32 m0, s52
	s_nop 0
	global_load_lds_dwordx4 v[2:3], off
	v_lshl_add_u64 v[2:3], v[226:227], 0, s[24:25]
	s_mov_b32 m0, s53
	s_nop 0
	global_load_lds_dwordx4 v[2:3], off
	s_waitcnt vmcnt(8)
	s_waitcnt lgkmcnt(0)
	s_barrier
	s_setprio 1
	s_waitcnt lgkmcnt(0)
	v_mfma_f32_16x16x32_bf16 v[68:71], v[152:155], v[188:191], v[68:71]
	v_mfma_f32_16x16x32_bf16 v[68:71], v[156:159], v[192:195], v[68:71]
	v_mfma_f32_16x16x32_bf16 v[64:67], v[160:163], v[188:191], v[64:67]
	v_mfma_f32_16x16x32_bf16 v[64:67], v[164:167], v[192:195], v[64:67]
	v_mfma_f32_16x16x32_bf16 v[52:55], v[152:155], v[196:199], v[52:55]
	v_mfma_f32_16x16x32_bf16 v[52:55], v[156:159], v[200:203], v[52:55]
	v_mfma_f32_16x16x32_bf16 v[48:51], v[160:163], v[196:199], v[48:51]
	v_mfma_f32_16x16x32_bf16 v[48:51], v[164:167], v[200:203], v[48:51]
	v_mfma_f32_16x16x32_bf16 v[36:39], v[152:155], v[204:207], v[36:39]
	v_mfma_f32_16x16x32_bf16 v[36:39], v[156:159], v[230:233], v[36:39]
	v_mfma_f32_16x16x32_bf16 v[32:35], v[160:163], v[204:207], v[32:35]
	v_mfma_f32_16x16x32_bf16 v[32:35], v[164:167], v[230:233], v[32:35]
	v_mfma_f32_16x16x32_bf16 v[20:23], v[152:155], v[234:237], v[20:23]
	v_mfma_f32_16x16x32_bf16 v[20:23], v[156:159], v[238:241], v[20:23]
	v_mfma_f32_16x16x32_bf16 v[16:19], v[160:163], v[234:237], v[16:19]
	v_mfma_f32_16x16x32_bf16 v[16:19], v[164:167], v[238:241], v[16:19]
	s_setprio 0
	s_setprio 1
	v_mfma_f32_16x16x32_bf16 v[60:63], v[168:171], v[188:191], v[60:63]
	v_mfma_f32_16x16x32_bf16 v[60:63], v[172:175], v[192:195], v[60:63]
	v_mfma_f32_16x16x32_bf16 v[56:59], v[176:179], v[188:191], v[56:59]
	v_mfma_f32_16x16x32_bf16 v[56:59], v[184:187], v[192:195], v[56:59]
	v_mfma_f32_16x16x32_bf16 v[44:47], v[168:171], v[196:199], v[44:47]
	v_mfma_f32_16x16x32_bf16 v[44:47], v[172:175], v[200:203], v[44:47]
	v_mfma_f32_16x16x32_bf16 v[40:43], v[176:179], v[196:199], v[40:43]
	v_mfma_f32_16x16x32_bf16 v[40:43], v[184:187], v[200:203], v[40:43]
	v_mfma_f32_16x16x32_bf16 v[28:31], v[168:171], v[204:207], v[28:31]
	v_mfma_f32_16x16x32_bf16 v[28:31], v[172:175], v[230:233], v[28:31]
	v_mfma_f32_16x16x32_bf16 v[24:27], v[176:179], v[204:207], v[24:27]
	v_mfma_f32_16x16x32_bf16 v[24:27], v[184:187], v[230:233], v[24:27]
	v_mfma_f32_16x16x32_bf16 v[12:15], v[168:171], v[234:237], v[12:15]
	v_mfma_f32_16x16x32_bf16 v[12:15], v[172:175], v[238:241], v[12:15]
	v_mfma_f32_16x16x32_bf16 v[8:11], v[176:179], v[234:237], v[8:11]
	v_mfma_f32_16x16x32_bf16 v[8:11], v[184:187], v[238:241], v[8:11]
	s_setprio 0
	s_barrier
	s_add_u32 s22, s22, 0x100
	s_addc_u32 s23, s23, 0
	s_add_u32 s76, s76, 0x100
	s_addc_u32 s77, s77, 0
	s_cmp_ge_u32 s78, s9
	s_mov_b32 s38, s78
	s_cbranch_scc0 .LBB0_202

; #define PG8_STAGE(bufoff, gbase, voff) do { _Pragma("unroll") for (int _i = 0; _i < 2; ++_i) \
;         __builtin_amdgcn_global_load_lds((const unsigned*)((const char*)(gbase) + (voff)[_i]), (PG8_LAS unsigned*)(lds + (bufoff) + ldsw + _i * 8192), 16, 0, 0); } while (0)
; #define PG8_LDA(dst, b, h) do { _Pragma("unroll") for (int m = 0; m < 4; ++m) _Pragma("unroll") for (int k = 0; k < 2; ++k) dst[m][k] = *(const PG8_LAS bf16x8*)(lds + PG8_SA(b, h) + aoff + m * 2048 + k * 1024); } while (0)
; #define PG8_LDB(dst, b, h) do { _Pragma("unroll") for (int n = 0; n < 2; ++n) _Pragma("unroll") for (int k = 0; k < 2; ++k) dst[n][k] = *(const PG8_LAS bf16x8*)(lds + PG8_SB(b, h) + boff + n * 2048 + k * 1024); } while (0)
; #define PG8_MMA(ai, bj, At, Bt) do { __builtin_amdgcn_s_setprio(1); _Pragma("unroll") for (int m = 0; m < 4; ++m) _Pragma("unroll") for (int n = 0; n < 2; ++n) _Pragma("unroll") for (int k = 0; k < 2; ++k) \
;         acc[ai][bj][m][n] = __builtin_amdgcn_mfma_f32_16x16x32_bf16(Bt[n][k], At[m][k], acc[ai][bj][m][n], 0, 0, 0); __builtin_amdgcn_s_setprio(0); } while (0)
; #define PG8_WAIT_V(n) asm volatile("s_waitcnt vmcnt(" #n ")" ::: "memory")
; template <class Epi, class Sched, bool ALIGN_EPI = false, bool SP2 = false>
; __device__ __forceinline__ void gemm_phase(PG8_LAS unsigned char* lds, const Gemm g, const Sched& S, const Epi& E) {
;     ...
;             if constexpr (Epi::KHOOK) { if ((t & 7) == 0 && t != 0) E.khook(acc, t >> 3, wr, fr, lds); }
;             const bool last = (t == nt - 2);
;             const char* a1 = cA + (size_t)(t + 1) * kstep;
;             const char* a2 = last ? nA : cA + (size_t)(t + 2) * kstep; const char* b2 = last ? nB : cB + (size_t)(t + 2) * kstep;
;             const char* a3 = a2 + kstep; const char* b3 = b2 + kstep;
;             if (last && has_next) S.a_ready(nxt);
;             if constexpr (SP2) {
;             PG8_LDB(B0, 0, 0); PG8_LDB(B1, 0, 1); PG8_SCHED; PG8_LDA(At, 0, 0); PG8_STAGE(PG8_SA(1, 1), a1 + hstep, voffA);
;             PG8_WAIT_V(8); PG8_WAIT_L(0); PG8_BAR; PG8_MMA(0, 0, At, B0); PG8_MMA(0, 1, At, B1); PG8_BAR; PG8_SCHED;
;             PG8_LDA(At, 0, 1); PG8_STAGE(PG8_SB(0, 0), b2, voffB); PG8_STAGE(PG8_SB(0, 1), b2 + hstep, voffB); PG8_STAGE(PG8_SA(0, 0), a2, voffA);
;             PG8_WAIT_V(8); PG8_WAIT_L(0); PG8_BAR; PG8_MMA(1, 0, At, B0); PG8_MMA(1, 1, At, B1); PG8_BAR; PG8_SCHED;
.LBB0_245:
	v_readlane_b32 s22, v252, 59
	v_readlane_b32 s23, v252, 60
	s_andn2_b64 vcc, exec, s[22:23]
	s_cbranch_vccnz .LBB0_252
	s_add_u32 s40, s6, s48
	s_addc_u32 s41, s7, s49
	s_add_u32 s37, s6, 0x100
	s_addc_u32 s80, s7, 0
	s_and_b64 s[22:23], s[12:13], exec
	s_cselect_b32 s23, s5, s80
	s_cselect_b32 s22, s4, s37
	s_add_u32 s37, s10, 0x100
	s_addc_u32 s82, s11, 0
	s_and_b64 s[80:81], s[12:13], exec
	s_cselect_b32 s85, s17, s82
	s_cselect_b32 s84, s16, s37
	s_add_i32 s83, 0, 0x14000
	v_add_u32_e32 v150, s19, v147
	v_add_u32_e32 v151, s83, v147
	ds_read_b128 v[152:155], v150
	ds_read_b128 v[156:159], v150 offset:1024
	ds_read_b128 v[160:163], v150 offset:2048
	ds_read_b128 v[164:167], v150 offset:3072
	ds_read_b128 v[168:171], v151
	ds_read_b128 v[172:175], v151 offset:1024
	ds_read_b128 v[176:179], v151 offset:2048
	ds_read_b128 v[184:187], v151 offset:3072
	v_lshl_add_u64 v[180:181], s[40:41], 0, v[2:3]
	s_add_i32 s37, s47, 0xc000
	v_lshl_add_u64 v[180:181], v[180:181], 0, s[24:25]
	s_mov_b32 m0, s37
	ds_read_b128 v[188:191], v149
	ds_read_b128 v[192:195], v149 offset:1024
	ds_read_b128 v[196:199], v149 offset:2048
	ds_read_b128 v[200:203], v149 offset:3072
	ds_read_b128 v[204:207], v149 offset:4096
	ds_read_b128 v[230:233], v149 offset:5120
	ds_read_b128 v[234:237], v149 offset:6144
	ds_read_b128 v[238:241], v149 offset:7168
	global_load_lds_dwordx4 v[180:181], off
	v_lshl_add_u64 v[180:181], s[40:41], 0, v[136:137]
	s_add_i32 s80, s47, 0xe000
	v_lshl_add_u64 v[180:181], v[180:181], 0, s[24:25]
	s_mov_b32 m0, s80
	s_nop 0
	global_load_lds_dwordx4 v[180:181], off
	s_waitcnt vmcnt(8)
	s_waitcnt lgkmcnt(0)
	s_barrier
	s_setprio 1
	s_waitcnt lgkmcnt(0)
	v_mfma_f32_16x16x32_bf16 v[132:135], v[152:155], v[188:191], v[132:135]
	v_mfma_f32_16x16x32_bf16 v[132:135], v[156:159], v[192:195], v[132:135]
	v_mfma_f32_16x16x32_bf16 v[128:131], v[160:163], v[188:191], v[128:131]
	v_mfma_f32_16x16x32_bf16 v[128:131], v[164:167], v[192:195], v[128:131]
	v_mfma_f32_16x16x32_bf16 v[116:119], v[152:155], v[196:199], v[116:119]
	v_mfma_f32_16x16x32_bf16 v[116:119], v[156:159], v[200:203], v[116:119]
	v_mfma_f32_16x16x32_bf16 v[112:115], v[160:163], v[196:199], v[112:115]
	v_mfma_f32_16x16x32_bf16 v[112:115], v[164:167], v[200:203], v[112:115]
	v_mfma_f32_16x16x32_bf16 v[100:103], v[152:155], v[204:207], v[100:103]
	v_mfma_f32_16x16x32_bf16 v[100:103], v[156:159], v[230:233], v[100:103]
	v_mfma_f32_16x16x32_bf16 v[96:99], v[160:163], v[204:207], v[96:99]
	v_mfma_f32_16x16x32_bf16 v[96:99], v[164:167], v[230:233], v[96:99]
	v_mfma_f32_16x16x32_bf16 v[84:87], v[152:155], v[234:237], v[84:87]
	v_mfma_f32_16x16x32_bf16 v[84:87], v[156:159], v[238:241], v[84:87]
	v_mfma_f32_16x16x32_bf16 v[80:83], v[160:163], v[234:237], v[80:83]
	v_mfma_f32_16x16x32_bf16 v[80:83], v[164:167], v[238:241], v[80:83]
	s_setprio 0
	s_setprio 1
	v_mfma_f32_16x16x32_bf16 v[124:127], v[168:171], v[188:191], v[124:127]
	v_mfma_f32_16x16x32_bf16 v[124:127], v[172:175], v[192:195], v[124:127]
	v_mfma_f32_16x16x32_bf16 v[120:123], v[176:179], v[188:191], v[120:123]
	v_mfma_f32_16x16x32_bf16 v[120:123], v[184:187], v[192:195], v[120:123]
	v_mfma_f32_16x16x32_bf16 v[108:111], v[168:171], v[196:199], v[108:111]
	v_mfma_f32_16x16x32_bf16 v[108:111], v[172:175], v[200:203], v[108:111]
	v_mfma_f32_16x16x32_bf16 v[104:107], v[176:179], v[196:199], v[104:107]
	v_mfma_f32_16x16x32_bf16 v[104:107], v[184:187], v[200:203], v[104:107]
	v_mfma_f32_16x16x32_bf16 v[92:95], v[168:171], v[204:207], v[92:95]
	v_mfma_f32_16x16x32_bf16 v[92:95], v[172:175], v[230:233], v[92:95]
	v_mfma_f32_16x16x32_bf16 v[88:91], v[176:179], v[204:207], v[88:91]
	v_mfma_f32_16x16x32_bf16 v[88:91], v[184:187], v[230:233], v[88:91]
	v_mfma_f32_16x16x32_bf16 v[76:79], v[168:171], v[234:237], v[76:79]
	v_mfma_f32_16x16x32_bf16 v[76:79], v[172:175], v[238:241], v[76:79]
	v_mfma_f32_16x16x32_bf16 v[72:75], v[176:179], v[234:237], v[72:75]
	v_mfma_f32_16x16x32_bf16 v[72:75], v[184:187], v[238:241], v[72:75]
	s_setprio 0
	s_barrier
	s_add_i32 s81, s19, s46
	s_add_i32 s82, s81, 0x2000
	v_lshl_add_u64 v[208:209], s[84:85], 0, v[0:1]
	s_mov_b32 m0, s81
	s_add_u32 s40, s84, s48
	ds_read_b128 v[188:191], v149 offset:16384
	ds_read_b128 v[192:195], v149 offset:17408
	ds_read_b128 v[196:199], v149 offset:18432
	ds_read_b128 v[200:203], v149 offset:19456
	ds_read_b128 v[204:207], v149 offset:20480
	ds_read_b128 v[230:233], v149 offset:21504
	ds_read_b128 v[234:237], v149 offset:22528
	ds_read_b128 v[238:241], v149 offset:23552
	global_load_lds_dwordx4 v[208:209], off
	v_lshl_add_u64 v[216:217], s[84:85], 0, v[138:139]
	s_mov_b32 m0, s82
	s_addc_u32 s41, s85, s49
	s_add_i32 s83, s83, s46
	global_load_lds_dwordx4 v[216:217], off
	v_lshl_add_u64 v[224:225], s[40:41], 0, v[0:1]
	s_mov_b32 m0, s83
	s_add_i32 s84, s83, 0x2000
	global_load_lds_dwordx4 v[224:225], off
	v_lshl_add_u64 v[226:227], s[40:41], 0, v[138:139]
	s_mov_b32 m0, s84
	v_lshl_add_u64 v[228:229], s[22:23], 0, v[2:3]
	global_load_lds_dwordx4 v[226:227], off
	s_mov_b32 m0, s47
	v_lshl_add_u64 v[242:243], s[22:23], 0, v[136:137]
	global_load_lds_dwordx4 v[228:229], off
	s_mov_b32 m0, s52
	s_nop 0
	global_load_lds_dwordx4 v[242:243], off
	s_waitcnt vmcnt(8)
	s_waitcnt lgkmcnt(0)
	s_barrier
; #define PG8_STAGE(bufoff, gbase, voff) do { _Pragma("unroll") for (int _i = 0; _i < 2; ++_i) \
;         __builtin_amdgcn_global_load_lds((const unsigned*)((const char*)(gbase) + (voff)[_i]), (PG8_LAS unsigned*)(lds + (bufoff) + ldsw + _i * 8192), 16, 0, 0); } while (0)
; #define PG8_LDA(dst, b, h) do { _Pragma("unroll") for (int m = 0; m < 4; ++m) _Pragma("unroll") for (int k = 0; k < 2; ++k) dst[m][k] = *(const PG8_LAS bf16x8*)(lds + PG8_SA(b, h) + aoff + m * 2048 + k * 1024); } while (0)
; #define PG8_LDB(dst, b, h) do { _Pragma("unroll") for (int n = 0; n < 2; ++n) _Pragma("unroll") for (int k = 0; k < 2; ++k) dst[n][k] = *(const PG8_LAS bf16x8*)(lds + PG8_SB(b, h) + boff + n * 2048 + k * 1024); } while (0)
; #define PG8_MMA(ai, bj, At, Bt) do { __builtin_amdgcn_s_setprio(1); _Pragma("unroll") for (int m = 0; m < 4; ++m) _Pragma("unroll") for (int n = 0; n < 2; ++n) _Pragma("unroll") for (int k = 0; k < 2; ++k) \
;         acc[ai][bj][m][n] = __builtin_amdgcn_mfma_f32_16x16x32_bf16(Bt[n][k], At[m][k], acc[ai][bj][m][n], 0, 0, 0); __builtin_amdgcn_s_setprio(0); } while (0)
; #define PG8_WAIT_V(n) asm volatile("s_waitcnt vmcnt(" #n ")" ::: "memory")
; #define PG8_WAIT_L(n) asm volatile("s_waitcnt lgkmcnt(" #n ")" ::: "memory")
; #define PG8_BAR __builtin_amdgcn_s_barrier()
; #define PG8_SCHED __builtin_amdgcn_sched_barrier(0)
; template <class Epi, class Sched, bool ALIGN_EPI = false, bool SP2 = false>
; __device__ __forceinline__ void gemm_phase(PG8_LAS unsigned char* lds, const Gemm g, const Sched& S, const Epi& E) {
;     ...
;             PG8_WAIT_V(8); PG8_WAIT_L(0); PG8_BAR; PG8_MMA(1, 0, At, B0); PG8_MMA(1, 1, At, B1); PG8_BAR; PG8_SCHED;
;             PG8_LDB(B0, 1, 0); PG8_LDB(B1, 1, 1); PG8_SCHED; PG8_LDA(At, 1, 0); PG8_STAGE(PG8_SA(0, 1), a2 + hstep, voffA);
;             PG8_WAIT_V(8); PG8_WAIT_L(0); PG8_BAR; PG8_MMA(0, 0, At, B0); PG8_MMA(0, 1, At, B1); PG8_BAR; PG8_SCHED;
	s_setprio 1
	s_waitcnt lgkmcnt(0)
	v_mfma_f32_16x16x32_bf16 v[68:71], v[152:155], v[188:191], v[68:71]
	v_mfma_f32_16x16x32_bf16 v[68:71], v[156:159], v[192:195], v[68:71]
	v_mfma_f32_16x16x32_bf16 v[64:67], v[160:163], v[188:191], v[64:67]
	v_mfma_f32_16x16x32_bf16 v[64:67], v[164:167], v[192:195], v[64:67]
	v_mfma_f32_16x16x32_bf16 v[52:55], v[152:155], v[196:199], v[52:55]
	v_mfma_f32_16x16x32_bf16 v[52:55], v[156:159], v[200:203], v[52:55]
	v_mfma_f32_16x16x32_bf16 v[48:51], v[160:163], v[196:199], v[48:51]
	v_mfma_f32_16x16x32_bf16 v[48:51], v[164:167], v[200:203], v[48:51]
	v_mfma_f32_16x16x32_bf16 v[36:39], v[152:155], v[204:207], v[36:39]
	v_mfma_f32_16x16x32_bf16 v[36:39], v[156:159], v[230:233], v[36:39]
	v_mfma_f32_16x16x32_bf16 v[32:35], v[160:163], v[204:207], v[32:35]
	v_mfma_f32_16x16x32_bf16 v[32:35], v[164:167], v[230:233], v[32:35]
	v_mfma_f32_16x16x32_bf16 v[20:23], v[152:155], v[234:237], v[20:23]
	v_mfma_f32_16x16x32_bf16 v[20:23], v[156:159], v[238:241], v[20:23]
	v_mfma_f32_16x16x32_bf16 v[16:19], v[160:163], v[234:237], v[16:19]
	v_mfma_f32_16x16x32_bf16 v[16:19], v[164:167], v[238:241], v[16:19]
	s_setprio 0
	s_setprio 1
	v_mfma_f32_16x16x32_bf16 v[60:63], v[168:171], v[188:191], v[60:63]
	v_mfma_f32_16x16x32_bf16 v[60:63], v[172:175], v[192:195], v[60:63]
	v_mfma_f32_16x16x32_bf16 v[56:59], v[176:179], v[188:191], v[56:59]
	v_mfma_f32_16x16x32_bf16 v[56:59], v[184:187], v[192:195], v[56:59]
	v_mfma_f32_16x16x32_bf16 v[44:47], v[168:171], v[196:199], v[44:47]
	v_mfma_f32_16x16x32_bf16 v[44:47], v[172:175], v[200:203], v[44:47]
	v_mfma_f32_16x16x32_bf16 v[40:43], v[176:179], v[196:199], v[40:43]
	v_mfma_f32_16x16x32_bf16 v[40:43], v[184:187], v[200:203], v[40:43]
	v_mfma_f32_16x16x32_bf16 v[28:31], v[168:171], v[204:207], v[28:31]
	v_mfma_f32_16x16x32_bf16 v[28:31], v[172:175], v[230:233], v[28:31]
	v_mfma_f32_16x16x32_bf16 v[24:27], v[176:179], v[204:207], v[24:27]
	v_mfma_f32_16x16x32_bf16 v[24:27], v[184:187], v[230:233], v[24:27]
	v_mfma_f32_16x16x32_bf16 v[12:15], v[168:171], v[234:237], v[12:15]
	v_mfma_f32_16x16x32_bf16 v[12:15], v[172:175], v[238:241], v[12:15]
	v_mfma_f32_16x16x32_bf16 v[8:11], v[176:179], v[234:237], v[8:11]
	v_mfma_f32_16x16x32_bf16 v[8:11], v[184:187], v[238:241], v[8:11]
	s_setprio 0
	s_barrier
	s_add_i32 s87, 0, 0x1c000
	v_add_u32_e32 v152, s91, v147
	v_add_u32_e32 v153, s87, v147
	ds_read_b128 v[154:157], v152
	ds_read_b128 v[158:161], v152 offset:1024
	ds_read_b128 v[162:165], v152 offset:2048
	ds_read_b128 v[166:169], v152 offset:3072
	ds_read_b128 v[170:173], v153
	ds_read_b128 v[174:177], v153 offset:1024
	ds_read_b128 v[178:181], v153 offset:2048
	ds_read_b128 v[184:187], v153 offset:3072
	s_add_u32 s22, s22, s48
	s_addc_u32 s23, s23, s49
	s_mov_b32 m0, s53
	v_lshl_add_u64 v[244:245], s[22:23], 0, v[2:3]
	ds_read_b128 v[188:191], v149 offset:32768
	ds_read_b128 v[192:195], v149 offset:33792
	ds_read_b128 v[196:199], v149 offset:34816
	ds_read_b128 v[200:203], v149 offset:35840
	ds_read_b128 v[204:207], v149 offset:36864
	ds_read_b128 v[230:233], v149 offset:37888
	ds_read_b128 v[234:237], v149 offset:38912
	ds_read_b128 v[238:241], v149 offset:39936
	global_load_lds_dwordx4 v[244:245], off
	v_lshl_add_u64 v[244:245], s[22:23], 0, v[136:137]
	s_mov_b32 m0, s72
	s_nop 0
	global_load_lds_dwordx4 v[244:245], off
	s_waitcnt vmcnt(8)
	s_waitcnt lgkmcnt(0)
	s_barrier
	s_setprio 1
	s_waitcnt lgkmcnt(0)
	v_mfma_f32_16x16x32_bf16 v[132:135], v[154:157], v[188:191], v[132:135]
	v_mfma_f32_16x16x32_bf16 v[132:135], v[158:161], v[192:195], v[132:135]
	v_mfma_f32_16x16x32_bf16 v[128:131], v[162:165], v[188:191], v[128:131]
	v_mfma_f32_16x16x32_bf16 v[128:131], v[166:169], v[192:195], v[128:131]
	v_mfma_f32_16x16x32_bf16 v[116:119], v[154:157], v[196:199], v[116:119]
	v_mfma_f32_16x16x32_bf16 v[116:119], v[158:161], v[200:203], v[116:119]
	v_mfma_f32_16x16x32_bf16 v[112:115], v[162:165], v[196:199], v[112:115]
	v_mfma_f32_16x16x32_bf16 v[112:115], v[166:169], v[200:203], v[112:115]
	v_mfma_f32_16x16x32_bf16 v[100:103], v[154:157], v[204:207], v[100:103]
	v_mfma_f32_16x16x32_bf16 v[100:103], v[158:161], v[230:233], v[100:103]
	v_mfma_f32_16x16x32_bf16 v[96:99], v[162:165], v[204:207], v[96:99]
	v_mfma_f32_16x16x32_bf16 v[96:99], v[166:169], v[230:233], v[96:99]
	v_mfma_f32_16x16x32_bf16 v[84:87], v[154:157], v[234:237], v[84:87]
	v_mfma_f32_16x16x32_bf16 v[84:87], v[158:161], v[238:241], v[84:87]
	v_mfma_f32_16x16x32_bf16 v[80:83], v[162:165], v[234:237], v[80:83]
	v_mfma_f32_16x16x32_bf16 v[80:83], v[166:169], v[238:241], v[80:83]
	s_setprio 0
	s_setprio 1
	v_mfma_f32_16x16x32_bf16 v[124:127], v[170:173], v[188:191], v[124:127]
	v_mfma_f32_16x16x32_bf16 v[124:127], v[174:177], v[192:195], v[124:127]
	v_mfma_f32_16x16x32_bf16 v[120:123], v[178:181], v[188:191], v[120:123]
	v_mfma_f32_16x16x32_bf16 v[120:123], v[184:187], v[192:195], v[120:123]
	v_mfma_f32_16x16x32_bf16 v[108:111], v[170:173], v[196:199], v[108:111]
	v_mfma_f32_16x16x32_bf16 v[108:111], v[174:177], v[200:203], v[108:111]
	v_mfma_f32_16x16x32_bf16 v[104:107], v[178:181], v[196:199], v[104:107]
	v_mfma_f32_16x16x32_bf16 v[104:107], v[184:187], v[200:203], v[104:107]
	v_mfma_f32_16x16x32_bf16 v[92:95], v[170:173], v[204:207], v[92:95]
	v_mfma_f32_16x16x32_bf16 v[92:95], v[174:177], v[230:233], v[92:95]
	v_mfma_f32_16x16x32_bf16 v[88:91], v[178:181], v[204:207], v[88:91]
	v_mfma_f32_16x16x32_bf16 v[88:91], v[184:187], v[230:233], v[88:91]
	v_mfma_f32_16x16x32_bf16 v[76:79], v[170:173], v[234:237], v[76:79]
	v_mfma_f32_16x16x32_bf16 v[76:79], v[174:177], v[238:241], v[76:79]
	v_mfma_f32_16x16x32_bf16 v[72:75], v[178:181], v[234:237], v[72:75]
	v_mfma_f32_16x16x32_bf16 v[72:75], v[184:187], v[238:241], v[72:75]
	s_setprio 0
	s_barrier
; #define PG8_STAGE(bufoff, gbase, voff) do { _Pragma("unroll") for (int _i = 0; _i < 2; ++_i) \
;         __builtin_amdgcn_global_load_lds((const unsigned*)((const char*)(gbase) + (voff)[_i]), (PG8_LAS unsigned*)(lds + (bufoff) + ldsw + _i * 8192), 16, 0, 0); } while (0)
; #define PG8_LDA(dst, b, h) do { _Pragma("unroll") for (int m = 0; m < 4; ++m) _Pragma("unroll") for (int k = 0; k < 2; ++k) dst[m][k] = *(const PG8_LAS bf16x8*)(lds + PG8_SA(b, h) + aoff + m * 2048 + k * 1024); } while (0)
; #define PG8_MMA(ai, bj, At, Bt) do { __builtin_amdgcn_s_setprio(1); _Pragma("unroll") for (int m = 0; m < 4; ++m) _Pragma("unroll") for (int n = 0; n < 2; ++n) _Pragma("unroll") for (int k = 0; k < 2; ++k) \
;         acc[ai][bj][m][n] = __builtin_amdgcn_mfma_f32_16x16x32_bf16(Bt[n][k], At[m][k], acc[ai][bj][m][n], 0, 0, 0); __builtin_amdgcn_s_setprio(0); } while (0)
; #define PG8_WAIT_V(n) asm volatile("s_waitcnt vmcnt(" #n ")" ::: "memory")
; #define PG8_WAIT_L(n) asm volatile("s_waitcnt lgkmcnt(" #n ")" ::: "memory")
; #define PG8_BAR __builtin_amdgcn_s_barrier()
; #define PG8_SCHED __builtin_amdgcn_sched_barrier(0)
; template <class Epi, class Sched, bool ALIGN_EPI = false, bool SP2 = false>
; __device__ __forceinline__ void gemm_phase(PG8_LAS unsigned char* lds, const Gemm g, const Sched& S, const Epi& E) {
;     ...
;             if constexpr (Epi::KHOOK) { if ((t & 7) == 0 && t != 0) E.khook(acc, t >> 3, wr, fr, lds); }
;     ...
;             PG8_LDA(At, 1, 1); PG8_STAGE(PG8_SB(1, 0), b3, voffB); PG8_STAGE(PG8_SB(1, 1), b3 + hstep, voffB); PG8_STAGE(PG8_SA(1, 0), a3, voffA);
;             PG8_WAIT_V(8); PG8_WAIT_L(0); PG8_BAR; PG8_MMA(1, 0, At, B0); PG8_MMA(1, 1, At, B1); PG8_BAR; PG8_SCHED;
	s_add_i32 s85, s91, s46
	v_lshl_add_u64 v[208:209], v[208:209], 0, s[24:25]
	s_mov_b32 m0, s85
	s_add_i32 s86, s85, 0x2000
	ds_read_b128 v[188:191], v149 offset:49152
	ds_read_b128 v[192:195], v149 offset:50176
	ds_read_b128 v[196:199], v149 offset:51200
	ds_read_b128 v[200:203], v149 offset:52224
	ds_read_b128 v[204:207], v149 offset:53248
	ds_read_b128 v[230:233], v149 offset:54272
	ds_read_b128 v[234:237], v149 offset:55296
	ds_read_b128 v[238:241], v149 offset:56320
	global_load_lds_dwordx4 v[208:209], off
	v_lshl_add_u64 v[208:209], v[216:217], 0, s[24:25]
	s_mov_b32 m0, s86
	s_add_i32 s87, s87, s46
	global_load_lds_dwordx4 v[208:209], off
	v_lshl_add_u64 v[208:209], v[224:225], 0, s[24:25]
	s_mov_b32 m0, s87
	s_add_i32 s88, s87, 0x2000
	global_load_lds_dwordx4 v[208:209], off
	v_lshl_add_u64 v[208:209], v[226:227], 0, s[24:25]
	s_mov_b32 m0, s88
	s_nop 0
	global_load_lds_dwordx4 v[208:209], off
	v_lshl_add_u64 v[208:209], v[228:229], 0, s[24:25]
	s_mov_b32 m0, s75
	s_nop 0
	global_load_lds_dwordx4 v[208:209], off
	v_lshl_add_u64 v[208:209], v[242:243], 0, s[24:25]
	s_mov_b32 m0, s76
	s_nop 0
	global_load_lds_dwordx4 v[208:209], off
	s_waitcnt vmcnt(8)
	s_waitcnt lgkmcnt(0)
	s_barrier
	s_setprio 1
	s_waitcnt lgkmcnt(0)
	v_mfma_f32_16x16x32_bf16 v[68:71], v[154:157], v[188:191], v[68:71]
	v_mfma_f32_16x16x32_bf16 v[68:71], v[158:161], v[192:195], v[68:71]
	v_mfma_f32_16x16x32_bf16 v[64:67], v[162:165], v[188:191], v[64:67]
	v_mfma_f32_16x16x32_bf16 v[64:67], v[166:169], v[192:195], v[64:67]
	v_mfma_f32_16x16x32_bf16 v[52:55], v[154:157], v[196:199], v[52:55]
	v_mfma_f32_16x16x32_bf16 v[52:55], v[158:161], v[200:203], v[52:55]
	v_mfma_f32_16x16x32_bf16 v[48:51], v[162:165], v[196:199], v[48:51]
	v_mfma_f32_16x16x32_bf16 v[48:51], v[166:169], v[200:203], v[48:51]
	v_mfma_f32_16x16x32_bf16 v[36:39], v[154:157], v[204:207], v[36:39]
	v_mfma_f32_16x16x32_bf16 v[36:39], v[158:161], v[230:233], v[36:39]
	v_mfma_f32_16x16x32_bf16 v[32:35], v[162:165], v[204:207], v[32:35]
	v_mfma_f32_16x16x32_bf16 v[32:35], v[166:169], v[230:233], v[32:35]
	v_mfma_f32_16x16x32_bf16 v[20:23], v[154:157], v[234:237], v[20:23]
	v_mfma_f32_16x16x32_bf16 v[20:23], v[158:161], v[238:241], v[20:23]
	v_mfma_f32_16x16x32_bf16 v[16:19], v[162:165], v[234:237], v[16:19]
	v_mfma_f32_16x16x32_bf16 v[16:19], v[166:169], v[238:241], v[16:19]
	s_setprio 0
	s_setprio 1
	v_mfma_f32_16x16x32_bf16 v[60:63], v[170:173], v[188:191], v[60:63]
	v_mfma_f32_16x16x32_bf16 v[60:63], v[174:177], v[192:195], v[60:63]
	v_mfma_f32_16x16x32_bf16 v[56:59], v[178:181], v[188:191], v[56:59]
	v_mfma_f32_16x16x32_bf16 v[56:59], v[184:187], v[192:195], v[56:59]
	v_mfma_f32_16x16x32_bf16 v[44:47], v[170:173], v[196:199], v[44:47]
	v_mfma_f32_16x16x32_bf16 v[44:47], v[174:177], v[200:203], v[44:47]
	v_mfma_f32_16x16x32_bf16 v[40:43], v[178:181], v[196:199], v[40:43]
	v_mfma_f32_16x16x32_bf16 v[40:43], v[184:187], v[200:203], v[40:43]
	v_mfma_f32_16x16x32_bf16 v[28:31], v[170:173], v[204:207], v[28:31]
	v_mfma_f32_16x16x32_bf16 v[28:31], v[174:177], v[230:233], v[28:31]
	v_mfma_f32_16x16x32_bf16 v[24:27], v[178:181], v[204:207], v[24:27]
	v_mfma_f32_16x16x32_bf16 v[24:27], v[184:187], v[230:233], v[24:27]
	v_mfma_f32_16x16x32_bf16 v[12:15], v[170:173], v[234:237], v[12:15]
	v_mfma_f32_16x16x32_bf16 v[12:15], v[174:177], v[238:241], v[12:15]
	v_mfma_f32_16x16x32_bf16 v[8:11], v[178:181], v[234:237], v[8:11]
	v_mfma_f32_16x16x32_bf16 v[8:11], v[184:187], v[238:241], v[8:11]
	s_setprio 0
	s_barrier
	v_readlane_b32 s22, v252, 42
	v_readlane_b32 s23, v252, 43
	s_andn2_b64 vcc, exec, s[22:23]
	s_cbranch_vccnz .LBB0_251
	s_add_u32 s22, s6, 0x180
	s_addc_u32 s23, s7, 0
	s_add_u32 s89, s10, 0x200
	s_addc_u32 s92, s11, 0
	s_mov_b32 s93, 4
	v_mov_b32_e32 v154, v148
	s_add_i32 s40, s93, -2
	s_and_b32 s40, s40, 6
	s_cmp_lg_u32 s40, 0
	s_cbranch_scc1 .LBB0_250
	s_branch .LBB0_249

; #define PG8_STAGE(bufoff, gbase, voff) do { _Pragma("unroll") for (int _i = 0; _i < 2; ++_i) \
;         __builtin_amdgcn_global_load_lds((const unsigned*)((const char*)(gbase) + (voff)[_i]), (PG8_LAS unsigned*)(lds + (bufoff) + ldsw + _i * 8192), 16, 0, 0); } while (0)
; #define PG8_LDA(dst, b, h) do { _Pragma("unroll") for (int m = 0; m < 4; ++m) _Pragma("unroll") for (int k = 0; k < 2; ++k) dst[m][k] = *(const PG8_LAS bf16x8*)(lds + PG8_SA(b, h) + aoff + m * 2048 + k * 1024); } while (0)
; #define PG8_LDB(dst, b, h) do { _Pragma("unroll") for (int n = 0; n < 2; ++n) _Pragma("unroll") for (int k = 0; k < 2; ++k) dst[n][k] = *(const PG8_LAS bf16x8*)(lds + PG8_SB(b, h) + boff + n * 2048 + k * 1024); } while (0)
; #define PG8_MMA(ai, bj, At, Bt) do { __builtin_amdgcn_s_setprio(1); _Pragma("unroll") for (int m = 0; m < 4; ++m) _Pragma("unroll") for (int n = 0; n < 2; ++n) _Pragma("unroll") for (int k = 0; k < 2; ++k) \
;         acc[ai][bj][m][n] = __builtin_amdgcn_mfma_f32_16x16x32_bf16(Bt[n][k], At[m][k], acc[ai][bj][m][n], 0, 0, 0); __builtin_amdgcn_s_setprio(0); } while (0)
; #define PG8_WAIT_V(n) asm volatile("s_waitcnt vmcnt(" #n ")" ::: "memory")
; #define PG8_WAIT_L(n) asm volatile("s_waitcnt lgkmcnt(" #n ")" ::: "memory")
; template <class Epi, class Sched, bool ALIGN_EPI = false, bool SP2 = false>
; __device__ __forceinline__ void gemm_phase(PG8_LAS unsigned char* lds, const Gemm g, const Sched& S, const Epi& E) {
;     ...
;             const bool last = (t == nt - 2);
;             const char* a1 = cA + (size_t)(t + 1) * kstep;
;             const char* a2 = last ? nA : cA + (size_t)(t + 2) * kstep; const char* b2 = last ? nB : cB + (size_t)(t + 2) * kstep;
;             const char* a3 = a2 + kstep; const char* b3 = b2 + kstep;
;             if (last && has_next) S.a_ready(nxt);
;             if constexpr (SP2) {
;             PG8_LDB(B0, 0, 0); PG8_LDB(B1, 0, 1); PG8_SCHED; PG8_LDA(At, 0, 0); PG8_STAGE(PG8_SA(1, 1), a1 + hstep, voffA);
;             PG8_WAIT_V(8); PG8_WAIT_L(0); PG8_BAR; PG8_MMA(0, 0, At, B0); PG8_MMA(0, 1, At, B1); PG8_BAR; PG8_SCHED;
;             PG8_LDA(At, 0, 1); PG8_STAGE(PG8_SB(0, 0), b2, voffB); PG8_STAGE(PG8_SB(0, 1), b2 + hstep, voffB); PG8_STAGE(PG8_SA(0, 0), a2, voffA);
;             PG8_WAIT_V(8); PG8_WAIT_L(0); PG8_BAR; PG8_MMA(1, 0, At, B0); PG8_MMA(1, 1, At, B1); PG8_BAR; PG8_SCHED;
.LBB0_250:
	ds_read_b128 v[156:159], v150
	ds_read_b128 v[160:163], v150 offset:1024
	ds_read_b128 v[164:167], v150 offset:2048
	ds_read_b128 v[168:171], v150 offset:3072
	ds_read_b128 v[172:175], v151
	ds_read_b128 v[176:179], v151 offset:1024
	ds_read_b128 v[184:187], v151 offset:2048
	ds_read_b128 v[188:191], v151 offset:3072
	s_add_u32 s40, s22, 0x80
	s_addc_u32 s41, s23, 0
	s_cmp_eq_u32 s9, s93
	s_cselect_b32 s40, s4, s40
	s_cselect_b32 s41, s5, s41
	s_cselect_b32 s95, s17, s92
	s_cselect_b32 s94, s16, s89
	s_mov_b32 m0, s37
	v_lshl_add_u64 v[180:181], s[22:23], 0, v[140:141]
	ds_read_b128 v[192:195], v149
	ds_read_b128 v[196:199], v149 offset:1024
	ds_read_b128 v[200:203], v149 offset:2048
	ds_read_b128 v[204:207], v149 offset:3072
	ds_read_b128 v[230:233], v149 offset:4096
	ds_read_b128 v[234:237], v149 offset:5120
	ds_read_b128 v[238:241], v149 offset:6144
	ds_read_b128 v[242:245], v149 offset:7168
	global_load_lds_dwordx4 v[180:181], off
	v_lshl_add_u64 v[180:181], s[22:23], 0, v[142:143]
	s_mov_b32 m0, s80
	s_nop 0
	global_load_lds_dwordx4 v[180:181], off
	s_waitcnt vmcnt(8)
	s_waitcnt lgkmcnt(0)
	s_barrier
	s_setprio 1
	s_waitcnt lgkmcnt(0)
	v_mfma_f32_16x16x32_bf16 v[132:135], v[156:159], v[192:195], v[132:135]
	v_mfma_f32_16x16x32_bf16 v[132:135], v[160:163], v[196:199], v[132:135]
	v_mfma_f32_16x16x32_bf16 v[128:131], v[164:167], v[192:195], v[128:131]
	v_mfma_f32_16x16x32_bf16 v[128:131], v[168:171], v[196:199], v[128:131]
	v_mfma_f32_16x16x32_bf16 v[116:119], v[156:159], v[200:203], v[116:119]
	v_mfma_f32_16x16x32_bf16 v[116:119], v[160:163], v[204:207], v[116:119]
	v_mfma_f32_16x16x32_bf16 v[112:115], v[164:167], v[200:203], v[112:115]
	v_mfma_f32_16x16x32_bf16 v[112:115], v[168:171], v[204:207], v[112:115]
	v_mfma_f32_16x16x32_bf16 v[100:103], v[156:159], v[230:233], v[100:103]
	v_mfma_f32_16x16x32_bf16 v[100:103], v[160:163], v[234:237], v[100:103]
	v_mfma_f32_16x16x32_bf16 v[96:99], v[164:167], v[230:233], v[96:99]
	v_mfma_f32_16x16x32_bf16 v[96:99], v[168:171], v[234:237], v[96:99]
	v_mfma_f32_16x16x32_bf16 v[84:87], v[156:159], v[238:241], v[84:87]
	v_mfma_f32_16x16x32_bf16 v[84:87], v[160:163], v[242:245], v[84:87]
	v_mfma_f32_16x16x32_bf16 v[80:83], v[164:167], v[238:241], v[80:83]
	v_mfma_f32_16x16x32_bf16 v[80:83], v[168:171], v[242:245], v[80:83]
	s_setprio 0
	s_setprio 1
	v_mfma_f32_16x16x32_bf16 v[124:127], v[172:175], v[192:195], v[124:127]
	v_mfma_f32_16x16x32_bf16 v[124:127], v[176:179], v[196:199], v[124:127]
	v_mfma_f32_16x16x32_bf16 v[120:123], v[184:187], v[192:195], v[120:123]
	v_mfma_f32_16x16x32_bf16 v[120:123], v[188:191], v[196:199], v[120:123]
	v_mfma_f32_16x16x32_bf16 v[108:111], v[172:175], v[200:203], v[108:111]
	v_mfma_f32_16x16x32_bf16 v[108:111], v[176:179], v[204:207], v[108:111]
	v_mfma_f32_16x16x32_bf16 v[104:107], v[184:187], v[200:203], v[104:107]
	v_mfma_f32_16x16x32_bf16 v[104:107], v[188:191], v[204:207], v[104:107]
	v_mfma_f32_16x16x32_bf16 v[92:95], v[172:175], v[230:233], v[92:95]
	v_mfma_f32_16x16x32_bf16 v[92:95], v[176:179], v[234:237], v[92:95]
	v_mfma_f32_16x16x32_bf16 v[88:91], v[184:187], v[230:233], v[88:91]
	v_mfma_f32_16x16x32_bf16 v[88:91], v[188:191], v[234:237], v[88:91]
	v_mfma_f32_16x16x32_bf16 v[76:79], v[172:175], v[238:241], v[76:79]
	v_mfma_f32_16x16x32_bf16 v[76:79], v[176:179], v[242:245], v[76:79]
	v_mfma_f32_16x16x32_bf16 v[72:75], v[184:187], v[238:241], v[72:75]
	v_mfma_f32_16x16x32_bf16 v[72:75], v[188:191], v[242:245], v[72:75]
	s_setprio 0
	s_barrier
	s_mov_b32 m0, s81
	v_lshl_add_u64 v[180:181], s[94:95], 0, v[0:1]
	v_lshl_add_u64 v[208:209], s[94:95], 0, v[138:139]
	s_add_u32 s94, s94, s48
	ds_read_b128 v[192:195], v149 offset:16384
	ds_read_b128 v[196:199], v149 offset:17408
	ds_read_b128 v[200:203], v149 offset:18432
	ds_read_b128 v[204:207], v149 offset:19456
	ds_read_b128 v[230:233], v149 offset:20480
	ds_read_b128 v[234:237], v149 offset:21504
	ds_read_b128 v[238:241], v149 offset:22528
	ds_read_b128 v[242:245], v149 offset:23552
	global_load_lds_dwordx4 v[180:181], off
	s_mov_b32 m0, s82
	s_addc_u32 s95, s95, s49
	global_load_lds_dwordx4 v[208:209], off
	v_lshl_add_u64 v[216:217], s[94:95], 0, v[0:1]
	s_mov_b32 m0, s83
	v_lshl_add_u64 v[224:225], s[94:95], 0, v[138:139]
	global_load_lds_dwordx4 v[216:217], off
	s_mov_b32 m0, s84
	v_lshl_add_u64 v[226:227], s[40:41], 0, v[2:3]
	global_load_lds_dwordx4 v[224:225], off
	s_mov_b32 m0, s47
	v_lshl_add_u64 v[228:229], s[40:41], 0, v[136:137]
	global_load_lds_dwordx4 v[226:227], off
	s_mov_b32 m0, s52
	s_nop 0
	global_load_lds_dwordx4 v[228:229], off
	s_waitcnt vmcnt(8)
	s_waitcnt lgkmcnt(0)
	s_barrier
; #define PG8_STAGE(bufoff, gbase, voff) do { _Pragma("unroll") for (int _i = 0; _i < 2; ++_i) \
;         __builtin_amdgcn_global_load_lds((const unsigned*)((const char*)(gbase) + (voff)[_i]), (PG8_LAS unsigned*)(lds + (bufoff) + ldsw + _i * 8192), 16, 0, 0); } while (0)
; #define PG8_LDA(dst, b, h) do { _Pragma("unroll") for (int m = 0; m < 4; ++m) _Pragma("unroll") for (int k = 0; k < 2; ++k) dst[m][k] = *(const PG8_LAS bf16x8*)(lds + PG8_SA(b, h) + aoff + m * 2048 + k * 1024); } while (0)
; #define PG8_LDB(dst, b, h) do { _Pragma("unroll") for (int n = 0; n < 2; ++n) _Pragma("unroll") for (int k = 0; k < 2; ++k) dst[n][k] = *(const PG8_LAS bf16x8*)(lds + PG8_SB(b, h) + boff + n * 2048 + k * 1024); } while (0)
; #define PG8_MMA(ai, bj, At, Bt) do { __builtin_amdgcn_s_setprio(1); _Pragma("unroll") for (int m = 0; m < 4; ++m) _Pragma("unroll") for (int n = 0; n < 2; ++n) _Pragma("unroll") for (int k = 0; k < 2; ++k) \
;         acc[ai][bj][m][n] = __builtin_amdgcn_mfma_f32_16x16x32_bf16(Bt[n][k], At[m][k], acc[ai][bj][m][n], 0, 0, 0); __builtin_amdgcn_s_setprio(0); } while (0)
; #define PG8_WAIT_V(n) asm volatile("s_waitcnt vmcnt(" #n ")" ::: "memory")
; #define PG8_WAIT_L(n) asm volatile("s_waitcnt lgkmcnt(" #n ")" ::: "memory")
; #define PG8_BAR __builtin_amdgcn_s_barrier()
; #define PG8_SCHED __builtin_amdgcn_sched_barrier(0)
; template <class Epi, class Sched, bool ALIGN_EPI = false, bool SP2 = false>
; __device__ __forceinline__ void gemm_phase(PG8_LAS unsigned char* lds, const Gemm g, const Sched& S, const Epi& E) {
;     ...
;             PG8_WAIT_V(8); PG8_WAIT_L(0); PG8_BAR; PG8_MMA(1, 0, At, B0); PG8_MMA(1, 1, At, B1); PG8_BAR; PG8_SCHED;
;             PG8_LDB(B0, 1, 0); PG8_LDB(B1, 1, 1); PG8_SCHED; PG8_LDA(At, 1, 0); PG8_STAGE(PG8_SA(0, 1), a2 + hstep, voffA);
;             PG8_WAIT_V(8); PG8_WAIT_L(0); PG8_BAR; PG8_MMA(0, 0, At, B0); PG8_MMA(0, 1, At, B1); PG8_BAR; PG8_SCHED;
	s_setprio 1
	s_waitcnt lgkmcnt(0)
	v_mfma_f32_16x16x32_bf16 v[68:71], v[156:159], v[192:195], v[68:71]
	v_mfma_f32_16x16x32_bf16 v[68:71], v[160:163], v[196:199], v[68:71]
	v_mfma_f32_16x16x32_bf16 v[64:67], v[164:167], v[192:195], v[64:67]
	v_mfma_f32_16x16x32_bf16 v[64:67], v[168:171], v[196:199], v[64:67]
	v_mfma_f32_16x16x32_bf16 v[52:55], v[156:159], v[200:203], v[52:55]
	v_mfma_f32_16x16x32_bf16 v[52:55], v[160:163], v[204:207], v[52:55]
	v_mfma_f32_16x16x32_bf16 v[48:51], v[164:167], v[200:203], v[48:51]
	v_mfma_f32_16x16x32_bf16 v[48:51], v[168:171], v[204:207], v[48:51]
	v_mfma_f32_16x16x32_bf16 v[36:39], v[156:159], v[230:233], v[36:39]
	v_mfma_f32_16x16x32_bf16 v[36:39], v[160:163], v[234:237], v[36:39]
	v_mfma_f32_16x16x32_bf16 v[32:35], v[164:167], v[230:233], v[32:35]
	v_mfma_f32_16x16x32_bf16 v[32:35], v[168:171], v[234:237], v[32:35]
	v_mfma_f32_16x16x32_bf16 v[20:23], v[156:159], v[238:241], v[20:23]
	v_mfma_f32_16x16x32_bf16 v[20:23], v[160:163], v[242:245], v[20:23]
	v_mfma_f32_16x16x32_bf16 v[16:19], v[164:167], v[238:241], v[16:19]
	v_mfma_f32_16x16x32_bf16 v[16:19], v[168:171], v[242:245], v[16:19]
	s_setprio 0
	s_setprio 1
	v_mfma_f32_16x16x32_bf16 v[60:63], v[172:175], v[192:195], v[60:63]
	v_mfma_f32_16x16x32_bf16 v[60:63], v[176:179], v[196:199], v[60:63]
	v_mfma_f32_16x16x32_bf16 v[56:59], v[184:187], v[192:195], v[56:59]
	v_mfma_f32_16x16x32_bf16 v[56:59], v[188:191], v[196:199], v[56:59]
	v_mfma_f32_16x16x32_bf16 v[44:47], v[172:175], v[200:203], v[44:47]
	v_mfma_f32_16x16x32_bf16 v[44:47], v[176:179], v[204:207], v[44:47]
	v_mfma_f32_16x16x32_bf16 v[40:43], v[184:187], v[200:203], v[40:43]
	v_mfma_f32_16x16x32_bf16 v[40:43], v[188:191], v[204:207], v[40:43]
	v_mfma_f32_16x16x32_bf16 v[28:31], v[172:175], v[230:233], v[28:31]
	v_mfma_f32_16x16x32_bf16 v[28:31], v[176:179], v[234:237], v[28:31]
	v_mfma_f32_16x16x32_bf16 v[24:27], v[184:187], v[230:233], v[24:27]
	v_mfma_f32_16x16x32_bf16 v[24:27], v[188:191], v[234:237], v[24:27]
	v_mfma_f32_16x16x32_bf16 v[12:15], v[172:175], v[238:241], v[12:15]
	v_mfma_f32_16x16x32_bf16 v[12:15], v[176:179], v[242:245], v[12:15]
	v_mfma_f32_16x16x32_bf16 v[8:11], v[184:187], v[238:241], v[8:11]
	v_mfma_f32_16x16x32_bf16 v[8:11], v[188:191], v[242:245], v[8:11]
	s_setprio 0
	s_barrier
	ds_read_b128 v[156:159], v152
	ds_read_b128 v[160:163], v152 offset:1024
	ds_read_b128 v[164:167], v152 offset:2048
	ds_read_b128 v[168:171], v152 offset:3072
	ds_read_b128 v[172:175], v153
	ds_read_b128 v[176:179], v153 offset:1024
	ds_read_b128 v[184:187], v153 offset:2048
	ds_read_b128 v[188:191], v153 offset:3072
	s_add_u32 s40, s40, s48
	s_addc_u32 s41, s41, s49
	s_mov_b32 m0, s53
	v_lshl_add_u64 v[246:247], s[40:41], 0, v[2:3]
	ds_read_b128 v[192:195], v149 offset:32768
	ds_read_b128 v[196:199], v149 offset:33792
	ds_read_b128 v[200:203], v149 offset:34816
	ds_read_b128 v[204:207], v149 offset:35840
	ds_read_b128 v[230:233], v149 offset:36864
	ds_read_b128 v[234:237], v149 offset:37888
	ds_read_b128 v[238:241], v149 offset:38912
	ds_read_b128 v[242:245], v149 offset:39936
	global_load_lds_dwordx4 v[246:247], off
	v_lshl_add_u64 v[246:247], s[40:41], 0, v[136:137]
	s_mov_b32 m0, s72
	s_nop 0
	global_load_lds_dwordx4 v[246:247], off
	s_waitcnt vmcnt(8)
	s_waitcnt lgkmcnt(0)
	s_barrier
	s_setprio 1
	s_waitcnt lgkmcnt(0)
	v_mfma_f32_16x16x32_bf16 v[132:135], v[156:159], v[192:195], v[132:135]
	v_mfma_f32_16x16x32_bf16 v[132:135], v[160:163], v[196:199], v[132:135]
	v_mfma_f32_16x16x32_bf16 v[128:131], v[164:167], v[192:195], v[128:131]
	v_mfma_f32_16x16x32_bf16 v[128:131], v[168:171], v[196:199], v[128:131]
	v_mfma_f32_16x16x32_bf16 v[116:119], v[156:159], v[200:203], v[116:119]
	v_mfma_f32_16x16x32_bf16 v[116:119], v[160:163], v[204:207], v[116:119]
	v_mfma_f32_16x16x32_bf16 v[112:115], v[164:167], v[200:203], v[112:115]
	v_mfma_f32_16x16x32_bf16 v[112:115], v[168:171], v[204:207], v[112:115]
	v_mfma_f32_16x16x32_bf16 v[100:103], v[156:159], v[230:233], v[100:103]
	v_mfma_f32_16x16x32_bf16 v[100:103], v[160:163], v[234:237], v[100:103]
	v_mfma_f32_16x16x32_bf16 v[96:99], v[164:167], v[230:233], v[96:99]
	v_mfma_f32_16x16x32_bf16 v[96:99], v[168:171], v[234:237], v[96:99]
	v_mfma_f32_16x16x32_bf16 v[84:87], v[156:159], v[238:241], v[84:87]
	v_mfma_f32_16x16x32_bf16 v[84:87], v[160:163], v[242:245], v[84:87]
	v_mfma_f32_16x16x32_bf16 v[80:83], v[164:167], v[238:241], v[80:83]
	v_mfma_f32_16x16x32_bf16 v[80:83], v[168:171], v[242:245], v[80:83]
	s_setprio 0
	s_setprio 1
	v_mfma_f32_16x16x32_bf16 v[124:127], v[172:175], v[192:195], v[124:127]
	v_mfma_f32_16x16x32_bf16 v[124:127], v[176:179], v[196:199], v[124:127]
	v_mfma_f32_16x16x32_bf16 v[120:123], v[184:187], v[192:195], v[120:123]
	v_mfma_f32_16x16x32_bf16 v[120:123], v[188:191], v[196:199], v[120:123]
	v_mfma_f32_16x16x32_bf16 v[108:111], v[172:175], v[200:203], v[108:111]
	v_mfma_f32_16x16x32_bf16 v[108:111], v[176:179], v[204:207], v[108:111]
	v_mfma_f32_16x16x32_bf16 v[104:107], v[184:187], v[200:203], v[104:107]
	v_mfma_f32_16x16x32_bf16 v[104:107], v[188:191], v[204:207], v[104:107]
	v_mfma_f32_16x16x32_bf16 v[92:95], v[172:175], v[230:233], v[92:95]
	v_mfma_f32_16x16x32_bf16 v[92:95], v[176:179], v[234:237], v[92:95]
	v_mfma_f32_16x16x32_bf16 v[88:91], v[184:187], v[230:233], v[88:91]
	v_mfma_f32_16x16x32_bf16 v[88:91], v[188:191], v[234:237], v[88:91]
	v_mfma_f32_16x16x32_bf16 v[76:79], v[172:175], v[238:241], v[76:79]
	v_mfma_f32_16x16x32_bf16 v[76:79], v[176:179], v[242:245], v[76:79]
	v_mfma_f32_16x16x32_bf16 v[72:75], v[184:187], v[238:241], v[72:75]
	v_mfma_f32_16x16x32_bf16 v[72:75], v[188:191], v[242:245], v[72:75]
	s_setprio 0
	s_barrier
; #define PG8_STAGE(bufoff, gbase, voff) do { _Pragma("unroll") for (int _i = 0; _i < 2; ++_i) \
;         __builtin_amdgcn_global_load_lds((const unsigned*)((const char*)(gbase) + (voff)[_i]), (PG8_LAS unsigned*)(lds + (bufoff) + ldsw + _i * 8192), 16, 0, 0); } while (0)
; #define PG8_LDA(dst, b, h) do { _Pragma("unroll") for (int m = 0; m < 4; ++m) _Pragma("unroll") for (int k = 0; k < 2; ++k) dst[m][k] = *(const PG8_LAS bf16x8*)(lds + PG8_SA(b, h) + aoff + m * 2048 + k * 1024); } while (0)
; #define PG8_MMA(ai, bj, At, Bt) do { __builtin_amdgcn_s_setprio(1); _Pragma("unroll") for (int m = 0; m < 4; ++m) _Pragma("unroll") for (int n = 0; n < 2; ++n) _Pragma("unroll") for (int k = 0; k < 2; ++k) \
;         acc[ai][bj][m][n] = __builtin_amdgcn_mfma_f32_16x16x32_bf16(Bt[n][k], At[m][k], acc[ai][bj][m][n], 0, 0, 0); __builtin_amdgcn_s_setprio(0); } while (0)
; #define PG8_WAIT_V(n) asm volatile("s_waitcnt vmcnt(" #n ")" ::: "memory")
; #define PG8_WAIT_L(n) asm volatile("s_waitcnt lgkmcnt(" #n ")" ::: "memory")
; #define PG8_BAR __builtin_amdgcn_s_barrier()
; #define PG8_SCHED __builtin_amdgcn_sched_barrier(0)
; template <class Epi, class Sched, bool ALIGN_EPI = false, bool SP2 = false>
; __device__ __forceinline__ void gemm_phase(PG8_LAS unsigned char* lds, const Gemm g, const Sched& S, const Epi& E) {
;     ...
;         for (int t = 0; t < nt; t += 2) {
;     ...
;             PG8_LDA(At, 1, 1); PG8_STAGE(PG8_SB(1, 0), b3, voffB); PG8_STAGE(PG8_SB(1, 1), b3 + hstep, voffB); PG8_STAGE(PG8_SA(1, 0), a3, voffA);
;             PG8_WAIT_V(8); PG8_WAIT_L(0); PG8_BAR; PG8_MMA(1, 0, At, B0); PG8_MMA(1, 1, At, B1); PG8_BAR; PG8_SCHED;
	s_mov_b32 m0, s85
	v_lshl_add_u64 v[180:181], v[180:181], 0, s[24:25]
	ds_read_b128 v[192:195], v149 offset:49152
	ds_read_b128 v[196:199], v149 offset:50176
	ds_read_b128 v[200:203], v149 offset:51200
	ds_read_b128 v[204:207], v149 offset:52224
	ds_read_b128 v[230:233], v149 offset:53248
	ds_read_b128 v[234:237], v149 offset:54272
	ds_read_b128 v[238:241], v149 offset:55296
	ds_read_b128 v[242:245], v149 offset:56320
	global_load_lds_dwordx4 v[180:181], off
	v_lshl_add_u64 v[180:181], v[208:209], 0, s[24:25]
	s_mov_b32 m0, s86
	s_nop 0
	global_load_lds_dwordx4 v[180:181], off
	v_lshl_add_u64 v[180:181], v[216:217], 0, s[24:25]
	s_mov_b32 m0, s87
	s_nop 0
	global_load_lds_dwordx4 v[180:181], off
	v_lshl_add_u64 v[180:181], v[224:225], 0, s[24:25]
	s_mov_b32 m0, s88
	s_nop 0
	global_load_lds_dwordx4 v[180:181], off
	v_lshl_add_u64 v[180:181], v[226:227], 0, s[24:25]
	s_mov_b32 m0, s75
	s_nop 0
	global_load_lds_dwordx4 v[180:181], off
	v_lshl_add_u64 v[180:181], v[228:229], 0, s[24:25]
	s_mov_b32 m0, s76
	s_nop 0
	global_load_lds_dwordx4 v[180:181], off
	s_waitcnt vmcnt(8)
	s_waitcnt lgkmcnt(0)
	s_barrier
	s_setprio 1
	s_waitcnt lgkmcnt(0)
	v_mfma_f32_16x16x32_bf16 v[68:71], v[156:159], v[192:195], v[68:71]
	v_mfma_f32_16x16x32_bf16 v[68:71], v[160:163], v[196:199], v[68:71]
	v_mfma_f32_16x16x32_bf16 v[64:67], v[164:167], v[192:195], v[64:67]
	v_mfma_f32_16x16x32_bf16 v[64:67], v[168:171], v[196:199], v[64:67]
	v_mfma_f32_16x16x32_bf16 v[52:55], v[156:159], v[200:203], v[52:55]
	v_mfma_f32_16x16x32_bf16 v[52:55], v[160:163], v[204:207], v[52:55]
	v_mfma_f32_16x16x32_bf16 v[48:51], v[164:167], v[200:203], v[48:51]
	v_mfma_f32_16x16x32_bf16 v[48:51], v[168:171], v[204:207], v[48:51]
	v_mfma_f32_16x16x32_bf16 v[36:39], v[156:159], v[230:233], v[36:39]
	v_mfma_f32_16x16x32_bf16 v[36:39], v[160:163], v[234:237], v[36:39]
	v_mfma_f32_16x16x32_bf16 v[32:35], v[164:167], v[230:233], v[32:35]
	v_mfma_f32_16x16x32_bf16 v[32:35], v[168:171], v[234:237], v[32:35]
	v_mfma_f32_16x16x32_bf16 v[20:23], v[156:159], v[238:241], v[20:23]
	v_mfma_f32_16x16x32_bf16 v[20:23], v[160:163], v[242:245], v[20:23]
	v_mfma_f32_16x16x32_bf16 v[16:19], v[164:167], v[238:241], v[16:19]
	v_mfma_f32_16x16x32_bf16 v[16:19], v[168:171], v[242:245], v[16:19]
	s_setprio 0
	s_setprio 1
	v_mfma_f32_16x16x32_bf16 v[60:63], v[172:175], v[192:195], v[60:63]
	v_mfma_f32_16x16x32_bf16 v[60:63], v[176:179], v[196:199], v[60:63]
	v_mfma_f32_16x16x32_bf16 v[56:59], v[184:187], v[192:195], v[56:59]
	v_mfma_f32_16x16x32_bf16 v[56:59], v[188:191], v[196:199], v[56:59]
	v_mfma_f32_16x16x32_bf16 v[44:47], v[172:175], v[200:203], v[44:47]
	v_mfma_f32_16x16x32_bf16 v[44:47], v[176:179], v[204:207], v[44:47]
	v_mfma_f32_16x16x32_bf16 v[40:43], v[184:187], v[200:203], v[40:43]
	v_mfma_f32_16x16x32_bf16 v[40:43], v[188:191], v[204:207], v[40:43]
	v_mfma_f32_16x16x32_bf16 v[28:31], v[172:175], v[230:233], v[28:31]
	v_mfma_f32_16x16x32_bf16 v[28:31], v[176:179], v[234:237], v[28:31]
	v_mfma_f32_16x16x32_bf16 v[24:27], v[184:187], v[230:233], v[24:27]
	v_mfma_f32_16x16x32_bf16 v[24:27], v[188:191], v[234:237], v[24:27]
	v_mfma_f32_16x16x32_bf16 v[12:15], v[172:175], v[238:241], v[12:15]
	v_mfma_f32_16x16x32_bf16 v[12:15], v[176:179], v[242:245], v[12:15]
	v_mfma_f32_16x16x32_bf16 v[8:11], v[184:187], v[238:241], v[8:11]
	v_mfma_f32_16x16x32_bf16 v[8:11], v[188:191], v[242:245], v[8:11]
	s_setprio 0
	s_barrier
	s_add_i32 s40, s93, 2
	s_add_u32 s22, s22, 0x100
	s_addc_u32 s23, s23, 0
	s_add_u32 s89, s89, 0x100
	s_addc_u32 s92, s92, 0
	s_cmp_ge_u32 s93, s9
	v_add_u32_e32 v154, 0x100, v154
	s_cbranch_scc0 .LBB0_248

; #define PG8_STAGE(bufoff, gbase, voff) do { _Pragma("unroll") for (int _i = 0; _i < 2; ++_i) \
;         __builtin_amdgcn_global_load_lds((const unsigned*)((const char*)(gbase) + (voff)[_i]), (PG8_LAS unsigned*)(lds + (bufoff) + ldsw + _i * 8192), 16, 0, 0); } while (0)
; #define PG8_LDA(dst, b, h) do { _Pragma("unroll") for (int m = 0; m < 4; ++m) _Pragma("unroll") for (int k = 0; k < 2; ++k) dst[m][k] = *(const PG8_LAS bf16x8*)(lds + PG8_SA(b, h) + aoff + m * 2048 + k * 1024); } while (0)
; #define PG8_LDB(dst, b, h) do { _Pragma("unroll") for (int n = 0; n < 2; ++n) _Pragma("unroll") for (int k = 0; k < 2; ++k) dst[n][k] = *(const PG8_LAS bf16x8*)(lds + PG8_SB(b, h) + boff + n * 2048 + k * 1024); } while (0)
; #define PG8_MMA(ai, bj, At, Bt) do { __builtin_amdgcn_s_setprio(1); _Pragma("unroll") for (int m = 0; m < 4; ++m) _Pragma("unroll") for (int n = 0; n < 2; ++n) _Pragma("unroll") for (int k = 0; k < 2; ++k) \
;         acc[ai][bj][m][n] = __builtin_amdgcn_mfma_f32_16x16x32_bf16(Bt[n][k], At[m][k], acc[ai][bj][m][n], 0, 0, 0); __builtin_amdgcn_s_setprio(0); } while (0)
; #define PG8_WAIT_V(n) asm volatile("s_waitcnt vmcnt(" #n ")" ::: "memory")
; #define PG8_WAIT_L(n) asm volatile("s_waitcnt lgkmcnt(" #n ")" ::: "memory")
; template <class Epi, class Sched, bool ALIGN_EPI = false, bool SP2 = false>
; __device__ __forceinline__ void gemm_phase(PG8_LAS unsigned char* lds, const Gemm g, const Sched& S, const Epi& E) {
;     ...
;             const bool last = (t == nt - 2);
;             const char* a1 = cA + (size_t)(t + 1) * kstep;
;             const char* a2 = last ? nA : cA + (size_t)(t + 2) * kstep; const char* b2 = last ? nB : cB + (size_t)(t + 2) * kstep;
;             const char* a3 = a2 + kstep; const char* b3 = b2 + kstep;
;             if (last && has_next) S.a_ready(nxt);
;             if constexpr (SP2) {
;             PG8_LDB(B0, 0, 0); PG8_LDB(B1, 0, 1); PG8_SCHED; PG8_LDA(At, 0, 0); PG8_STAGE(PG8_SA(1, 1), a1 + hstep, voffA);
;             PG8_WAIT_V(8); PG8_WAIT_L(0); PG8_BAR; PG8_MMA(0, 0, At, B0); PG8_MMA(0, 1, At, B1); PG8_BAR; PG8_SCHED;
;             PG8_LDA(At, 0, 1); PG8_STAGE(PG8_SB(0, 0), b2, voffB); PG8_STAGE(PG8_SB(0, 1), b2 + hstep, voffB); PG8_STAGE(PG8_SA(0, 0), a2, voffA);
;             PG8_WAIT_V(8); PG8_WAIT_L(0); PG8_BAR; PG8_MMA(1, 0, At, B0); PG8_MMA(1, 1, At, B1); PG8_BAR; PG8_SCHED;
.LBB0_294:
	s_add_i32 s81, s40, 2
	s_add_u32 s82, s38, 0x80
	s_addc_u32 s41, s39, 0
	s_cmp_eq_u32 s33, s40
	s_cselect_b32 s41, s7, s41
	s_cselect_b32 s40, s6, s82
	v_add_u32_e32 v0, s19, v151
	s_cselect_b32 s83, s23, s80
	s_cselect_b32 s82, s22, s79
	s_add_i32 s84, 0, 0x14000
	ds_read_b128 v[154:157], v0
	ds_read_b128 v[158:161], v0 offset:1024
	ds_read_b128 v[162:165], v0 offset:2048
	ds_read_b128 v[166:169], v0 offset:3072
	v_add_u32_e32 v0, s84, v151
	ds_read_b128 v[170:173], v0
	ds_read_b128 v[174:177], v0 offset:1024
	ds_read_b128 v[178:181], v0 offset:2048
	ds_read_b128 v[184:187], v0 offset:3072
	v_lshl_add_u64 v[2:3], s[38:39], 0, v[144:145]
	s_add_i32 m0, s46, 0xc000
	ds_read_b128 v[188:191], v152
	ds_read_b128 v[192:195], v152 offset:1024
	ds_read_b128 v[196:199], v152 offset:2048
	ds_read_b128 v[200:203], v152 offset:3072
	ds_read_b128 v[204:207], v152 offset:4096
	ds_read_b128 v[230:233], v152 offset:5120
	ds_read_b128 v[234:237], v152 offset:6144
	ds_read_b128 v[238:241], v152 offset:7168
	global_load_lds_dwordx4 v[2:3], off
	v_lshl_add_u64 v[2:3], s[38:39], 0, v[146:147]
	s_add_i32 m0, s46, 0xe000
	s_nop 0
	global_load_lds_dwordx4 v[2:3], off
	s_waitcnt vmcnt(8)
	s_waitcnt lgkmcnt(0)
	s_barrier
	s_setprio 1
	s_waitcnt lgkmcnt(0)
	v_mfma_f32_16x16x32_bf16 v[8:11], v[154:157], v[188:191], v[8:11]
	v_mfma_f32_16x16x32_bf16 v[8:11], v[158:161], v[192:195], v[8:11]
	v_mfma_f32_16x16x32_bf16 v[12:15], v[162:165], v[188:191], v[12:15]
	v_mfma_f32_16x16x32_bf16 v[12:15], v[166:169], v[192:195], v[12:15]
	v_mfma_f32_16x16x32_bf16 v[48:51], v[154:157], v[196:199], v[48:51]
	v_mfma_f32_16x16x32_bf16 v[48:51], v[158:161], v[200:203], v[48:51]
	v_mfma_f32_16x16x32_bf16 v[52:55], v[162:165], v[196:199], v[52:55]
	v_mfma_f32_16x16x32_bf16 v[52:55], v[166:169], v[200:203], v[52:55]
	v_mfma_f32_16x16x32_bf16 v[96:99], v[154:157], v[204:207], v[96:99]
	v_mfma_f32_16x16x32_bf16 v[96:99], v[158:161], v[230:233], v[96:99]
	v_mfma_f32_16x16x32_bf16 v[100:103], v[162:165], v[204:207], v[100:103]
	v_mfma_f32_16x16x32_bf16 v[100:103], v[166:169], v[230:233], v[100:103]
	v_mfma_f32_16x16x32_bf16 v[120:123], v[154:157], v[234:237], v[120:123]
	v_mfma_f32_16x16x32_bf16 v[120:123], v[158:161], v[238:241], v[120:123]
	v_mfma_f32_16x16x32_bf16 v[124:127], v[162:165], v[234:237], v[124:127]
	v_mfma_f32_16x16x32_bf16 v[124:127], v[166:169], v[238:241], v[124:127]
	s_setprio 0
	s_setprio 1
	v_mfma_f32_16x16x32_bf16 v[24:27], v[170:173], v[188:191], v[24:27]
	v_mfma_f32_16x16x32_bf16 v[24:27], v[174:177], v[192:195], v[24:27]
	v_mfma_f32_16x16x32_bf16 v[28:31], v[178:181], v[188:191], v[28:31]
	v_mfma_f32_16x16x32_bf16 v[28:31], v[184:187], v[192:195], v[28:31]
	v_mfma_f32_16x16x32_bf16 v[72:75], v[170:173], v[196:199], v[72:75]
	v_mfma_f32_16x16x32_bf16 v[72:75], v[174:177], v[200:203], v[72:75]
	v_mfma_f32_16x16x32_bf16 v[76:79], v[178:181], v[196:199], v[76:79]
	v_mfma_f32_16x16x32_bf16 v[76:79], v[184:187], v[200:203], v[76:79]
	v_mfma_f32_16x16x32_bf16 v[112:115], v[170:173], v[204:207], v[112:115]
	v_mfma_f32_16x16x32_bf16 v[112:115], v[174:177], v[230:233], v[112:115]
	v_mfma_f32_16x16x32_bf16 v[116:119], v[178:181], v[204:207], v[116:119]
	v_mfma_f32_16x16x32_bf16 v[116:119], v[184:187], v[230:233], v[116:119]
	v_mfma_f32_16x16x32_bf16 v[128:131], v[170:173], v[234:237], v[128:131]
	v_mfma_f32_16x16x32_bf16 v[128:131], v[174:177], v[238:241], v[128:131]
	v_mfma_f32_16x16x32_bf16 v[132:135], v[178:181], v[234:237], v[132:135]
	v_mfma_f32_16x16x32_bf16 v[132:135], v[184:187], v[238:241], v[132:135]
	s_setprio 0
	s_barrier
	s_add_i32 s85, s19, s37
	v_lshl_add_u64 v[2:3], s[82:83], 0, v[140:141]
	s_mov_b32 m0, s85
	ds_read_b128 v[188:191], v152 offset:16384
	ds_read_b128 v[192:195], v152 offset:17408
	ds_read_b128 v[196:199], v152 offset:18432
	ds_read_b128 v[200:203], v152 offset:19456
	ds_read_b128 v[204:207], v152 offset:20480
	ds_read_b128 v[230:233], v152 offset:21504
	ds_read_b128 v[234:237], v152 offset:22528
	ds_read_b128 v[238:241], v152 offset:23552
	global_load_lds_dwordx4 v[2:3], off
	s_add_i32 m0, s85, 0x2000
	v_lshl_add_u64 v[208:209], s[82:83], 0, v[136:137]
	s_add_u32 s82, s82, s48
	s_addc_u32 s83, s83, s49
	s_add_i32 s84, s84, s37
	global_load_lds_dwordx4 v[208:209], off
	v_lshl_add_u64 v[216:217], s[82:83], 0, v[140:141]
	s_mov_b32 m0, s84
	v_lshl_add_u64 v[224:225], s[82:83], 0, v[136:137]
	global_load_lds_dwordx4 v[216:217], off
	s_add_i32 m0, s84, 0x2000
	v_lshl_add_u64 v[226:227], s[40:41], 0, v[142:143]
	global_load_lds_dwordx4 v[224:225], off
	s_mov_b32 m0, s46
	v_lshl_add_u64 v[228:229], s[40:41], 0, v[138:139]
	global_load_lds_dwordx4 v[226:227], off
	s_mov_b32 m0, s47
	s_nop 0
	global_load_lds_dwordx4 v[228:229], off
	s_waitcnt vmcnt(8)
	s_waitcnt lgkmcnt(0)
	s_barrier
; #define PG8_STAGE(bufoff, gbase, voff) do { _Pragma("unroll") for (int _i = 0; _i < 2; ++_i) \
;         __builtin_amdgcn_global_load_lds((const unsigned*)((const char*)(gbase) + (voff)[_i]), (PG8_LAS unsigned*)(lds + (bufoff) + ldsw + _i * 8192), 16, 0, 0); } while (0)
; #define PG8_LDA(dst, b, h) do { _Pragma("unroll") for (int m = 0; m < 4; ++m) _Pragma("unroll") for (int k = 0; k < 2; ++k) dst[m][k] = *(const PG8_LAS bf16x8*)(lds + PG8_SA(b, h) + aoff + m * 2048 + k * 1024); } while (0)
; #define PG8_LDB(dst, b, h) do { _Pragma("unroll") for (int n = 0; n < 2; ++n) _Pragma("unroll") for (int k = 0; k < 2; ++k) dst[n][k] = *(const PG8_LAS bf16x8*)(lds + PG8_SB(b, h) + boff + n * 2048 + k * 1024); } while (0)
; #define PG8_MMA(ai, bj, At, Bt) do { __builtin_amdgcn_s_setprio(1); _Pragma("unroll") for (int m = 0; m < 4; ++m) _Pragma("unroll") for (int n = 0; n < 2; ++n) _Pragma("unroll") for (int k = 0; k < 2; ++k) \
;         acc[ai][bj][m][n] = __builtin_amdgcn_mfma_f32_16x16x32_bf16(Bt[n][k], At[m][k], acc[ai][bj][m][n], 0, 0, 0); __builtin_amdgcn_s_setprio(0); } while (0)
; #define PG8_WAIT_V(n) asm volatile("s_waitcnt vmcnt(" #n ")" ::: "memory")
; #define PG8_WAIT_L(n) asm volatile("s_waitcnt lgkmcnt(" #n ")" ::: "memory")
; #define PG8_BAR __builtin_amdgcn_s_barrier()
; #define PG8_SCHED __builtin_amdgcn_sched_barrier(0)
; template <class Epi, class Sched, bool ALIGN_EPI = false, bool SP2 = false>
; __device__ __forceinline__ void gemm_phase(PG8_LAS unsigned char* lds, const Gemm g, const Sched& S, const Epi& E) {
;     ...
;             PG8_WAIT_V(8); PG8_WAIT_L(0); PG8_BAR; PG8_MMA(1, 0, At, B0); PG8_MMA(1, 1, At, B1); PG8_BAR; PG8_SCHED;
;             PG8_LDB(B0, 1, 0); PG8_LDB(B1, 1, 1); PG8_SCHED; PG8_LDA(At, 1, 0); PG8_STAGE(PG8_SA(0, 1), a2 + hstep, voffA);
;             PG8_WAIT_V(8); PG8_WAIT_L(0); PG8_BAR; PG8_MMA(0, 0, At, B0); PG8_MMA(0, 1, At, B1); PG8_BAR; PG8_SCHED;
	s_setprio 1
	s_waitcnt lgkmcnt(0)
	v_mfma_f32_16x16x32_bf16 v[16:19], v[154:157], v[188:191], v[16:19]
	v_mfma_f32_16x16x32_bf16 v[16:19], v[158:161], v[192:195], v[16:19]
	v_mfma_f32_16x16x32_bf16 v[20:23], v[162:165], v[188:191], v[20:23]
	v_mfma_f32_16x16x32_bf16 v[20:23], v[166:169], v[192:195], v[20:23]
	v_mfma_f32_16x16x32_bf16 v[56:59], v[154:157], v[196:199], v[56:59]
	v_mfma_f32_16x16x32_bf16 v[56:59], v[158:161], v[200:203], v[56:59]
	v_mfma_f32_16x16x32_bf16 v[60:63], v[162:165], v[196:199], v[60:63]
	v_mfma_f32_16x16x32_bf16 v[60:63], v[166:169], v[200:203], v[60:63]
	v_mfma_f32_16x16x32_bf16 v[104:107], v[154:157], v[204:207], v[104:107]
	v_mfma_f32_16x16x32_bf16 v[104:107], v[158:161], v[230:233], v[104:107]
	v_mfma_f32_16x16x32_bf16 v[108:111], v[162:165], v[204:207], v[108:111]
	v_mfma_f32_16x16x32_bf16 v[108:111], v[166:169], v[230:233], v[108:111]
	v_mfma_f32_16x16x32_bf16 v[68:71], v[154:157], v[234:237], v[68:71]
	v_mfma_f32_16x16x32_bf16 v[68:71], v[158:161], v[238:241], v[68:71]
	v_mfma_f32_16x16x32_bf16 v[64:67], v[162:165], v[234:237], v[64:67]
	v_mfma_f32_16x16x32_bf16 v[64:67], v[166:169], v[238:241], v[64:67]
	s_setprio 0
	s_setprio 1
	v_mfma_f32_16x16x32_bf16 v[40:43], v[170:173], v[188:191], v[40:43]
	v_mfma_f32_16x16x32_bf16 v[40:43], v[174:177], v[192:195], v[40:43]
	v_mfma_f32_16x16x32_bf16 v[44:47], v[178:181], v[188:191], v[44:47]
	v_mfma_f32_16x16x32_bf16 v[44:47], v[184:187], v[192:195], v[44:47]
	v_mfma_f32_16x16x32_bf16 v[88:91], v[170:173], v[196:199], v[88:91]
	v_mfma_f32_16x16x32_bf16 v[88:91], v[174:177], v[200:203], v[88:91]
	v_mfma_f32_16x16x32_bf16 v[92:95], v[178:181], v[196:199], v[92:95]
	v_mfma_f32_16x16x32_bf16 v[92:95], v[184:187], v[200:203], v[92:95]
	v_mfma_f32_16x16x32_bf16 v[84:87], v[170:173], v[204:207], v[84:87]
	v_mfma_f32_16x16x32_bf16 v[84:87], v[174:177], v[230:233], v[84:87]
	v_mfma_f32_16x16x32_bf16 v[80:83], v[178:181], v[204:207], v[80:83]
	v_mfma_f32_16x16x32_bf16 v[80:83], v[184:187], v[230:233], v[80:83]
	v_mfma_f32_16x16x32_bf16 v[36:39], v[170:173], v[234:237], v[36:39]
	v_mfma_f32_16x16x32_bf16 v[36:39], v[174:177], v[238:241], v[36:39]
	v_mfma_f32_16x16x32_bf16 v[32:35], v[178:181], v[234:237], v[32:35]
	v_mfma_f32_16x16x32_bf16 v[32:35], v[184:187], v[238:241], v[32:35]
	s_setprio 0
	s_barrier
	v_add_u32_e32 v0, s91, v151
	s_add_i32 s82, 0, 0x1c000
	ds_read_b128 v[154:157], v0
	ds_read_b128 v[158:161], v0 offset:1024
	ds_read_b128 v[162:165], v0 offset:2048
	ds_read_b128 v[166:169], v0 offset:3072
	v_add_u32_e32 v0, s82, v151
	ds_read_b128 v[170:173], v0
	ds_read_b128 v[174:177], v0 offset:1024
	ds_read_b128 v[178:181], v0 offset:2048
	ds_read_b128 v[184:187], v0 offset:3072
	s_add_u32 s40, s40, s48
	s_addc_u32 s41, s41, s49
	s_mov_b32 m0, s52
	v_lshl_add_u64 v[242:243], s[40:41], 0, v[142:143]
	ds_read_b128 v[188:191], v152 offset:32768
	ds_read_b128 v[192:195], v152 offset:33792
	ds_read_b128 v[196:199], v152 offset:34816
	ds_read_b128 v[200:203], v152 offset:35840
	ds_read_b128 v[204:207], v152 offset:36864
	ds_read_b128 v[230:233], v152 offset:37888
	ds_read_b128 v[234:237], v152 offset:38912
	ds_read_b128 v[238:241], v152 offset:39936
	global_load_lds_dwordx4 v[242:243], off
	v_lshl_add_u64 v[242:243], s[40:41], 0, v[138:139]
	s_mov_b32 m0, s53
	s_nop 0
	global_load_lds_dwordx4 v[242:243], off
	s_waitcnt vmcnt(8)
	s_waitcnt lgkmcnt(0)
	s_barrier
	s_setprio 1
	s_waitcnt lgkmcnt(0)
	v_mfma_f32_16x16x32_bf16 v[8:11], v[154:157], v[188:191], v[8:11]
	v_mfma_f32_16x16x32_bf16 v[8:11], v[158:161], v[192:195], v[8:11]
	v_mfma_f32_16x16x32_bf16 v[12:15], v[162:165], v[188:191], v[12:15]
	v_mfma_f32_16x16x32_bf16 v[12:15], v[166:169], v[192:195], v[12:15]
	v_mfma_f32_16x16x32_bf16 v[48:51], v[154:157], v[196:199], v[48:51]
	v_mfma_f32_16x16x32_bf16 v[48:51], v[158:161], v[200:203], v[48:51]
	v_mfma_f32_16x16x32_bf16 v[52:55], v[162:165], v[196:199], v[52:55]
	v_mfma_f32_16x16x32_bf16 v[52:55], v[166:169], v[200:203], v[52:55]
	v_mfma_f32_16x16x32_bf16 v[96:99], v[154:157], v[204:207], v[96:99]
	v_mfma_f32_16x16x32_bf16 v[96:99], v[158:161], v[230:233], v[96:99]
	v_mfma_f32_16x16x32_bf16 v[100:103], v[162:165], v[204:207], v[100:103]
	v_mfma_f32_16x16x32_bf16 v[100:103], v[166:169], v[230:233], v[100:103]
	v_mfma_f32_16x16x32_bf16 v[120:123], v[154:157], v[234:237], v[120:123]
	v_mfma_f32_16x16x32_bf16 v[120:123], v[158:161], v[238:241], v[120:123]
	v_mfma_f32_16x16x32_bf16 v[124:127], v[162:165], v[234:237], v[124:127]
	v_mfma_f32_16x16x32_bf16 v[124:127], v[166:169], v[238:241], v[124:127]
	s_setprio 0
	s_setprio 1
	v_mfma_f32_16x16x32_bf16 v[24:27], v[170:173], v[188:191], v[24:27]
	v_mfma_f32_16x16x32_bf16 v[24:27], v[174:177], v[192:195], v[24:27]
	v_mfma_f32_16x16x32_bf16 v[28:31], v[178:181], v[188:191], v[28:31]
	v_mfma_f32_16x16x32_bf16 v[28:31], v[184:187], v[192:195], v[28:31]
	v_mfma_f32_16x16x32_bf16 v[72:75], v[170:173], v[196:199], v[72:75]
	v_mfma_f32_16x16x32_bf16 v[72:75], v[174:177], v[200:203], v[72:75]
	v_mfma_f32_16x16x32_bf16 v[76:79], v[178:181], v[196:199], v[76:79]
	v_mfma_f32_16x16x32_bf16 v[76:79], v[184:187], v[200:203], v[76:79]
	v_mfma_f32_16x16x32_bf16 v[112:115], v[170:173], v[204:207], v[112:115]
	v_mfma_f32_16x16x32_bf16 v[112:115], v[174:177], v[230:233], v[112:115]
	v_mfma_f32_16x16x32_bf16 v[116:119], v[178:181], v[204:207], v[116:119]
	v_mfma_f32_16x16x32_bf16 v[116:119], v[184:187], v[230:233], v[116:119]
	v_mfma_f32_16x16x32_bf16 v[128:131], v[170:173], v[234:237], v[128:131]
	v_mfma_f32_16x16x32_bf16 v[128:131], v[174:177], v[238:241], v[128:131]
	v_mfma_f32_16x16x32_bf16 v[132:135], v[178:181], v[234:237], v[132:135]
	v_mfma_f32_16x16x32_bf16 v[132:135], v[184:187], v[238:241], v[132:135]
	s_setprio 0
	s_barrier
; #define PG8_STAGE(bufoff, gbase, voff) do { _Pragma("unroll") for (int _i = 0; _i < 2; ++_i) \
;         __builtin_amdgcn_global_load_lds((const unsigned*)((const char*)(gbase) + (voff)[_i]), (PG8_LAS unsigned*)(lds + (bufoff) + ldsw + _i * 8192), 16, 0, 0); } while (0)
; #define PG8_LDA(dst, b, h) do { _Pragma("unroll") for (int m = 0; m < 4; ++m) _Pragma("unroll") for (int k = 0; k < 2; ++k) dst[m][k] = *(const PG8_LAS bf16x8*)(lds + PG8_SA(b, h) + aoff + m * 2048 + k * 1024); } while (0)
; #define PG8_MMA(ai, bj, At, Bt) do { __builtin_amdgcn_s_setprio(1); _Pragma("unroll") for (int m = 0; m < 4; ++m) _Pragma("unroll") for (int n = 0; n < 2; ++n) _Pragma("unroll") for (int k = 0; k < 2; ++k) \
;         acc[ai][bj][m][n] = __builtin_amdgcn_mfma_f32_16x16x32_bf16(Bt[n][k], At[m][k], acc[ai][bj][m][n], 0, 0, 0); __builtin_amdgcn_s_setprio(0); } while (0)
; #define PG8_WAIT_V(n) asm volatile("s_waitcnt vmcnt(" #n ")" ::: "memory")
; #define PG8_WAIT_L(n) asm volatile("s_waitcnt lgkmcnt(" #n ")" ::: "memory")
; #define PG8_BAR __builtin_amdgcn_s_barrier()
; #define PG8_SCHED __builtin_amdgcn_sched_barrier(0)
; template <class Epi, class Sched, bool ALIGN_EPI = false, bool SP2 = false>
; __device__ __forceinline__ void gemm_phase(PG8_LAS unsigned char* lds, const Gemm g, const Sched& S, const Epi& E) {
;     ...
;         for (int t = 0; t < nt; t += 2) {
;     ...
;             PG8_LDA(At, 1, 1); PG8_STAGE(PG8_SB(1, 0), b3, voffB); PG8_STAGE(PG8_SB(1, 1), b3 + hstep, voffB); PG8_STAGE(PG8_SA(1, 0), a3, voffA);
;             PG8_WAIT_V(8); PG8_WAIT_L(0); PG8_BAR; PG8_MMA(1, 0, At, B0); PG8_MMA(1, 1, At, B1); PG8_BAR; PG8_SCHED;
	s_add_i32 s40, s91, s37
	v_lshl_add_u64 v[2:3], v[2:3], 0, s[24:25]
	s_mov_b32 m0, s40
	ds_read_b128 v[188:191], v152 offset:49152
	ds_read_b128 v[192:195], v152 offset:50176
	ds_read_b128 v[196:199], v152 offset:51200
	ds_read_b128 v[200:203], v152 offset:52224
	ds_read_b128 v[204:207], v152 offset:53248
	ds_read_b128 v[230:233], v152 offset:54272
	ds_read_b128 v[234:237], v152 offset:55296
	ds_read_b128 v[238:241], v152 offset:56320
	global_load_lds_dwordx4 v[2:3], off
	v_lshl_add_u64 v[2:3], v[208:209], 0, s[24:25]
	s_add_i32 m0, s40, 0x2000
	s_add_i32 s40, s82, s37
	global_load_lds_dwordx4 v[2:3], off
	v_lshl_add_u64 v[2:3], v[216:217], 0, s[24:25]
	s_mov_b32 m0, s40
	s_nop 0
	global_load_lds_dwordx4 v[2:3], off
	v_lshl_add_u64 v[2:3], v[224:225], 0, s[24:25]
	s_add_i32 m0, s40, 0x2000
	s_nop 0
	global_load_lds_dwordx4 v[2:3], off
	v_lshl_add_u64 v[2:3], v[226:227], 0, s[24:25]
	s_mov_b32 m0, s73
	s_nop 0
	global_load_lds_dwordx4 v[2:3], off
	v_lshl_add_u64 v[2:3], v[228:229], 0, s[24:25]
	s_mov_b32 m0, s74
	s_nop 0
	global_load_lds_dwordx4 v[2:3], off
	s_waitcnt vmcnt(8)
	s_waitcnt lgkmcnt(0)
	s_barrier
	s_setprio 1
	s_waitcnt lgkmcnt(0)
	v_mfma_f32_16x16x32_bf16 v[16:19], v[154:157], v[188:191], v[16:19]
	v_mfma_f32_16x16x32_bf16 v[16:19], v[158:161], v[192:195], v[16:19]
	v_mfma_f32_16x16x32_bf16 v[20:23], v[162:165], v[188:191], v[20:23]
	v_mfma_f32_16x16x32_bf16 v[20:23], v[166:169], v[192:195], v[20:23]
	v_mfma_f32_16x16x32_bf16 v[56:59], v[154:157], v[196:199], v[56:59]
	v_mfma_f32_16x16x32_bf16 v[56:59], v[158:161], v[200:203], v[56:59]
	v_mfma_f32_16x16x32_bf16 v[60:63], v[162:165], v[196:199], v[60:63]
	v_mfma_f32_16x16x32_bf16 v[60:63], v[166:169], v[200:203], v[60:63]
	v_mfma_f32_16x16x32_bf16 v[104:107], v[154:157], v[204:207], v[104:107]
	v_mfma_f32_16x16x32_bf16 v[104:107], v[158:161], v[230:233], v[104:107]
	v_mfma_f32_16x16x32_bf16 v[108:111], v[162:165], v[204:207], v[108:111]
	v_mfma_f32_16x16x32_bf16 v[108:111], v[166:169], v[230:233], v[108:111]
	v_mfma_f32_16x16x32_bf16 v[68:71], v[154:157], v[234:237], v[68:71]
	v_mfma_f32_16x16x32_bf16 v[68:71], v[158:161], v[238:241], v[68:71]
	v_mfma_f32_16x16x32_bf16 v[64:67], v[162:165], v[234:237], v[64:67]
	v_mfma_f32_16x16x32_bf16 v[64:67], v[166:169], v[238:241], v[64:67]
	s_setprio 0
	s_setprio 1
	v_mfma_f32_16x16x32_bf16 v[40:43], v[170:173], v[188:191], v[40:43]
	v_mfma_f32_16x16x32_bf16 v[40:43], v[174:177], v[192:195], v[40:43]
	v_mfma_f32_16x16x32_bf16 v[44:47], v[178:181], v[188:191], v[44:47]
	v_mfma_f32_16x16x32_bf16 v[44:47], v[184:187], v[192:195], v[44:47]
	v_mfma_f32_16x16x32_bf16 v[88:91], v[170:173], v[196:199], v[88:91]
	v_mfma_f32_16x16x32_bf16 v[88:91], v[174:177], v[200:203], v[88:91]
	v_mfma_f32_16x16x32_bf16 v[92:95], v[178:181], v[196:199], v[92:95]
	v_mfma_f32_16x16x32_bf16 v[92:95], v[184:187], v[200:203], v[92:95]
	v_mfma_f32_16x16x32_bf16 v[84:87], v[170:173], v[204:207], v[84:87]
	v_mfma_f32_16x16x32_bf16 v[84:87], v[174:177], v[230:233], v[84:87]
	v_mfma_f32_16x16x32_bf16 v[80:83], v[178:181], v[204:207], v[80:83]
	v_mfma_f32_16x16x32_bf16 v[80:83], v[184:187], v[230:233], v[80:83]
	v_mfma_f32_16x16x32_bf16 v[36:39], v[170:173], v[234:237], v[36:39]
	v_mfma_f32_16x16x32_bf16 v[36:39], v[174:177], v[238:241], v[36:39]
	v_mfma_f32_16x16x32_bf16 v[32:35], v[178:181], v[234:237], v[32:35]
	v_mfma_f32_16x16x32_bf16 v[32:35], v[184:187], v[238:241], v[32:35]
	s_setprio 0
	s_barrier
	s_add_u32 s38, s38, 0x100
	s_addc_u32 s39, s39, 0
	s_add_u32 s79, s79, 0x100
	s_addc_u32 s80, s80, 0
	s_cmp_ge_u32 s81, s9
	s_mov_b32 s40, s81
	s_cbranch_scc0 .LBB0_294

; #define PG8_STAGE(bufoff, gbase, voff) do { _Pragma("unroll") for (int _i = 0; _i < 2; ++_i) \
;         __builtin_amdgcn_global_load_lds((const unsigned*)((const char*)(gbase) + (voff)[_i]), (PG8_LAS unsigned*)(lds + (bufoff) + ldsw + _i * 8192), 16, 0, 0); } while (0)
; #define PG8_LDA(dst, b, h) do { _Pragma("unroll") for (int m = 0; m < 4; ++m) _Pragma("unroll") for (int k = 0; k < 2; ++k) dst[m][k] = *(const PG8_LAS bf16x8*)(lds + PG8_SA(b, h) + aoff + m * 2048 + k * 1024); } while (0)
; #define PG8_LDB(dst, b, h) do { _Pragma("unroll") for (int n = 0; n < 2; ++n) _Pragma("unroll") for (int k = 0; k < 2; ++k) dst[n][k] = *(const PG8_LAS bf16x8*)(lds + PG8_SB(b, h) + boff + n * 2048 + k * 1024); } while (0)
; #define PG8_MMA(ai, bj, At, Bt) do { __builtin_amdgcn_s_setprio(1); _Pragma("unroll") for (int m = 0; m < 4; ++m) _Pragma("unroll") for (int n = 0; n < 2; ++n) _Pragma("unroll") for (int k = 0; k < 2; ++k) \
;         acc[ai][bj][m][n] = __builtin_amdgcn_mfma_f32_16x16x32_bf16(Bt[n][k], At[m][k], acc[ai][bj][m][n], 0, 0, 0); __builtin_amdgcn_s_setprio(0); } while (0)
; #define PG8_WAIT_V(n) asm volatile("s_waitcnt vmcnt(" #n ")" ::: "memory")
; #define PG8_WAIT_L(n) asm volatile("s_waitcnt lgkmcnt(" #n ")" ::: "memory")
; template <class Epi, class Sched, bool ALIGN_EPI = false, bool SP2 = false>
; __device__ __forceinline__ void gemm_phase(PG8_LAS unsigned char* lds, const Gemm g, const Sched& S, const Epi& E) {
;     ...
;             const bool last = (t == nt - 2);
;             const char* a1 = cA + (size_t)(t + 1) * kstep;
;             const char* a2 = last ? nA : cA + (size_t)(t + 2) * kstep; const char* b2 = last ? nB : cB + (size_t)(t + 2) * kstep;
;             const char* a3 = a2 + kstep; const char* b3 = b2 + kstep;
;             if (last && has_next) S.a_ready(nxt);
;             if constexpr (SP2) {
;             PG8_LDB(B0, 0, 0); PG8_LDB(B1, 0, 1); PG8_SCHED; PG8_LDA(At, 0, 0); PG8_STAGE(PG8_SA(1, 1), a1 + hstep, voffA);
;             PG8_WAIT_V(8); PG8_WAIT_L(0); PG8_BAR; PG8_MMA(0, 0, At, B0); PG8_MMA(0, 1, At, B1); PG8_BAR; PG8_SCHED;
;             PG8_LDA(At, 0, 1); PG8_STAGE(PG8_SB(0, 0), b2, voffB); PG8_STAGE(PG8_SB(0, 1), b2 + hstep, voffB); PG8_STAGE(PG8_SA(0, 0), a2, voffA);
;             PG8_WAIT_V(8); PG8_WAIT_L(0); PG8_BAR; PG8_MMA(1, 0, At, B0); PG8_MMA(1, 1, At, B1); PG8_BAR; PG8_SCHED;
.LBB0_365:
	s_add_i32 s88, s86, 2
	s_add_u32 s89, s0, 0x80
	s_addc_u32 s87, s1, 0
	s_cmp_eq_u32 s33, s86
	s_cselect_b32 s87, s3, s87
	s_cselect_b32 s86, s2, s89
	v_add_u32_e32 v0, s19, v230
	s_cselect_b32 vcc_hi, s85, s73
	s_cselect_b32 vcc_lo, s84, s72
	s_add_i32 s89, 0, 0x14000
	ds_read_b128 v[120:123], v0
	ds_read_b128 v[124:127], v0 offset:1024
	ds_read_b128 v[128:131], v0 offset:2048
	ds_read_b128 v[132:135], v0 offset:3072
	v_add_u32_e32 v0, s89, v230
	ds_read_b128 v[136:139], v0
	ds_read_b128 v[140:143], v0 offset:1024
	ds_read_b128 v[162:165], v0 offset:2048
	ds_read_b128 v[166:169], v0 offset:3072
	v_lshl_add_u64 v[144:145], s[0:1], 0, v[184:185]
	s_add_i32 m0, s93, 0xc000
	ds_read_b128 v[170:173], v238
	ds_read_b128 v[188:191], v238 offset:1024
	ds_read_b128 v[192:195], v238 offset:2048
	ds_read_b128 v[196:199], v238 offset:3072
	ds_read_b128 v[200:203], v238 offset:4096
	ds_read_b128 v[204:207], v238 offset:5120
	ds_read_b128 v[242:245], v238 offset:6144
	ds_read_b128 v[246:249], v238 offset:7168
	global_load_lds_dwordx4 v[144:145], off
	v_lshl_add_u64 v[144:145], s[0:1], 0, v[186:187]
	s_add_i32 m0, s93, 0xe000
	s_nop 0
	global_load_lds_dwordx4 v[144:145], off
	s_waitcnt vmcnt(8)
	s_waitcnt lgkmcnt(0)
	s_barrier
	s_setprio 1
	s_waitcnt lgkmcnt(0)
	v_mfma_f32_16x16x32_bf16 v[158:161], v[120:123], v[170:173], v[158:161]
	v_mfma_f32_16x16x32_bf16 v[158:161], v[124:127], v[188:191], v[158:161]
	v_mfma_f32_16x16x32_bf16 v[60:63], v[128:131], v[170:173], v[60:63]
	v_mfma_f32_16x16x32_bf16 v[60:63], v[132:135], v[188:191], v[60:63]
	v_mfma_f32_16x16x32_bf16 v[150:153], v[120:123], v[192:195], v[150:153]
	v_mfma_f32_16x16x32_bf16 v[150:153], v[124:127], v[196:199], v[150:153]
	v_mfma_f32_16x16x32_bf16 v[52:55], v[128:131], v[192:195], v[52:55]
	v_mfma_f32_16x16x32_bf16 v[52:55], v[132:135], v[196:199], v[52:55]
	v_mfma_f32_16x16x32_bf16 v[100:103], v[120:123], v[200:203], v[100:103]
	v_mfma_f32_16x16x32_bf16 v[100:103], v[124:127], v[204:207], v[100:103]
	v_mfma_f32_16x16x32_bf16 v[36:39], v[128:131], v[200:203], v[36:39]
	v_mfma_f32_16x16x32_bf16 v[36:39], v[132:135], v[204:207], v[36:39]
	v_mfma_f32_16x16x32_bf16 v[116:119], v[120:123], v[242:245], v[116:119]
	v_mfma_f32_16x16x32_bf16 v[116:119], v[124:127], v[246:249], v[116:119]
	v_mfma_f32_16x16x32_bf16 v[68:71], v[128:131], v[242:245], v[68:71]
	v_mfma_f32_16x16x32_bf16 v[68:71], v[132:135], v[246:249], v[68:71]
	s_setprio 0
	s_setprio 1
	v_mfma_f32_16x16x32_bf16 v[154:157], v[136:139], v[170:173], v[154:157]
	v_mfma_f32_16x16x32_bf16 v[154:157], v[140:143], v[188:191], v[154:157]
	v_mfma_f32_16x16x32_bf16 v[56:59], v[162:165], v[170:173], v[56:59]
	v_mfma_f32_16x16x32_bf16 v[56:59], v[166:169], v[188:191], v[56:59]
	v_mfma_f32_16x16x32_bf16 v[144:147], v[136:139], v[192:195], v[146:149]
	v_mfma_f32_16x16x32_bf16 v[144:147], v[140:143], v[196:199], v[144:147]
	v_mfma_f32_16x16x32_bf16 v[48:51], v[162:165], v[192:195], v[48:51]
	v_mfma_f32_16x16x32_bf16 v[48:51], v[166:169], v[196:199], v[48:51]
	v_mfma_f32_16x16x32_bf16 v[96:99], v[136:139], v[200:203], v[96:99]
	v_mfma_f32_16x16x32_bf16 v[96:99], v[140:143], v[204:207], v[96:99]
	v_mfma_f32_16x16x32_bf16 v[32:35], v[162:165], v[200:203], v[32:35]
	v_mfma_f32_16x16x32_bf16 v[32:35], v[166:169], v[204:207], v[32:35]
	v_mfma_f32_16x16x32_bf16 v[112:115], v[136:139], v[242:245], v[112:115]
	v_mfma_f32_16x16x32_bf16 v[112:115], v[140:143], v[246:249], v[112:115]
	v_mfma_f32_16x16x32_bf16 v[64:67], v[162:165], v[242:245], v[64:67]
	v_mfma_f32_16x16x32_bf16 v[64:67], v[166:169], v[246:249], v[64:67]
	s_setprio 0
	s_barrier
	s_add_i32 s38, s19, s92
	v_lshl_add_u64 v[174:175], vcc, 0, v[176:177]
	s_mov_b32 m0, s38
	ds_read_b128 v[170:173], v238 offset:16384
	ds_read_b128 v[188:191], v238 offset:17408
	ds_read_b128 v[192:195], v238 offset:18432
	ds_read_b128 v[196:199], v238 offset:19456
	ds_read_b128 v[200:203], v238 offset:20480
	ds_read_b128 v[204:207], v238 offset:21504
	ds_read_b128 v[242:245], v238 offset:22528
	ds_read_b128 v[246:249], v238 offset:23552
	global_load_lds_dwordx4 v[174:175], off
	s_add_i32 m0, s38, 0x2000
	v_lshl_add_u64 v[208:209], vcc, 0, v[180:181]
	s_add_u32 vcc_lo, vcc_lo, s48
	s_addc_u32 vcc_hi, vcc_hi, s49
	s_add_i32 s38, s89, s92
	global_load_lds_dwordx4 v[208:209], off
	v_lshl_add_u64 v[216:217], vcc, 0, v[176:177]
	s_mov_b32 m0, s38
	v_lshl_add_u64 v[224:225], vcc, 0, v[180:181]
	global_load_lds_dwordx4 v[216:217], off
	s_add_i32 m0, s38, 0x2000
	v_lshl_add_u64 v[226:227], s[86:87], 0, v[2:3]
	global_load_lds_dwordx4 v[224:225], off
	s_mov_b32 m0, s93
	v_lshl_add_u64 v[228:229], s[86:87], 0, v[178:179]
	global_load_lds_dwordx4 v[226:227], off
	s_mov_b32 m0, s94
	s_nop 0
	global_load_lds_dwordx4 v[228:229], off
	s_waitcnt vmcnt(8)
	s_waitcnt lgkmcnt(0)
	s_barrier
; #define PG8_STAGE(bufoff, gbase, voff) do { _Pragma("unroll") for (int _i = 0; _i < 2; ++_i) \
;         __builtin_amdgcn_global_load_lds((const unsigned*)((const char*)(gbase) + (voff)[_i]), (PG8_LAS unsigned*)(lds + (bufoff) + ldsw + _i * 8192), 16, 0, 0); } while (0)
; #define PG8_LDA(dst, b, h) do { _Pragma("unroll") for (int m = 0; m < 4; ++m) _Pragma("unroll") for (int k = 0; k < 2; ++k) dst[m][k] = *(const PG8_LAS bf16x8*)(lds + PG8_SA(b, h) + aoff + m * 2048 + k * 1024); } while (0)
; #define PG8_LDB(dst, b, h) do { _Pragma("unroll") for (int n = 0; n < 2; ++n) _Pragma("unroll") for (int k = 0; k < 2; ++k) dst[n][k] = *(const PG8_LAS bf16x8*)(lds + PG8_SB(b, h) + boff + n * 2048 + k * 1024); } while (0)
; #define PG8_MMA(ai, bj, At, Bt) do { __builtin_amdgcn_s_setprio(1); _Pragma("unroll") for (int m = 0; m < 4; ++m) _Pragma("unroll") for (int n = 0; n < 2; ++n) _Pragma("unroll") for (int k = 0; k < 2; ++k) \
;         acc[ai][bj][m][n] = __builtin_amdgcn_mfma_f32_16x16x32_bf16(Bt[n][k], At[m][k], acc[ai][bj][m][n], 0, 0, 0); __builtin_amdgcn_s_setprio(0); } while (0)
; #define PG8_WAIT_V(n) asm volatile("s_waitcnt vmcnt(" #n ")" ::: "memory")
; #define PG8_WAIT_L(n) asm volatile("s_waitcnt lgkmcnt(" #n ")" ::: "memory")
; #define PG8_BAR __builtin_amdgcn_s_barrier()
; #define PG8_SCHED __builtin_amdgcn_sched_barrier(0)
; template <class Epi, class Sched, bool ALIGN_EPI = false, bool SP2 = false>
; __device__ __forceinline__ void gemm_phase(PG8_LAS unsigned char* lds, const Gemm g, const Sched& S, const Epi& E) {
;     ...
;             PG8_WAIT_V(8); PG8_WAIT_L(0); PG8_BAR; PG8_MMA(1, 0, At, B0); PG8_MMA(1, 1, At, B1); PG8_BAR; PG8_SCHED;
;             PG8_LDB(B0, 1, 0); PG8_LDB(B1, 1, 1); PG8_SCHED; PG8_LDA(At, 1, 0); PG8_STAGE(PG8_SA(0, 1), a2 + hstep, voffA);
;             PG8_WAIT_V(8); PG8_WAIT_L(0); PG8_BAR; PG8_MMA(0, 0, At, B0); PG8_MMA(0, 1, At, B1); PG8_BAR; PG8_SCHED;
	s_setprio 1
	s_waitcnt lgkmcnt(0)
	v_mfma_f32_16x16x32_bf16 v[92:95], v[120:123], v[170:173], v[92:95]
	v_mfma_f32_16x16x32_bf16 v[92:95], v[124:127], v[188:191], v[92:95]
	v_mfma_f32_16x16x32_bf16 v[28:31], v[128:131], v[170:173], v[28:31]
	v_mfma_f32_16x16x32_bf16 v[28:31], v[132:135], v[188:191], v[28:31]
	v_mfma_f32_16x16x32_bf16 v[84:87], v[120:123], v[192:195], v[84:87]
	v_mfma_f32_16x16x32_bf16 v[84:87], v[124:127], v[196:199], v[84:87]
	v_mfma_f32_16x16x32_bf16 v[20:23], v[128:131], v[192:195], v[20:23]
	v_mfma_f32_16x16x32_bf16 v[20:23], v[132:135], v[196:199], v[20:23]
	v_mfma_f32_16x16x32_bf16 v[76:79], v[120:123], v[200:203], v[76:79]
	v_mfma_f32_16x16x32_bf16 v[76:79], v[124:127], v[204:207], v[76:79]
	v_mfma_f32_16x16x32_bf16 v[12:15], v[128:131], v[200:203], v[12:15]
	v_mfma_f32_16x16x32_bf16 v[12:15], v[132:135], v[204:207], v[12:15]
	v_mfma_f32_16x16x32_bf16 v[108:111], v[120:123], v[242:245], v[108:111]
	v_mfma_f32_16x16x32_bf16 v[108:111], v[124:127], v[246:249], v[108:111]
	v_mfma_f32_16x16x32_bf16 v[44:47], v[128:131], v[242:245], v[44:47]
	v_mfma_f32_16x16x32_bf16 v[44:47], v[132:135], v[246:249], v[44:47]
	s_setprio 0
	s_setprio 1
	v_mfma_f32_16x16x32_bf16 v[88:91], v[136:139], v[170:173], v[88:91]
	v_mfma_f32_16x16x32_bf16 v[88:91], v[140:143], v[188:191], v[88:91]
	v_mfma_f32_16x16x32_bf16 v[24:27], v[162:165], v[170:173], v[24:27]
	v_mfma_f32_16x16x32_bf16 v[24:27], v[166:169], v[188:191], v[24:27]
	v_mfma_f32_16x16x32_bf16 v[80:83], v[136:139], v[192:195], v[80:83]
	v_mfma_f32_16x16x32_bf16 v[80:83], v[140:143], v[196:199], v[80:83]
	v_mfma_f32_16x16x32_bf16 v[16:19], v[162:165], v[192:195], v[16:19]
	v_mfma_f32_16x16x32_bf16 v[16:19], v[166:169], v[196:199], v[16:19]
	v_mfma_f32_16x16x32_bf16 v[72:75], v[136:139], v[200:203], v[72:75]
	v_mfma_f32_16x16x32_bf16 v[72:75], v[140:143], v[204:207], v[72:75]
	v_mfma_f32_16x16x32_bf16 v[8:11], v[162:165], v[200:203], v[8:11]
	v_mfma_f32_16x16x32_bf16 v[8:11], v[166:169], v[204:207], v[8:11]
	v_mfma_f32_16x16x32_bf16 v[104:107], v[136:139], v[242:245], v[104:107]
	v_mfma_f32_16x16x32_bf16 v[104:107], v[140:143], v[246:249], v[104:107]
	v_mfma_f32_16x16x32_bf16 v[40:43], v[162:165], v[242:245], v[40:43]
	v_mfma_f32_16x16x32_bf16 v[40:43], v[166:169], v[246:249], v[40:43]
	s_setprio 0
	s_barrier
	v_add_u32_e32 v0, s91, v230
	s_add_i32 s38, 0, 0x1c000
	ds_read_b128 v[120:123], v0
	ds_read_b128 v[124:127], v0 offset:1024
	ds_read_b128 v[128:131], v0 offset:2048
	ds_read_b128 v[132:135], v0 offset:3072
	v_add_u32_e32 v0, s38, v230
	ds_read_b128 v[136:139], v0
	ds_read_b128 v[140:143], v0 offset:1024
	ds_read_b128 v[162:165], v0 offset:2048
	ds_read_b128 v[166:169], v0 offset:3072
	s_add_u32 s86, s86, s48
	s_addc_u32 s87, s87, s49
	s_mov_b32 m0, s95
	v_lshl_add_u64 v[148:149], s[86:87], 0, v[2:3]
	ds_read_b128 v[170:173], v238 offset:32768
	ds_read_b128 v[188:191], v238 offset:33792
	ds_read_b128 v[192:195], v238 offset:34816
	ds_read_b128 v[196:199], v238 offset:35840
	ds_read_b128 v[200:203], v238 offset:36864
	ds_read_b128 v[204:207], v238 offset:37888
	ds_read_b128 v[242:245], v238 offset:38912
	ds_read_b128 v[246:249], v238 offset:39936
	global_load_lds_dwordx4 v[148:149], off
	v_lshl_add_u64 v[148:149], s[86:87], 0, v[178:179]
	s_mov_b32 m0, s96
	s_nop 0
	global_load_lds_dwordx4 v[148:149], off
	s_waitcnt vmcnt(8)
	s_waitcnt lgkmcnt(0)
	s_barrier
	s_setprio 1
	s_waitcnt lgkmcnt(0)
	v_mfma_f32_16x16x32_bf16 v[158:161], v[120:123], v[170:173], v[158:161]
	v_mfma_f32_16x16x32_bf16 v[60:63], v[128:131], v[170:173], v[60:63]
	v_mfma_f32_16x16x32_bf16 v[148:151], v[120:123], v[192:195], v[150:153]
	v_mfma_f32_16x16x32_bf16 v[52:55], v[128:131], v[192:195], v[52:55]
	v_mfma_f32_16x16x32_bf16 v[100:103], v[120:123], v[200:203], v[100:103]
	v_mfma_f32_16x16x32_bf16 v[36:39], v[128:131], v[200:203], v[36:39]
	v_mfma_f32_16x16x32_bf16 v[116:119], v[120:123], v[242:245], v[116:119]
	v_mfma_f32_16x16x32_bf16 v[68:71], v[128:131], v[242:245], v[68:71]
	v_mfma_f32_16x16x32_bf16 v[158:161], v[124:127], v[188:191], v[158:161]
	v_mfma_f32_16x16x32_bf16 v[60:63], v[132:135], v[188:191], v[60:63]
	v_mfma_f32_16x16x32_bf16 v[150:153], v[124:127], v[196:199], v[148:151]
	v_mfma_f32_16x16x32_bf16 v[52:55], v[132:135], v[196:199], v[52:55]
	v_mfma_f32_16x16x32_bf16 v[100:103], v[124:127], v[204:207], v[100:103]
	v_mfma_f32_16x16x32_bf16 v[36:39], v[132:135], v[204:207], v[36:39]
	v_mfma_f32_16x16x32_bf16 v[116:119], v[124:127], v[246:249], v[116:119]
	v_mfma_f32_16x16x32_bf16 v[68:71], v[132:135], v[246:249], v[68:71]
	s_setprio 0
	s_setprio 1
	v_mfma_f32_16x16x32_bf16 v[154:157], v[136:139], v[170:173], v[154:157]
	v_mfma_f32_16x16x32_bf16 v[56:59], v[162:165], v[170:173], v[56:59]
	v_mfma_f32_16x16x32_bf16 v[144:147], v[136:139], v[192:195], v[144:147]
	v_mfma_f32_16x16x32_bf16 v[48:51], v[162:165], v[192:195], v[48:51]
	v_mfma_f32_16x16x32_bf16 v[96:99], v[136:139], v[200:203], v[96:99]
	v_mfma_f32_16x16x32_bf16 v[32:35], v[162:165], v[200:203], v[32:35]
	v_mfma_f32_16x16x32_bf16 v[112:115], v[136:139], v[242:245], v[112:115]
	v_mfma_f32_16x16x32_bf16 v[64:67], v[162:165], v[242:245], v[64:67]
	v_mfma_f32_16x16x32_bf16 v[154:157], v[140:143], v[188:191], v[154:157]
	v_mfma_f32_16x16x32_bf16 v[56:59], v[166:169], v[188:191], v[56:59]
	v_mfma_f32_16x16x32_bf16 v[146:149], v[140:143], v[196:199], v[144:147]
	v_mfma_f32_16x16x32_bf16 v[48:51], v[166:169], v[196:199], v[48:51]
	v_mfma_f32_16x16x32_bf16 v[96:99], v[140:143], v[204:207], v[96:99]
	v_mfma_f32_16x16x32_bf16 v[32:35], v[166:169], v[204:207], v[32:35]
	v_mfma_f32_16x16x32_bf16 v[112:115], v[140:143], v[246:249], v[112:115]
	v_mfma_f32_16x16x32_bf16 v[64:67], v[166:169], v[246:249], v[64:67]
	s_setprio 0
	s_barrier
; #define PG8_STAGE(bufoff, gbase, voff) do { _Pragma("unroll") for (int _i = 0; _i < 2; ++_i) \
;         __builtin_amdgcn_global_load_lds((const unsigned*)((const char*)(gbase) + (voff)[_i]), (PG8_LAS unsigned*)(lds + (bufoff) + ldsw + _i * 8192), 16, 0, 0); } while (0)
; #define PG8_LDA(dst, b, h) do { _Pragma("unroll") for (int m = 0; m < 4; ++m) _Pragma("unroll") for (int k = 0; k < 2; ++k) dst[m][k] = *(const PG8_LAS bf16x8*)(lds + PG8_SA(b, h) + aoff + m * 2048 + k * 1024); } while (0)
; #define PG8_MMA(ai, bj, At, Bt) do { __builtin_amdgcn_s_setprio(1); _Pragma("unroll") for (int m = 0; m < 4; ++m) _Pragma("unroll") for (int n = 0; n < 2; ++n) _Pragma("unroll") for (int k = 0; k < 2; ++k) \
;         acc[ai][bj][m][n] = __builtin_amdgcn_mfma_f32_16x16x32_bf16(Bt[n][k], At[m][k], acc[ai][bj][m][n], 0, 0, 0); __builtin_amdgcn_s_setprio(0); } while (0)
; #define PG8_WAIT_V(n) asm volatile("s_waitcnt vmcnt(" #n ")" ::: "memory")
; #define PG8_WAIT_L(n) asm volatile("s_waitcnt lgkmcnt(" #n ")" ::: "memory")
; #define PG8_BAR __builtin_amdgcn_s_barrier()
; #define PG8_SCHED __builtin_amdgcn_sched_barrier(0)
; template <class Epi, class Sched, bool ALIGN_EPI = false, bool SP2 = false>
; __device__ __forceinline__ void gemm_phase(PG8_LAS unsigned char* lds, const Gemm g, const Sched& S, const Epi& E) {
;     ...
;         for (int t = 0; t < nt; t += 2) {
;     ...
;             PG8_LDA(At, 1, 1); PG8_STAGE(PG8_SB(1, 0), b3, voffB); PG8_STAGE(PG8_SB(1, 1), b3 + hstep, voffB); PG8_STAGE(PG8_SA(1, 0), a3, voffA);
;             PG8_WAIT_V(8); PG8_WAIT_L(0); PG8_BAR; PG8_MMA(1, 0, At, B0); PG8_MMA(1, 1, At, B1); PG8_BAR; PG8_SCHED;
	s_add_i32 s39, s91, s92
	v_lshl_add_u64 v[144:145], v[174:175], 0, s[24:25]
	s_mov_b32 m0, s39
	ds_read_b128 v[170:173], v238 offset:49152
	ds_read_b128 v[188:191], v238 offset:50176
	ds_read_b128 v[192:195], v238 offset:51200
	ds_read_b128 v[196:199], v238 offset:52224
	ds_read_b128 v[200:203], v238 offset:53248
	ds_read_b128 v[204:207], v238 offset:54272
	ds_read_b128 v[242:245], v238 offset:55296
	ds_read_b128 v[246:249], v238 offset:56320
	global_load_lds_dwordx4 v[144:145], off
	v_lshl_add_u64 v[144:145], v[208:209], 0, s[24:25]
	s_add_i32 m0, s39, 0x2000
	s_add_i32 s38, s38, s92
	global_load_lds_dwordx4 v[144:145], off
	v_lshl_add_u64 v[144:145], v[216:217], 0, s[24:25]
	s_mov_b32 m0, s38
	s_nop 0
	global_load_lds_dwordx4 v[144:145], off
	v_lshl_add_u64 v[144:145], v[224:225], 0, s[24:25]
	s_add_i32 m0, s38, 0x2000
	s_nop 0
	global_load_lds_dwordx4 v[144:145], off
	v_lshl_add_u64 v[144:145], v[226:227], 0, s[24:25]
	s_mov_b32 m0, s10
	s_nop 0
	global_load_lds_dwordx4 v[144:145], off
	v_lshl_add_u64 v[144:145], v[228:229], 0, s[24:25]
	s_mov_b32 m0, s11
	s_nop 0
	global_load_lds_dwordx4 v[144:145], off
	s_waitcnt vmcnt(8)
	s_waitcnt lgkmcnt(0)
	s_barrier
	s_setprio 1
	s_waitcnt lgkmcnt(0)
	v_mfma_f32_16x16x32_bf16 v[92:95], v[120:123], v[170:173], v[92:95]
	v_mfma_f32_16x16x32_bf16 v[92:95], v[124:127], v[188:191], v[92:95]
	v_mfma_f32_16x16x32_bf16 v[28:31], v[128:131], v[170:173], v[28:31]
	v_mfma_f32_16x16x32_bf16 v[28:31], v[132:135], v[188:191], v[28:31]
	v_mfma_f32_16x16x32_bf16 v[84:87], v[120:123], v[192:195], v[84:87]
	v_mfma_f32_16x16x32_bf16 v[84:87], v[124:127], v[196:199], v[84:87]
	v_mfma_f32_16x16x32_bf16 v[20:23], v[128:131], v[192:195], v[20:23]
	v_mfma_f32_16x16x32_bf16 v[20:23], v[132:135], v[196:199], v[20:23]
	v_mfma_f32_16x16x32_bf16 v[76:79], v[120:123], v[200:203], v[76:79]
	v_mfma_f32_16x16x32_bf16 v[76:79], v[124:127], v[204:207], v[76:79]
	v_mfma_f32_16x16x32_bf16 v[12:15], v[128:131], v[200:203], v[12:15]
	v_mfma_f32_16x16x32_bf16 v[12:15], v[132:135], v[204:207], v[12:15]
	v_mfma_f32_16x16x32_bf16 v[108:111], v[120:123], v[242:245], v[108:111]
	v_mfma_f32_16x16x32_bf16 v[108:111], v[124:127], v[246:249], v[108:111]
	v_mfma_f32_16x16x32_bf16 v[44:47], v[128:131], v[242:245], v[44:47]
	v_mfma_f32_16x16x32_bf16 v[44:47], v[132:135], v[246:249], v[44:47]
	s_setprio 0
	s_setprio 1
	v_mfma_f32_16x16x32_bf16 v[88:91], v[136:139], v[170:173], v[88:91]
	v_mfma_f32_16x16x32_bf16 v[88:91], v[140:143], v[188:191], v[88:91]
	v_mfma_f32_16x16x32_bf16 v[24:27], v[162:165], v[170:173], v[24:27]
	v_mfma_f32_16x16x32_bf16 v[24:27], v[166:169], v[188:191], v[24:27]
	v_mfma_f32_16x16x32_bf16 v[80:83], v[136:139], v[192:195], v[80:83]
	v_mfma_f32_16x16x32_bf16 v[80:83], v[140:143], v[196:199], v[80:83]
	v_mfma_f32_16x16x32_bf16 v[16:19], v[162:165], v[192:195], v[16:19]
	v_mfma_f32_16x16x32_bf16 v[16:19], v[166:169], v[196:199], v[16:19]
	v_mfma_f32_16x16x32_bf16 v[72:75], v[136:139], v[200:203], v[72:75]
	v_mfma_f32_16x16x32_bf16 v[72:75], v[140:143], v[204:207], v[72:75]
	v_mfma_f32_16x16x32_bf16 v[8:11], v[162:165], v[200:203], v[8:11]
	v_mfma_f32_16x16x32_bf16 v[8:11], v[166:169], v[204:207], v[8:11]
	v_mfma_f32_16x16x32_bf16 v[104:107], v[136:139], v[242:245], v[104:107]
	v_mfma_f32_16x16x32_bf16 v[104:107], v[140:143], v[246:249], v[104:107]
	v_mfma_f32_16x16x32_bf16 v[40:43], v[162:165], v[242:245], v[40:43]
	v_mfma_f32_16x16x32_bf16 v[40:43], v[166:169], v[246:249], v[40:43]
	s_setprio 0
	s_barrier
	s_add_u32 s0, s0, 0x100
	s_addc_u32 s1, s1, 0
	s_add_u32 s72, s72, 0x100
	s_addc_u32 s73, s73, 0
	s_cmp_ge_u32 s88, s9
	s_mov_b32 s86, s88
	s_cbranch_scc0 .LBB0_365

; #define PG8_STAGE(bufoff, gbase, voff) do { _Pragma("unroll") for (int _i = 0; _i < 2; ++_i) \
;         __builtin_amdgcn_global_load_lds((const unsigned*)((const char*)(gbase) + (voff)[_i]), (PG8_LAS unsigned*)(lds + (bufoff) + ldsw + _i * 8192), 16, 0, 0); } while (0)
; #define PG8_LDA(dst, b, h) do { _Pragma("unroll") for (int m = 0; m < 4; ++m) _Pragma("unroll") for (int k = 0; k < 2; ++k) dst[m][k] = *(const PG8_LAS bf16x8*)(lds + PG8_SA(b, h) + aoff + m * 2048 + k * 1024); } while (0)
; #define PG8_LDB(dst, b, h) do { _Pragma("unroll") for (int n = 0; n < 2; ++n) _Pragma("unroll") for (int k = 0; k < 2; ++k) dst[n][k] = *(const PG8_LAS bf16x8*)(lds + PG8_SB(b, h) + boff + n * 2048 + k * 1024); } while (0)
; #define PG8_MMA(ai, bj, At, Bt) do { __builtin_amdgcn_s_setprio(1); _Pragma("unroll") for (int m = 0; m < 4; ++m) _Pragma("unroll") for (int n = 0; n < 2; ++n) _Pragma("unroll") for (int k = 0; k < 2; ++k) \
;         acc[ai][bj][m][n] = __builtin_amdgcn_mfma_f32_16x16x32_bf16(Bt[n][k], At[m][k], acc[ai][bj][m][n], 0, 0, 0); __builtin_amdgcn_s_setprio(0); } while (0)
; #define PG8_WAIT_V(n) asm volatile("s_waitcnt vmcnt(" #n ")" ::: "memory")
; #define PG8_WAIT_L(n) asm volatile("s_waitcnt lgkmcnt(" #n ")" ::: "memory")
; template <class Epi, class Sched, bool ALIGN_EPI = false, bool SP2 = false>
; __device__ __forceinline__ void gemm_phase(PG8_LAS unsigned char* lds, const Gemm g, const Sched& S, const Epi& E) {
;     ...
;             const bool last = (t == nt - 2);
;             const char* a1 = cA + (size_t)(t + 1) * kstep;
;             const char* a2 = last ? nA : cA + (size_t)(t + 2) * kstep; const char* b2 = last ? nB : cB + (size_t)(t + 2) * kstep;
;             const char* a3 = a2 + kstep; const char* b3 = b2 + kstep;
;             if (last && has_next) S.a_ready(nxt);
;             if constexpr (SP2) {
;             PG8_LDB(B0, 0, 0); PG8_LDB(B1, 0, 1); PG8_SCHED; PG8_LDA(At, 0, 0); PG8_STAGE(PG8_SA(1, 1), a1 + hstep, voffA);
;             PG8_WAIT_V(8); PG8_WAIT_L(0); PG8_BAR; PG8_MMA(0, 0, At, B0); PG8_MMA(0, 1, At, B1); PG8_BAR; PG8_SCHED;
;             PG8_LDA(At, 0, 1); PG8_STAGE(PG8_SB(0, 0), b2, voffB); PG8_STAGE(PG8_SB(0, 1), b2 + hstep, voffB); PG8_STAGE(PG8_SA(0, 0), a2, voffA);
;             PG8_WAIT_V(8); PG8_WAIT_L(0); PG8_BAR; PG8_MMA(1, 0, At, B0); PG8_MMA(1, 1, At, B1); PG8_BAR; PG8_SCHED;
.LBB0_468:
	s_add_i32 s78, s38, 2
	s_add_u32 s79, s0, 0x80
	s_addc_u32 s39, s1, 0
	s_cmp_eq_u32 s33, s38
	s_cselect_b32 s39, s7, s39
	s_cselect_b32 s38, s6, s79
	s_cselect_b32 s81, s23, s41
	s_cselect_b32 s80, s22, s40
	s_add_i32 s79, 0, 0x14000
	v_add_u32_e32 v148, s19, v162
	v_add_u32_e32 v171, s79, v162
	ds_read_b128 v[136:139], v148
	ds_read_b128 v[140:143], v148 offset:1024
	ds_read_b128 v[144:147], v148 offset:2048
	ds_read_b128 v[148:151], v148 offset:3072
	ds_read_b128 v[172:175], v171
	ds_read_b128 v[176:179], v171 offset:1024
	ds_read_b128 v[184:187], v171 offset:2048
	ds_read_b128 v[188:191], v171 offset:3072
	v_lshl_add_u64 v[180:181], s[0:1], 0, v[158:159]
	s_add_i32 m0, s46, 0xc000
	ds_read_b128 v[192:195], v167
	ds_read_b128 v[196:199], v167 offset:1024
	ds_read_b128 v[200:203], v167 offset:2048
	ds_read_b128 v[204:207], v167 offset:3072
	ds_read_b128 v[230:233], v167 offset:4096
	ds_read_b128 v[234:237], v167 offset:5120
	ds_read_b128 v[238:241], v167 offset:6144
	ds_read_b128 v[242:245], v167 offset:7168
	global_load_lds_dwordx4 v[180:181], off
	v_lshl_add_u64 v[180:181], s[0:1], 0, v[160:161]
	s_add_i32 m0, s46, 0xe000
	s_nop 0
	global_load_lds_dwordx4 v[180:181], off
	s_waitcnt vmcnt(8)
	s_waitcnt lgkmcnt(0)
	s_barrier
	s_setprio 1
	s_waitcnt lgkmcnt(0)
	v_mfma_f32_16x16x32_bf16 v[132:135], v[136:139], v[192:195], v[132:135]
	v_mfma_f32_16x16x32_bf16 v[132:135], v[140:143], v[196:199], v[132:135]
	v_mfma_f32_16x16x32_bf16 v[128:131], v[144:147], v[192:195], v[128:131]
	v_mfma_f32_16x16x32_bf16 v[128:131], v[148:151], v[196:199], v[128:131]
	v_mfma_f32_16x16x32_bf16 v[116:119], v[136:139], v[200:203], v[116:119]
	v_mfma_f32_16x16x32_bf16 v[116:119], v[140:143], v[204:207], v[116:119]
	v_mfma_f32_16x16x32_bf16 v[112:115], v[144:147], v[200:203], v[112:115]
	v_mfma_f32_16x16x32_bf16 v[112:115], v[148:151], v[204:207], v[112:115]
	v_mfma_f32_16x16x32_bf16 v[100:103], v[136:139], v[230:233], v[100:103]
	v_mfma_f32_16x16x32_bf16 v[100:103], v[140:143], v[234:237], v[100:103]
	v_mfma_f32_16x16x32_bf16 v[96:99], v[144:147], v[230:233], v[96:99]
	v_mfma_f32_16x16x32_bf16 v[96:99], v[148:151], v[234:237], v[96:99]
	v_mfma_f32_16x16x32_bf16 v[84:87], v[136:139], v[238:241], v[84:87]
	v_mfma_f32_16x16x32_bf16 v[84:87], v[140:143], v[242:245], v[84:87]
	v_mfma_f32_16x16x32_bf16 v[80:83], v[144:147], v[238:241], v[80:83]
	v_mfma_f32_16x16x32_bf16 v[80:83], v[148:151], v[242:245], v[80:83]
	s_setprio 0
	s_setprio 1
	v_mfma_f32_16x16x32_bf16 v[124:127], v[172:175], v[192:195], v[124:127]
	v_mfma_f32_16x16x32_bf16 v[124:127], v[176:179], v[196:199], v[124:127]
	v_mfma_f32_16x16x32_bf16 v[120:123], v[184:187], v[192:195], v[120:123]
	v_mfma_f32_16x16x32_bf16 v[120:123], v[188:191], v[196:199], v[120:123]
	v_mfma_f32_16x16x32_bf16 v[108:111], v[172:175], v[200:203], v[108:111]
	v_mfma_f32_16x16x32_bf16 v[108:111], v[176:179], v[204:207], v[108:111]
	v_mfma_f32_16x16x32_bf16 v[104:107], v[184:187], v[200:203], v[104:107]
	v_mfma_f32_16x16x32_bf16 v[104:107], v[188:191], v[204:207], v[104:107]
	v_mfma_f32_16x16x32_bf16 v[92:95], v[172:175], v[230:233], v[92:95]
	v_mfma_f32_16x16x32_bf16 v[92:95], v[176:179], v[234:237], v[92:95]
	v_mfma_f32_16x16x32_bf16 v[88:91], v[184:187], v[230:233], v[88:91]
	v_mfma_f32_16x16x32_bf16 v[88:91], v[188:191], v[234:237], v[88:91]
	v_mfma_f32_16x16x32_bf16 v[76:79], v[172:175], v[238:241], v[76:79]
	v_mfma_f32_16x16x32_bf16 v[76:79], v[176:179], v[242:245], v[76:79]
	v_mfma_f32_16x16x32_bf16 v[72:75], v[184:187], v[238:241], v[72:75]
	v_mfma_f32_16x16x32_bf16 v[72:75], v[188:191], v[242:245], v[72:75]
	s_setprio 0
	s_barrier
	s_add_i32 s82, s19, s42
	v_lshl_add_u64 v[180:181], s[80:81], 0, v[154:155]
	s_mov_b32 m0, s82
	ds_read_b128 v[192:195], v167 offset:16384
	ds_read_b128 v[196:199], v167 offset:17408
	ds_read_b128 v[200:203], v167 offset:18432
	ds_read_b128 v[204:207], v167 offset:19456
	ds_read_b128 v[230:233], v167 offset:20480
	ds_read_b128 v[234:237], v167 offset:21504
	ds_read_b128 v[238:241], v167 offset:22528
	ds_read_b128 v[242:245], v167 offset:23552
	global_load_lds_dwordx4 v[180:181], off
	s_add_i32 m0, s82, 0x2000
	v_lshl_add_u64 v[208:209], s[80:81], 0, v[2:3]
	s_add_u32 s80, s80, s48
	s_addc_u32 s81, s81, s49
	s_add_i32 s79, s79, s42
	global_load_lds_dwordx4 v[208:209], off
	v_lshl_add_u64 v[216:217], s[80:81], 0, v[154:155]
	s_mov_b32 m0, s79
	v_lshl_add_u64 v[224:225], s[80:81], 0, v[2:3]
	global_load_lds_dwordx4 v[216:217], off
	s_add_i32 m0, s79, 0x2000
	v_lshl_add_u64 v[226:227], s[38:39], 0, v[156:157]
	global_load_lds_dwordx4 v[224:225], off
	s_mov_b32 m0, s46
	v_lshl_add_u64 v[246:247], s[38:39], 0, v[152:153]
	global_load_lds_dwordx4 v[226:227], off
	s_mov_b32 m0, s47
	s_nop 0
	global_load_lds_dwordx4 v[246:247], off
	s_waitcnt vmcnt(8)
	s_waitcnt lgkmcnt(0)
	s_barrier
; #define PG8_STAGE(bufoff, gbase, voff) do { _Pragma("unroll") for (int _i = 0; _i < 2; ++_i) \
;         __builtin_amdgcn_global_load_lds((const unsigned*)((const char*)(gbase) + (voff)[_i]), (PG8_LAS unsigned*)(lds + (bufoff) + ldsw + _i * 8192), 16, 0, 0); } while (0)
; #define PG8_LDA(dst, b, h) do { _Pragma("unroll") for (int m = 0; m < 4; ++m) _Pragma("unroll") for (int k = 0; k < 2; ++k) dst[m][k] = *(const PG8_LAS bf16x8*)(lds + PG8_SA(b, h) + aoff + m * 2048 + k * 1024); } while (0)
; #define PG8_LDB(dst, b, h) do { _Pragma("unroll") for (int n = 0; n < 2; ++n) _Pragma("unroll") for (int k = 0; k < 2; ++k) dst[n][k] = *(const PG8_LAS bf16x8*)(lds + PG8_SB(b, h) + boff + n * 2048 + k * 1024); } while (0)
; #define PG8_MMA(ai, bj, At, Bt) do { __builtin_amdgcn_s_setprio(1); _Pragma("unroll") for (int m = 0; m < 4; ++m) _Pragma("unroll") for (int n = 0; n < 2; ++n) _Pragma("unroll") for (int k = 0; k < 2; ++k) \
;         acc[ai][bj][m][n] = __builtin_amdgcn_mfma_f32_16x16x32_bf16(Bt[n][k], At[m][k], acc[ai][bj][m][n], 0, 0, 0); __builtin_amdgcn_s_setprio(0); } while (0)
; #define PG8_WAIT_V(n) asm volatile("s_waitcnt vmcnt(" #n ")" ::: "memory")
; #define PG8_WAIT_L(n) asm volatile("s_waitcnt lgkmcnt(" #n ")" ::: "memory")
; #define PG8_BAR __builtin_amdgcn_s_barrier()
; #define PG8_SCHED __builtin_amdgcn_sched_barrier(0)
; template <class Epi, class Sched, bool ALIGN_EPI = false, bool SP2 = false>
; __device__ __forceinline__ void gemm_phase(PG8_LAS unsigned char* lds, const Gemm g, const Sched& S, const Epi& E) {
;     ...
;             PG8_WAIT_V(8); PG8_WAIT_L(0); PG8_BAR; PG8_MMA(1, 0, At, B0); PG8_MMA(1, 1, At, B1); PG8_BAR; PG8_SCHED;
;             PG8_LDB(B0, 1, 0); PG8_LDB(B1, 1, 1); PG8_SCHED; PG8_LDA(At, 1, 0); PG8_STAGE(PG8_SA(0, 1), a2 + hstep, voffA);
;             PG8_WAIT_V(8); PG8_WAIT_L(0); PG8_BAR; PG8_MMA(0, 0, At, B0); PG8_MMA(0, 1, At, B1); PG8_BAR; PG8_SCHED;
	s_setprio 1
	s_waitcnt lgkmcnt(0)
	v_mfma_f32_16x16x32_bf16 v[68:71], v[136:139], v[192:195], v[68:71]
	v_mfma_f32_16x16x32_bf16 v[68:71], v[140:143], v[196:199], v[68:71]
	v_mfma_f32_16x16x32_bf16 v[64:67], v[144:147], v[192:195], v[64:67]
	v_mfma_f32_16x16x32_bf16 v[64:67], v[148:151], v[196:199], v[64:67]
	v_mfma_f32_16x16x32_bf16 v[52:55], v[136:139], v[200:203], v[52:55]
	v_mfma_f32_16x16x32_bf16 v[52:55], v[140:143], v[204:207], v[52:55]
	v_mfma_f32_16x16x32_bf16 v[48:51], v[144:147], v[200:203], v[48:51]
	v_mfma_f32_16x16x32_bf16 v[48:51], v[148:151], v[204:207], v[48:51]
	v_mfma_f32_16x16x32_bf16 v[36:39], v[136:139], v[230:233], v[36:39]
	v_mfma_f32_16x16x32_bf16 v[36:39], v[140:143], v[234:237], v[36:39]
	v_mfma_f32_16x16x32_bf16 v[32:35], v[144:147], v[230:233], v[32:35]
	v_mfma_f32_16x16x32_bf16 v[32:35], v[148:151], v[234:237], v[32:35]
	v_mfma_f32_16x16x32_bf16 v[20:23], v[136:139], v[238:241], v[20:23]
	v_mfma_f32_16x16x32_bf16 v[20:23], v[140:143], v[242:245], v[20:23]
	v_mfma_f32_16x16x32_bf16 v[16:19], v[144:147], v[238:241], v[16:19]
	v_mfma_f32_16x16x32_bf16 v[16:19], v[148:151], v[242:245], v[16:19]
	s_setprio 0
	s_setprio 1
	v_mfma_f32_16x16x32_bf16 v[60:63], v[172:175], v[192:195], v[60:63]
	v_mfma_f32_16x16x32_bf16 v[60:63], v[176:179], v[196:199], v[60:63]
	v_mfma_f32_16x16x32_bf16 v[56:59], v[184:187], v[192:195], v[56:59]
	v_mfma_f32_16x16x32_bf16 v[56:59], v[188:191], v[196:199], v[56:59]
	v_mfma_f32_16x16x32_bf16 v[44:47], v[172:175], v[200:203], v[44:47]
	v_mfma_f32_16x16x32_bf16 v[44:47], v[176:179], v[204:207], v[44:47]
	v_mfma_f32_16x16x32_bf16 v[40:43], v[184:187], v[200:203], v[40:43]
	v_mfma_f32_16x16x32_bf16 v[40:43], v[188:191], v[204:207], v[40:43]
	v_mfma_f32_16x16x32_bf16 v[28:31], v[172:175], v[230:233], v[28:31]
	v_mfma_f32_16x16x32_bf16 v[28:31], v[176:179], v[234:237], v[28:31]
	v_mfma_f32_16x16x32_bf16 v[24:27], v[184:187], v[230:233], v[24:27]
	v_mfma_f32_16x16x32_bf16 v[24:27], v[188:191], v[234:237], v[24:27]
	v_mfma_f32_16x16x32_bf16 v[12:15], v[172:175], v[238:241], v[12:15]
	v_mfma_f32_16x16x32_bf16 v[12:15], v[176:179], v[242:245], v[12:15]
	v_mfma_f32_16x16x32_bf16 v[8:11], v[184:187], v[238:241], v[8:11]
	v_mfma_f32_16x16x32_bf16 v[8:11], v[188:191], v[242:245], v[8:11]
	s_setprio 0
	s_barrier
	s_add_i32 s79, 0, 0x1c000
	v_add_u32_e32 v148, s91, v162
	v_add_u32_e32 v171, s79, v162
	ds_read_b128 v[136:139], v148
	ds_read_b128 v[140:143], v148 offset:1024
	ds_read_b128 v[144:147], v148 offset:2048
	ds_read_b128 v[148:151], v148 offset:3072
	ds_read_b128 v[172:175], v171
	ds_read_b128 v[176:179], v171 offset:1024
	ds_read_b128 v[184:187], v171 offset:2048
	ds_read_b128 v[188:191], v171 offset:3072
	s_add_u32 s38, s38, s48
	s_addc_u32 s39, s39, s49
	s_mov_b32 m0, s52
	v_lshl_add_u64 v[248:249], s[38:39], 0, v[156:157]
	ds_read_b128 v[192:195], v167 offset:32768
	ds_read_b128 v[196:199], v167 offset:33792
	ds_read_b128 v[200:203], v167 offset:34816
	ds_read_b128 v[204:207], v167 offset:35840
	ds_read_b128 v[230:233], v167 offset:36864
	ds_read_b128 v[234:237], v167 offset:37888
	ds_read_b128 v[238:241], v167 offset:38912
	ds_read_b128 v[242:245], v167 offset:39936
	global_load_lds_dwordx4 v[248:249], off
	v_lshl_add_u64 v[248:249], s[38:39], 0, v[152:153]
	s_mov_b32 m0, s53
	s_nop 0
	global_load_lds_dwordx4 v[248:249], off
	s_waitcnt vmcnt(8)
	s_waitcnt lgkmcnt(0)
	s_barrier
	s_setprio 1
	s_waitcnt lgkmcnt(0)
	v_mfma_f32_16x16x32_bf16 v[132:135], v[136:139], v[192:195], v[132:135]
	v_mfma_f32_16x16x32_bf16 v[132:135], v[140:143], v[196:199], v[132:135]
	v_mfma_f32_16x16x32_bf16 v[128:131], v[144:147], v[192:195], v[128:131]
	v_mfma_f32_16x16x32_bf16 v[128:131], v[148:151], v[196:199], v[128:131]
	v_mfma_f32_16x16x32_bf16 v[116:119], v[136:139], v[200:203], v[116:119]
	v_mfma_f32_16x16x32_bf16 v[116:119], v[140:143], v[204:207], v[116:119]
	v_mfma_f32_16x16x32_bf16 v[112:115], v[144:147], v[200:203], v[112:115]
	v_mfma_f32_16x16x32_bf16 v[112:115], v[148:151], v[204:207], v[112:115]
	v_mfma_f32_16x16x32_bf16 v[100:103], v[136:139], v[230:233], v[100:103]
	v_mfma_f32_16x16x32_bf16 v[100:103], v[140:143], v[234:237], v[100:103]
	v_mfma_f32_16x16x32_bf16 v[96:99], v[144:147], v[230:233], v[96:99]
	v_mfma_f32_16x16x32_bf16 v[96:99], v[148:151], v[234:237], v[96:99]
	v_mfma_f32_16x16x32_bf16 v[84:87], v[136:139], v[238:241], v[84:87]
	v_mfma_f32_16x16x32_bf16 v[84:87], v[140:143], v[242:245], v[84:87]
	v_mfma_f32_16x16x32_bf16 v[80:83], v[144:147], v[238:241], v[80:83]
	v_mfma_f32_16x16x32_bf16 v[80:83], v[148:151], v[242:245], v[80:83]
	s_setprio 0
	s_setprio 1
	v_mfma_f32_16x16x32_bf16 v[124:127], v[172:175], v[192:195], v[124:127]
	v_mfma_f32_16x16x32_bf16 v[124:127], v[176:179], v[196:199], v[124:127]
	v_mfma_f32_16x16x32_bf16 v[120:123], v[184:187], v[192:195], v[120:123]
	v_mfma_f32_16x16x32_bf16 v[120:123], v[188:191], v[196:199], v[120:123]
	v_mfma_f32_16x16x32_bf16 v[108:111], v[172:175], v[200:203], v[108:111]
	v_mfma_f32_16x16x32_bf16 v[108:111], v[176:179], v[204:207], v[108:111]
	v_mfma_f32_16x16x32_bf16 v[104:107], v[184:187], v[200:203], v[104:107]
	v_mfma_f32_16x16x32_bf16 v[104:107], v[188:191], v[204:207], v[104:107]
	v_mfma_f32_16x16x32_bf16 v[92:95], v[172:175], v[230:233], v[92:95]
	v_mfma_f32_16x16x32_bf16 v[92:95], v[176:179], v[234:237], v[92:95]
	v_mfma_f32_16x16x32_bf16 v[88:91], v[184:187], v[230:233], v[88:91]
	v_mfma_f32_16x16x32_bf16 v[88:91], v[188:191], v[234:237], v[88:91]
	v_mfma_f32_16x16x32_bf16 v[76:79], v[172:175], v[238:241], v[76:79]
	v_mfma_f32_16x16x32_bf16 v[76:79], v[176:179], v[242:245], v[76:79]
	v_mfma_f32_16x16x32_bf16 v[72:75], v[184:187], v[238:241], v[72:75]
	v_mfma_f32_16x16x32_bf16 v[72:75], v[188:191], v[242:245], v[72:75]
	s_setprio 0
	s_barrier
; #define PG8_STAGE(bufoff, gbase, voff) do { _Pragma("unroll") for (int _i = 0; _i < 2; ++_i) \
;         __builtin_amdgcn_global_load_lds((const unsigned*)((const char*)(gbase) + (voff)[_i]), (PG8_LAS unsigned*)(lds + (bufoff) + ldsw + _i * 8192), 16, 0, 0); } while (0)
; #define PG8_LDA(dst, b, h) do { _Pragma("unroll") for (int m = 0; m < 4; ++m) _Pragma("unroll") for (int k = 0; k < 2; ++k) dst[m][k] = *(const PG8_LAS bf16x8*)(lds + PG8_SA(b, h) + aoff + m * 2048 + k * 1024); } while (0)
; #define PG8_MMA(ai, bj, At, Bt) do { __builtin_amdgcn_s_setprio(1); _Pragma("unroll") for (int m = 0; m < 4; ++m) _Pragma("unroll") for (int n = 0; n < 2; ++n) _Pragma("unroll") for (int k = 0; k < 2; ++k) \
;         acc[ai][bj][m][n] = __builtin_amdgcn_mfma_f32_16x16x32_bf16(Bt[n][k], At[m][k], acc[ai][bj][m][n], 0, 0, 0); __builtin_amdgcn_s_setprio(0); } while (0)
; #define PG8_WAIT_V(n) asm volatile("s_waitcnt vmcnt(" #n ")" ::: "memory")
; #define PG8_WAIT_L(n) asm volatile("s_waitcnt lgkmcnt(" #n ")" ::: "memory")
; #define PG8_BAR __builtin_amdgcn_s_barrier()
; #define PG8_SCHED __builtin_amdgcn_sched_barrier(0)
; template <class Epi, class Sched, bool ALIGN_EPI = false, bool SP2 = false>
; __device__ __forceinline__ void gemm_phase(PG8_LAS unsigned char* lds, const Gemm g, const Sched& S, const Epi& E) {
;     ...
;             PG8_LDA(At, 1, 1); PG8_STAGE(PG8_SB(1, 0), b3, voffB); PG8_STAGE(PG8_SB(1, 1), b3 + hstep, voffB); PG8_STAGE(PG8_SA(1, 0), a3, voffA);
;             PG8_WAIT_V(8); PG8_WAIT_L(0); PG8_BAR; PG8_MMA(1, 0, At, B0); PG8_MMA(1, 1, At, B1); PG8_BAR; PG8_SCHED;
	s_add_i32 s38, s91, s42
	v_lshl_add_u64 v[180:181], v[180:181], 0, s[24:25]
	s_mov_b32 m0, s38
	ds_read_b128 v[192:195], v167 offset:49152
	ds_read_b128 v[196:199], v167 offset:50176
	ds_read_b128 v[200:203], v167 offset:51200
	ds_read_b128 v[204:207], v167 offset:52224
	ds_read_b128 v[230:233], v167 offset:53248
	ds_read_b128 v[234:237], v167 offset:54272
	ds_read_b128 v[238:241], v167 offset:55296
	ds_read_b128 v[242:245], v167 offset:56320
	global_load_lds_dwordx4 v[180:181], off
	v_lshl_add_u64 v[180:181], v[208:209], 0, s[24:25]
	s_add_i32 m0, s38, 0x2000
	s_add_i32 s38, s79, s42
	global_load_lds_dwordx4 v[180:181], off
	v_lshl_add_u64 v[180:181], v[216:217], 0, s[24:25]
	s_mov_b32 m0, s38
	s_nop 0
	global_load_lds_dwordx4 v[180:181], off
	v_lshl_add_u64 v[180:181], v[224:225], 0, s[24:25]
	s_add_i32 m0, s38, 0x2000
	s_nop 0
	global_load_lds_dwordx4 v[180:181], off
	v_lshl_add_u64 v[180:181], v[226:227], 0, s[24:25]
	s_mov_b32 m0, s72
	s_nop 0
	global_load_lds_dwordx4 v[180:181], off
	v_lshl_add_u64 v[180:181], v[246:247], 0, s[24:25]
	s_mov_b32 m0, s73
	s_nop 0
	global_load_lds_dwordx4 v[180:181], off
	s_waitcnt vmcnt(8)
	s_waitcnt lgkmcnt(0)
	s_barrier
	s_setprio 1
	s_waitcnt lgkmcnt(0)
	v_mfma_f32_16x16x32_bf16 v[68:71], v[136:139], v[192:195], v[68:71]
	v_mfma_f32_16x16x32_bf16 v[68:71], v[140:143], v[196:199], v[68:71]
	v_mfma_f32_16x16x32_bf16 v[64:67], v[144:147], v[192:195], v[64:67]
	v_mfma_f32_16x16x32_bf16 v[64:67], v[148:151], v[196:199], v[64:67]
	v_mfma_f32_16x16x32_bf16 v[52:55], v[136:139], v[200:203], v[52:55]
	v_mfma_f32_16x16x32_bf16 v[52:55], v[140:143], v[204:207], v[52:55]
	v_mfma_f32_16x16x32_bf16 v[48:51], v[144:147], v[200:203], v[48:51]
	v_mfma_f32_16x16x32_bf16 v[48:51], v[148:151], v[204:207], v[48:51]
	v_mfma_f32_16x16x32_bf16 v[36:39], v[136:139], v[230:233], v[36:39]
	v_mfma_f32_16x16x32_bf16 v[36:39], v[140:143], v[234:237], v[36:39]
	v_mfma_f32_16x16x32_bf16 v[32:35], v[144:147], v[230:233], v[32:35]
	v_mfma_f32_16x16x32_bf16 v[32:35], v[148:151], v[234:237], v[32:35]
	v_mfma_f32_16x16x32_bf16 v[20:23], v[136:139], v[238:241], v[20:23]
	v_mfma_f32_16x16x32_bf16 v[20:23], v[140:143], v[242:245], v[20:23]
	v_mfma_f32_16x16x32_bf16 v[16:19], v[144:147], v[238:241], v[16:19]
	v_mfma_f32_16x16x32_bf16 v[16:19], v[148:151], v[242:245], v[16:19]
	s_setprio 0
	s_setprio 1
	v_mfma_f32_16x16x32_bf16 v[60:63], v[172:175], v[192:195], v[60:63]
	v_mfma_f32_16x16x32_bf16 v[60:63], v[176:179], v[196:199], v[60:63]
	v_mfma_f32_16x16x32_bf16 v[56:59], v[184:187], v[192:195], v[56:59]
	v_mfma_f32_16x16x32_bf16 v[56:59], v[188:191], v[196:199], v[56:59]
	v_mfma_f32_16x16x32_bf16 v[44:47], v[172:175], v[200:203], v[44:47]
	v_mfma_f32_16x16x32_bf16 v[44:47], v[176:179], v[204:207], v[44:47]
	v_mfma_f32_16x16x32_bf16 v[40:43], v[184:187], v[200:203], v[40:43]
	v_mfma_f32_16x16x32_bf16 v[40:43], v[188:191], v[204:207], v[40:43]
	v_mfma_f32_16x16x32_bf16 v[28:31], v[172:175], v[230:233], v[28:31]
	v_mfma_f32_16x16x32_bf16 v[28:31], v[176:179], v[234:237], v[28:31]
	v_mfma_f32_16x16x32_bf16 v[24:27], v[184:187], v[230:233], v[24:27]
	v_mfma_f32_16x16x32_bf16 v[24:27], v[188:191], v[234:237], v[24:27]
	v_mfma_f32_16x16x32_bf16 v[12:15], v[172:175], v[238:241], v[12:15]
	v_mfma_f32_16x16x32_bf16 v[12:15], v[176:179], v[242:245], v[12:15]
	v_mfma_f32_16x16x32_bf16 v[8:11], v[184:187], v[238:241], v[8:11]
	v_mfma_f32_16x16x32_bf16 v[8:11], v[188:191], v[242:245], v[8:11]
	s_setprio 0
	s_barrier
	s_add_u32 s0, s0, 0x100
	s_addc_u32 s1, s1, 0
	s_add_u32 s40, s40, 0x100
	s_addc_u32 s41, s41, 0
	s_cmp_ge_u32 s78, s9
	s_mov_b32 s38, s78
	s_cbranch_scc0 .LBB0_468

; #define PG8_STAGE(bufoff, gbase, voff) do { _Pragma("unroll") for (int _i = 0; _i < 2; ++_i) \
;         __builtin_amdgcn_global_load_lds((const unsigned*)((const char*)(gbase) + (voff)[_i]), (PG8_LAS unsigned*)(lds + (bufoff) + ldsw + _i * 8192), 16, 0, 0); } while (0)
; #define PG8_LDA(dst, b, h) do { _Pragma("unroll") for (int m = 0; m < 4; ++m) _Pragma("unroll") for (int k = 0; k < 2; ++k) dst[m][k] = *(const PG8_LAS bf16x8*)(lds + PG8_SA(b, h) + aoff + m * 2048 + k * 1024); } while (0)
; #define PG8_LDB(dst, b, h) do { _Pragma("unroll") for (int n = 0; n < 2; ++n) _Pragma("unroll") for (int k = 0; k < 2; ++k) dst[n][k] = *(const PG8_LAS bf16x8*)(lds + PG8_SB(b, h) + boff + n * 2048 + k * 1024); } while (0)
; #define PG8_MMA(ai, bj, At, Bt) do { __builtin_amdgcn_s_setprio(1); _Pragma("unroll") for (int m = 0; m < 4; ++m) _Pragma("unroll") for (int n = 0; n < 2; ++n) _Pragma("unroll") for (int k = 0; k < 2; ++k) \
;         acc[ai][bj][m][n] = __builtin_amdgcn_mfma_f32_16x16x32_bf16(Bt[n][k], At[m][k], acc[ai][bj][m][n], 0, 0, 0); __builtin_amdgcn_s_setprio(0); } while (0)
; #define PG8_WAIT_V(n) asm volatile("s_waitcnt vmcnt(" #n ")" ::: "memory")
; #define PG8_WAIT_L(n) asm volatile("s_waitcnt lgkmcnt(" #n ")" ::: "memory")
; template <class Epi, class Sched, bool ALIGN_EPI = false, bool SP2 = false>
; __device__ __forceinline__ void gemm_phase(PG8_LAS unsigned char* lds, const Gemm g, const Sched& S, const Epi& E) {
;     ...
;             const bool last = (t == nt - 2);
;             const char* a1 = cA + (size_t)(t + 1) * kstep;
;             const char* a2 = last ? nA : cA + (size_t)(t + 2) * kstep; const char* b2 = last ? nB : cB + (size_t)(t + 2) * kstep;
;             const char* a3 = a2 + kstep; const char* b3 = b2 + kstep;
;             if (last && has_next) S.a_ready(nxt);
;             if constexpr (SP2) {
;             PG8_LDB(B0, 0, 0); PG8_LDB(B1, 0, 1); PG8_SCHED; PG8_LDA(At, 0, 0); PG8_STAGE(PG8_SA(1, 1), a1 + hstep, voffA);
;             PG8_WAIT_V(8); PG8_WAIT_L(0); PG8_BAR; PG8_MMA(0, 0, At, B0); PG8_MMA(0, 1, At, B1); PG8_BAR; PG8_SCHED;
;             PG8_LDA(At, 0, 1); PG8_STAGE(PG8_SB(0, 0), b2, voffB); PG8_STAGE(PG8_SB(0, 1), b2 + hstep, voffB); PG8_STAGE(PG8_SA(0, 0), a2, voffA);
;             PG8_WAIT_V(8); PG8_WAIT_L(0); PG8_BAR; PG8_MMA(1, 0, At, B0); PG8_MMA(1, 1, At, B1); PG8_BAR; PG8_SCHED;
.LBB0_501:
	s_add_i32 s80, s4, 2
	s_add_u32 s81, s0, 0x80
	s_addc_u32 s5, s1, 0
	s_cmp_eq_u32 s33, s4
	s_cselect_b32 s5, s23, s5
	s_cselect_b32 s4, s22, s81
	s_cselect_b32 s83, s41, s43
	s_cselect_b32 s82, s40, s42
	s_add_i32 s81, 0, 0x14000
	v_add_u32_e32 v148, s19, v164
	v_add_u32_e32 v162, s81, v164
	ds_read_b128 v[136:139], v148
	ds_read_b128 v[140:143], v148 offset:1024
	ds_read_b128 v[144:147], v148 offset:2048
	ds_read_b128 v[148:151], v148 offset:3072
	ds_read_b128 v[174:177], v162
	ds_read_b128 v[178:181], v162 offset:1024
	ds_read_b128 v[184:187], v162 offset:2048
	ds_read_b128 v[188:191], v162 offset:3072
	v_lshl_add_u64 v[162:163], s[0:1], 0, v[158:159]
	s_add_i32 m0, s45, 0xc000
	ds_read_b128 v[192:195], v170
	ds_read_b128 v[196:199], v170 offset:1024
	ds_read_b128 v[200:203], v170 offset:2048
	ds_read_b128 v[204:207], v170 offset:3072
	ds_read_b128 v[230:233], v170 offset:4096
	ds_read_b128 v[234:237], v170 offset:5120
	ds_read_b128 v[238:241], v170 offset:6144
	ds_read_b128 v[242:245], v170 offset:7168
	global_load_lds_dwordx4 v[162:163], off
	v_lshl_add_u64 v[162:163], s[0:1], 0, v[160:161]
	s_add_i32 m0, s45, 0xe000
	s_nop 0
	global_load_lds_dwordx4 v[162:163], off
	s_waitcnt vmcnt(8)
	s_waitcnt lgkmcnt(0)
	s_barrier
	s_setprio 1
	s_waitcnt lgkmcnt(0)
	v_mfma_f32_16x16x32_bf16 v[132:135], v[136:139], v[192:195], v[132:135]
	v_mfma_f32_16x16x32_bf16 v[132:135], v[140:143], v[196:199], v[132:135]
	v_mfma_f32_16x16x32_bf16 v[128:131], v[144:147], v[192:195], v[128:131]
	v_mfma_f32_16x16x32_bf16 v[128:131], v[148:151], v[196:199], v[128:131]
	v_mfma_f32_16x16x32_bf16 v[116:119], v[136:139], v[200:203], v[116:119]
	v_mfma_f32_16x16x32_bf16 v[116:119], v[140:143], v[204:207], v[116:119]
	v_mfma_f32_16x16x32_bf16 v[112:115], v[144:147], v[200:203], v[112:115]
	v_mfma_f32_16x16x32_bf16 v[112:115], v[148:151], v[204:207], v[112:115]
	v_mfma_f32_16x16x32_bf16 v[100:103], v[136:139], v[230:233], v[100:103]
	v_mfma_f32_16x16x32_bf16 v[100:103], v[140:143], v[234:237], v[100:103]
	v_mfma_f32_16x16x32_bf16 v[96:99], v[144:147], v[230:233], v[96:99]
	v_mfma_f32_16x16x32_bf16 v[96:99], v[148:151], v[234:237], v[96:99]
	v_mfma_f32_16x16x32_bf16 v[84:87], v[136:139], v[238:241], v[84:87]
	v_mfma_f32_16x16x32_bf16 v[84:87], v[140:143], v[242:245], v[84:87]
	v_mfma_f32_16x16x32_bf16 v[80:83], v[144:147], v[238:241], v[80:83]
	v_mfma_f32_16x16x32_bf16 v[80:83], v[148:151], v[242:245], v[80:83]
	s_setprio 0
	s_setprio 1
	v_mfma_f32_16x16x32_bf16 v[124:127], v[174:177], v[192:195], v[124:127]
	v_mfma_f32_16x16x32_bf16 v[124:127], v[178:181], v[196:199], v[124:127]
	v_mfma_f32_16x16x32_bf16 v[120:123], v[184:187], v[192:195], v[120:123]
	v_mfma_f32_16x16x32_bf16 v[120:123], v[188:191], v[196:199], v[120:123]
	v_mfma_f32_16x16x32_bf16 v[108:111], v[174:177], v[200:203], v[108:111]
	v_mfma_f32_16x16x32_bf16 v[108:111], v[178:181], v[204:207], v[108:111]
	v_mfma_f32_16x16x32_bf16 v[104:107], v[184:187], v[200:203], v[104:107]
	v_mfma_f32_16x16x32_bf16 v[104:107], v[188:191], v[204:207], v[104:107]
	v_mfma_f32_16x16x32_bf16 v[92:95], v[174:177], v[230:233], v[92:95]
	v_mfma_f32_16x16x32_bf16 v[92:95], v[178:181], v[234:237], v[92:95]
	v_mfma_f32_16x16x32_bf16 v[88:91], v[184:187], v[230:233], v[88:91]
	v_mfma_f32_16x16x32_bf16 v[88:91], v[188:191], v[234:237], v[88:91]
	v_mfma_f32_16x16x32_bf16 v[76:79], v[174:177], v[238:241], v[76:79]
	v_mfma_f32_16x16x32_bf16 v[76:79], v[178:181], v[242:245], v[76:79]
	v_mfma_f32_16x16x32_bf16 v[72:75], v[184:187], v[238:241], v[72:75]
	v_mfma_f32_16x16x32_bf16 v[72:75], v[188:191], v[242:245], v[72:75]
	s_setprio 0
	s_barrier
	s_add_i32 s84, s19, s44
	v_lshl_add_u64 v[162:163], s[82:83], 0, v[152:153]
	s_mov_b32 m0, s84
	ds_read_b128 v[192:195], v170 offset:16384
	ds_read_b128 v[196:199], v170 offset:17408
	ds_read_b128 v[200:203], v170 offset:18432
	ds_read_b128 v[204:207], v170 offset:19456
	ds_read_b128 v[230:233], v170 offset:20480
	ds_read_b128 v[234:237], v170 offset:21504
	ds_read_b128 v[238:241], v170 offset:22528
	ds_read_b128 v[242:245], v170 offset:23552
	global_load_lds_dwordx4 v[162:163], off
	s_add_i32 m0, s84, 0x2000
	v_lshl_add_u64 v[208:209], s[82:83], 0, v[156:157]
	s_add_u32 s82, s82, s48
	s_addc_u32 s83, s83, s49
	s_add_i32 s81, s81, s44
	global_load_lds_dwordx4 v[208:209], off
	v_lshl_add_u64 v[246:247], s[82:83], 0, v[152:153]
	s_mov_b32 m0, s81
	v_lshl_add_u64 v[248:249], s[82:83], 0, v[156:157]
	global_load_lds_dwordx4 v[246:247], off
	s_add_i32 m0, s81, 0x2000
	v_lshl_add_u64 v[216:217], s[4:5], 0, v[2:3]
	global_load_lds_dwordx4 v[248:249], off
	s_mov_b32 m0, s45
	v_lshl_add_u64 v[224:225], s[4:5], 0, v[154:155]
	global_load_lds_dwordx4 v[216:217], off
	s_mov_b32 m0, s46
	s_nop 0
	global_load_lds_dwordx4 v[224:225], off
	s_waitcnt vmcnt(8)
	s_waitcnt lgkmcnt(0)
	s_barrier
; #define PG8_STAGE(bufoff, gbase, voff) do { _Pragma("unroll") for (int _i = 0; _i < 2; ++_i) \
;         __builtin_amdgcn_global_load_lds((const unsigned*)((const char*)(gbase) + (voff)[_i]), (PG8_LAS unsigned*)(lds + (bufoff) + ldsw + _i * 8192), 16, 0, 0); } while (0)
; #define PG8_LDA(dst, b, h) do { _Pragma("unroll") for (int m = 0; m < 4; ++m) _Pragma("unroll") for (int k = 0; k < 2; ++k) dst[m][k] = *(const PG8_LAS bf16x8*)(lds + PG8_SA(b, h) + aoff + m * 2048 + k * 1024); } while (0)
; #define PG8_LDB(dst, b, h) do { _Pragma("unroll") for (int n = 0; n < 2; ++n) _Pragma("unroll") for (int k = 0; k < 2; ++k) dst[n][k] = *(const PG8_LAS bf16x8*)(lds + PG8_SB(b, h) + boff + n * 2048 + k * 1024); } while (0)
; #define PG8_MMA(ai, bj, At, Bt) do { __builtin_amdgcn_s_setprio(1); _Pragma("unroll") for (int m = 0; m < 4; ++m) _Pragma("unroll") for (int n = 0; n < 2; ++n) _Pragma("unroll") for (int k = 0; k < 2; ++k) \
;         acc[ai][bj][m][n] = __builtin_amdgcn_mfma_f32_16x16x32_bf16(Bt[n][k], At[m][k], acc[ai][bj][m][n], 0, 0, 0); __builtin_amdgcn_s_setprio(0); } while (0)
; #define PG8_WAIT_V(n) asm volatile("s_waitcnt vmcnt(" #n ")" ::: "memory")
; #define PG8_WAIT_L(n) asm volatile("s_waitcnt lgkmcnt(" #n ")" ::: "memory")
; #define PG8_BAR __builtin_amdgcn_s_barrier()
; #define PG8_SCHED __builtin_amdgcn_sched_barrier(0)
; template <class Epi, class Sched, bool ALIGN_EPI = false, bool SP2 = false>
; __device__ __forceinline__ void gemm_phase(PG8_LAS unsigned char* lds, const Gemm g, const Sched& S, const Epi& E) {
;     ...
;             PG8_WAIT_V(8); PG8_WAIT_L(0); PG8_BAR; PG8_MMA(1, 0, At, B0); PG8_MMA(1, 1, At, B1); PG8_BAR; PG8_SCHED;
;             PG8_LDB(B0, 1, 0); PG8_LDB(B1, 1, 1); PG8_SCHED; PG8_LDA(At, 1, 0); PG8_STAGE(PG8_SA(0, 1), a2 + hstep, voffA);
;             PG8_WAIT_V(8); PG8_WAIT_L(0); PG8_BAR; PG8_MMA(0, 0, At, B0); PG8_MMA(0, 1, At, B1); PG8_BAR; PG8_SCHED;
	s_setprio 1
	s_waitcnt lgkmcnt(0)
	v_mfma_f32_16x16x32_bf16 v[68:71], v[136:139], v[192:195], v[68:71]
	v_mfma_f32_16x16x32_bf16 v[68:71], v[140:143], v[196:199], v[68:71]
	v_mfma_f32_16x16x32_bf16 v[64:67], v[144:147], v[192:195], v[64:67]
	v_mfma_f32_16x16x32_bf16 v[64:67], v[148:151], v[196:199], v[64:67]
	v_mfma_f32_16x16x32_bf16 v[52:55], v[136:139], v[200:203], v[52:55]
	v_mfma_f32_16x16x32_bf16 v[52:55], v[140:143], v[204:207], v[52:55]
	v_mfma_f32_16x16x32_bf16 v[48:51], v[144:147], v[200:203], v[48:51]
	v_mfma_f32_16x16x32_bf16 v[48:51], v[148:151], v[204:207], v[48:51]
	v_mfma_f32_16x16x32_bf16 v[36:39], v[136:139], v[230:233], v[36:39]
	v_mfma_f32_16x16x32_bf16 v[36:39], v[140:143], v[234:237], v[36:39]
	v_mfma_f32_16x16x32_bf16 v[32:35], v[144:147], v[230:233], v[32:35]
	v_mfma_f32_16x16x32_bf16 v[32:35], v[148:151], v[234:237], v[32:35]
	v_mfma_f32_16x16x32_bf16 v[20:23], v[136:139], v[238:241], v[20:23]
	v_mfma_f32_16x16x32_bf16 v[20:23], v[140:143], v[242:245], v[20:23]
	v_mfma_f32_16x16x32_bf16 v[16:19], v[144:147], v[238:241], v[16:19]
	v_mfma_f32_16x16x32_bf16 v[16:19], v[148:151], v[242:245], v[16:19]
	s_setprio 0
	s_setprio 1
	v_mfma_f32_16x16x32_bf16 v[60:63], v[174:177], v[192:195], v[60:63]
	v_mfma_f32_16x16x32_bf16 v[60:63], v[178:181], v[196:199], v[60:63]
	v_mfma_f32_16x16x32_bf16 v[56:59], v[184:187], v[192:195], v[56:59]
	v_mfma_f32_16x16x32_bf16 v[56:59], v[188:191], v[196:199], v[56:59]
	v_mfma_f32_16x16x32_bf16 v[44:47], v[174:177], v[200:203], v[44:47]
	v_mfma_f32_16x16x32_bf16 v[44:47], v[178:181], v[204:207], v[44:47]
	v_mfma_f32_16x16x32_bf16 v[40:43], v[184:187], v[200:203], v[40:43]
	v_mfma_f32_16x16x32_bf16 v[40:43], v[188:191], v[204:207], v[40:43]
	v_mfma_f32_16x16x32_bf16 v[28:31], v[174:177], v[230:233], v[28:31]
	v_mfma_f32_16x16x32_bf16 v[28:31], v[178:181], v[234:237], v[28:31]
	v_mfma_f32_16x16x32_bf16 v[24:27], v[184:187], v[230:233], v[24:27]
	v_mfma_f32_16x16x32_bf16 v[24:27], v[188:191], v[234:237], v[24:27]
	v_mfma_f32_16x16x32_bf16 v[12:15], v[174:177], v[238:241], v[12:15]
	v_mfma_f32_16x16x32_bf16 v[12:15], v[178:181], v[242:245], v[12:15]
	v_mfma_f32_16x16x32_bf16 v[8:11], v[184:187], v[238:241], v[8:11]
	v_mfma_f32_16x16x32_bf16 v[8:11], v[188:191], v[242:245], v[8:11]
	s_setprio 0
	s_barrier
	s_add_i32 s81, 0, 0x1c000
	v_add_u32_e32 v148, s91, v164
	v_add_u32_e32 v173, s81, v164
	ds_read_b128 v[136:139], v148
	ds_read_b128 v[140:143], v148 offset:1024
	ds_read_b128 v[144:147], v148 offset:2048
	ds_read_b128 v[148:151], v148 offset:3072
	ds_read_b128 v[174:177], v173
	ds_read_b128 v[178:181], v173 offset:1024
	ds_read_b128 v[184:187], v173 offset:2048
	ds_read_b128 v[188:191], v173 offset:3072
	s_add_u32 s4, s4, s48
	s_addc_u32 s5, s5, s49
	s_mov_b32 m0, s47
	v_lshl_add_u64 v[226:227], s[4:5], 0, v[2:3]
	ds_read_b128 v[192:195], v170 offset:32768
	ds_read_b128 v[196:199], v170 offset:33792
	ds_read_b128 v[200:203], v170 offset:34816
	ds_read_b128 v[204:207], v170 offset:35840
	ds_read_b128 v[230:233], v170 offset:36864
	ds_read_b128 v[234:237], v170 offset:37888
	ds_read_b128 v[238:241], v170 offset:38912
	ds_read_b128 v[242:245], v170 offset:39936
	global_load_lds_dwordx4 v[226:227], off
	v_lshl_add_u64 v[226:227], s[4:5], 0, v[154:155]
	s_mov_b32 m0, s52
	s_nop 0
	global_load_lds_dwordx4 v[226:227], off
	s_waitcnt vmcnt(8)
	s_waitcnt lgkmcnt(0)
	s_barrier
	s_setprio 1
	s_waitcnt lgkmcnt(0)
	v_mfma_f32_16x16x32_bf16 v[132:135], v[136:139], v[192:195], v[132:135]
	v_mfma_f32_16x16x32_bf16 v[132:135], v[140:143], v[196:199], v[132:135]
	v_mfma_f32_16x16x32_bf16 v[128:131], v[144:147], v[192:195], v[128:131]
	v_mfma_f32_16x16x32_bf16 v[128:131], v[148:151], v[196:199], v[128:131]
	v_mfma_f32_16x16x32_bf16 v[116:119], v[136:139], v[200:203], v[116:119]
	v_mfma_f32_16x16x32_bf16 v[116:119], v[140:143], v[204:207], v[116:119]
	v_mfma_f32_16x16x32_bf16 v[112:115], v[144:147], v[200:203], v[112:115]
	v_mfma_f32_16x16x32_bf16 v[112:115], v[148:151], v[204:207], v[112:115]
	v_mfma_f32_16x16x32_bf16 v[100:103], v[136:139], v[230:233], v[100:103]
	v_mfma_f32_16x16x32_bf16 v[100:103], v[140:143], v[234:237], v[100:103]
	v_mfma_f32_16x16x32_bf16 v[96:99], v[144:147], v[230:233], v[96:99]
	v_mfma_f32_16x16x32_bf16 v[96:99], v[148:151], v[234:237], v[96:99]
	v_mfma_f32_16x16x32_bf16 v[84:87], v[136:139], v[238:241], v[84:87]
	v_mfma_f32_16x16x32_bf16 v[84:87], v[140:143], v[242:245], v[84:87]
	v_mfma_f32_16x16x32_bf16 v[80:83], v[144:147], v[238:241], v[80:83]
	v_mfma_f32_16x16x32_bf16 v[80:83], v[148:151], v[242:245], v[80:83]
	s_setprio 0
	s_setprio 1
	v_mfma_f32_16x16x32_bf16 v[124:127], v[174:177], v[192:195], v[124:127]
	v_mfma_f32_16x16x32_bf16 v[124:127], v[178:181], v[196:199], v[124:127]
	v_mfma_f32_16x16x32_bf16 v[120:123], v[184:187], v[192:195], v[120:123]
	v_mfma_f32_16x16x32_bf16 v[120:123], v[188:191], v[196:199], v[120:123]
	v_mfma_f32_16x16x32_bf16 v[108:111], v[174:177], v[200:203], v[108:111]
	v_mfma_f32_16x16x32_bf16 v[108:111], v[178:181], v[204:207], v[108:111]
	v_mfma_f32_16x16x32_bf16 v[104:107], v[184:187], v[200:203], v[104:107]
	v_mfma_f32_16x16x32_bf16 v[104:107], v[188:191], v[204:207], v[104:107]
	v_mfma_f32_16x16x32_bf16 v[92:95], v[174:177], v[230:233], v[92:95]
	v_mfma_f32_16x16x32_bf16 v[92:95], v[178:181], v[234:237], v[92:95]
	v_mfma_f32_16x16x32_bf16 v[88:91], v[184:187], v[230:233], v[88:91]
	v_mfma_f32_16x16x32_bf16 v[88:91], v[188:191], v[234:237], v[88:91]
	v_mfma_f32_16x16x32_bf16 v[76:79], v[174:177], v[238:241], v[76:79]
	v_mfma_f32_16x16x32_bf16 v[76:79], v[178:181], v[242:245], v[76:79]
	v_mfma_f32_16x16x32_bf16 v[72:75], v[184:187], v[238:241], v[72:75]
	v_mfma_f32_16x16x32_bf16 v[72:75], v[188:191], v[242:245], v[72:75]
	s_setprio 0
	s_barrier
; #define PG8_STAGE(bufoff, gbase, voff) do { _Pragma("unroll") for (int _i = 0; _i < 2; ++_i) \
;         __builtin_amdgcn_global_load_lds((const unsigned*)((const char*)(gbase) + (voff)[_i]), (PG8_LAS unsigned*)(lds + (bufoff) + ldsw + _i * 8192), 16, 0, 0); } while (0)
; #define PG8_LDA(dst, b, h) do { _Pragma("unroll") for (int m = 0; m < 4; ++m) _Pragma("unroll") for (int k = 0; k < 2; ++k) dst[m][k] = *(const PG8_LAS bf16x8*)(lds + PG8_SA(b, h) + aoff + m * 2048 + k * 1024); } while (0)
; #define PG8_MMA(ai, bj, At, Bt) do { __builtin_amdgcn_s_setprio(1); _Pragma("unroll") for (int m = 0; m < 4; ++m) _Pragma("unroll") for (int n = 0; n < 2; ++n) _Pragma("unroll") for (int k = 0; k < 2; ++k) \
;         acc[ai][bj][m][n] = __builtin_amdgcn_mfma_f32_16x16x32_bf16(Bt[n][k], At[m][k], acc[ai][bj][m][n], 0, 0, 0); __builtin_amdgcn_s_setprio(0); } while (0)
; #define PG8_WAIT_V(n) asm volatile("s_waitcnt vmcnt(" #n ")" ::: "memory")
; #define PG8_WAIT_L(n) asm volatile("s_waitcnt lgkmcnt(" #n ")" ::: "memory")
; #define PG8_BAR __builtin_amdgcn_s_barrier()
; #define PG8_SCHED __builtin_amdgcn_sched_barrier(0)
; template <class Epi, class Sched, bool ALIGN_EPI = false, bool SP2 = false>
; __device__ __forceinline__ void gemm_phase(PG8_LAS unsigned char* lds, const Gemm g, const Sched& S, const Epi& E) {
;     ...
;             PG8_LDA(At, 1, 1); PG8_STAGE(PG8_SB(1, 0), b3, voffB); PG8_STAGE(PG8_SB(1, 1), b3 + hstep, voffB); PG8_STAGE(PG8_SA(1, 0), a3, voffA);
;             PG8_WAIT_V(8); PG8_WAIT_L(0); PG8_BAR; PG8_MMA(1, 0, At, B0); PG8_MMA(1, 1, At, B1); PG8_BAR; PG8_SCHED;
	s_add_i32 s4, s91, s44
	v_lshl_add_u64 v[162:163], v[162:163], 0, s[24:25]
	s_mov_b32 m0, s4
	ds_read_b128 v[192:195], v170 offset:49152
	ds_read_b128 v[196:199], v170 offset:50176
	ds_read_b128 v[200:203], v170 offset:51200
	ds_read_b128 v[204:207], v170 offset:52224
	ds_read_b128 v[230:233], v170 offset:53248
	ds_read_b128 v[234:237], v170 offset:54272
	ds_read_b128 v[238:241], v170 offset:55296
	ds_read_b128 v[242:245], v170 offset:56320
	global_load_lds_dwordx4 v[162:163], off
	v_lshl_add_u64 v[162:163], v[208:209], 0, s[24:25]
	s_add_i32 m0, s4, 0x2000
	s_add_i32 s4, s81, s44
	global_load_lds_dwordx4 v[162:163], off
	v_lshl_add_u64 v[162:163], v[246:247], 0, s[24:25]
	s_mov_b32 m0, s4
	s_nop 0
	global_load_lds_dwordx4 v[162:163], off
	v_lshl_add_u64 v[162:163], v[248:249], 0, s[24:25]
	s_add_i32 m0, s4, 0x2000
	s_nop 0
	global_load_lds_dwordx4 v[162:163], off
	v_lshl_add_u64 v[162:163], v[216:217], 0, s[24:25]
	s_mov_b32 m0, s53
	s_nop 0
	global_load_lds_dwordx4 v[162:163], off
	v_lshl_add_u64 v[162:163], v[224:225], 0, s[24:25]
	s_mov_b32 m0, s72
	s_nop 0
	global_load_lds_dwordx4 v[162:163], off
	s_waitcnt vmcnt(8)
	s_waitcnt lgkmcnt(0)
	s_barrier
	s_setprio 1
	s_waitcnt lgkmcnt(0)
	v_mfma_f32_16x16x32_bf16 v[68:71], v[136:139], v[192:195], v[68:71]
	v_mfma_f32_16x16x32_bf16 v[68:71], v[140:143], v[196:199], v[68:71]
	v_mfma_f32_16x16x32_bf16 v[64:67], v[144:147], v[192:195], v[64:67]
	v_mfma_f32_16x16x32_bf16 v[64:67], v[148:151], v[196:199], v[64:67]
	v_mfma_f32_16x16x32_bf16 v[52:55], v[136:139], v[200:203], v[52:55]
	v_mfma_f32_16x16x32_bf16 v[52:55], v[140:143], v[204:207], v[52:55]
	v_mfma_f32_16x16x32_bf16 v[48:51], v[144:147], v[200:203], v[48:51]
	v_mfma_f32_16x16x32_bf16 v[48:51], v[148:151], v[204:207], v[48:51]
	v_mfma_f32_16x16x32_bf16 v[36:39], v[136:139], v[230:233], v[36:39]
	v_mfma_f32_16x16x32_bf16 v[36:39], v[140:143], v[234:237], v[36:39]
	v_mfma_f32_16x16x32_bf16 v[32:35], v[144:147], v[230:233], v[32:35]
	v_mfma_f32_16x16x32_bf16 v[32:35], v[148:151], v[234:237], v[32:35]
	v_mfma_f32_16x16x32_bf16 v[20:23], v[136:139], v[238:241], v[20:23]
	v_mfma_f32_16x16x32_bf16 v[20:23], v[140:143], v[242:245], v[20:23]
	v_mfma_f32_16x16x32_bf16 v[16:19], v[144:147], v[238:241], v[16:19]
	v_mfma_f32_16x16x32_bf16 v[16:19], v[148:151], v[242:245], v[16:19]
	s_setprio 0
	s_setprio 1
	v_mfma_f32_16x16x32_bf16 v[60:63], v[174:177], v[192:195], v[60:63]
	v_mfma_f32_16x16x32_bf16 v[60:63], v[178:181], v[196:199], v[60:63]
	v_mfma_f32_16x16x32_bf16 v[56:59], v[184:187], v[192:195], v[56:59]
	v_mfma_f32_16x16x32_bf16 v[56:59], v[188:191], v[196:199], v[56:59]
	v_mfma_f32_16x16x32_bf16 v[44:47], v[174:177], v[200:203], v[44:47]
	v_mfma_f32_16x16x32_bf16 v[44:47], v[178:181], v[204:207], v[44:47]
	v_mfma_f32_16x16x32_bf16 v[40:43], v[184:187], v[200:203], v[40:43]
	v_mfma_f32_16x16x32_bf16 v[40:43], v[188:191], v[204:207], v[40:43]
	v_mfma_f32_16x16x32_bf16 v[28:31], v[174:177], v[230:233], v[28:31]
	v_mfma_f32_16x16x32_bf16 v[28:31], v[178:181], v[234:237], v[28:31]
	v_mfma_f32_16x16x32_bf16 v[24:27], v[184:187], v[230:233], v[24:27]
	v_mfma_f32_16x16x32_bf16 v[24:27], v[188:191], v[234:237], v[24:27]
	v_mfma_f32_16x16x32_bf16 v[12:15], v[174:177], v[238:241], v[12:15]
	v_mfma_f32_16x16x32_bf16 v[12:15], v[178:181], v[242:245], v[12:15]
	v_mfma_f32_16x16x32_bf16 v[8:11], v[184:187], v[238:241], v[8:11]
	v_mfma_f32_16x16x32_bf16 v[8:11], v[188:191], v[242:245], v[8:11]
	s_setprio 0
	s_barrier
	s_add_u32 s0, s0, 0x100
	s_addc_u32 s1, s1, 0
	s_add_u32 s42, s42, 0x100
	s_addc_u32 s43, s43, 0
	s_cmp_ge_u32 s80, s9
	s_mov_b32 s4, s80
	s_cbranch_scc0 .LBB0_501
